# static priority: per-phase s_setprio toggles removed from all GEMM K-loops, the trailing wave half raised to priority 1 once per GEMM phase and reset at the unit-loop exit
# speedup vs baseline: 1.0215x; 1.0215x over previous
.LBB0_241:
	s_and_b64 s[6:7], s[88:89], exec
	s_cselect_b32 s84, s44, 2.0
	s_cmp_ge_i32 s33, s84
	s_cselect_b64 s[6:7], -1, 0
	s_xor_b64 s[4:5], s[4:5], -1
	v_and_b32_e32 v193, 15, v194
	v_ashrrev_i32_e32 v1, 1, v194
	s_or_b64 s[4:5], s[6:7], s[4:5]
	v_or_b32_e32 v192, s92, v193
	v_and_b32_e32 v152, -8, v1
	s_and_b64 vcc, exec, s[4:5]
	s_cbranch_vccnz .LBB0_377
	v_lshlrev_b32_e32 v1, 4, v194
	v_add_u32_e32 v2, s97, v1
	v_ashrrev_i32_e32 v3, 31, v2
	v_lshrrev_b32_e32 v3, 22, v3
	v_add_u32_e32 v3, v2, v3
	v_ashrrev_i32_e32 v10, 10, v3
	v_mul_i32_i24_e32 v3, 0x400, v10
	v_sub_u32_e32 v3, v2, v3
	v_lshrrev_b32_e32 v4, 4, v3
	v_bitop3_b32 v3, v4, v3, 32 bitop3:0x6c
	v_ashrrev_i32_e32 v5, 31, v3
	v_lshrrev_b32_e32 v5, 26, v5
	v_add_u32_e32 v5, v3, v5
	v_lshlrev_b32_e32 v4, 3, v10
	v_ashrrev_i32_e32 v11, 6, v5
	v_and_b32_e32 v5, 0xc0, v5
	v_and_b32_e32 v4, -16, v4
	v_sub_u32_e32 v3, v3, v5
	v_add_u32_e32 v4, v11, v4
	v_ashrrev_i16_sdwa v3, v188, sext(v3) dst_sel:DWORD dst_unused:UNUSED_PAD src0_sel:DWORD src1_sel:BYTE_0
	v_lshlrev_b32_e32 v6, 5, v10
	v_bfe_i32 v12, v3, 0, 16
	v_lshlrev_b32_e32 v3, 1, v4
	v_lshrrev_b32_e32 v5, 2, v4
	v_and_b32_e32 v7, 3, v11
	s_mov_b32 s4, 0x7ffe0
	v_and_b32_e32 v6, 32, v6
	v_and_b32_e32 v3, 24, v3
	v_and_b32_e32 v5, 4, v5
	v_and_or_b32 v7, v4, s4, v7
	v_or3_b32 v3, v7, v5, v3
	v_add_lshl_u32 v5, v6, v12, 1
	v_add_u32_e32 v2, 0x2000, v2
	v_lshl_add_u32 v156, v3, 13, v5
	v_ashrrev_i32_e32 v3, 31, v2
	v_lshrrev_b32_e32 v3, 22, v3
	v_add_u32_e32 v3, v2, v3
	v_ashrrev_i32_e32 v13, 10, v3
	v_mul_i32_i24_e32 v3, 0x400, v13
	v_sub_u32_e32 v2, v2, v3
	v_lshrrev_b32_e32 v3, 4, v2
	v_bitop3_b32 v2, v3, v2, 32 bitop3:0x6c
	v_lshl_add_u32 v154, v4, 13, v5
	v_ashrrev_i32_e32 v4, 31, v2
	v_lshrrev_b32_e32 v4, 26, v4
	v_lshlrev_b32_e32 v3, 3, v13
	v_add_u32_e32 v4, v2, v4
	v_and_b32_e32 v3, -16, v3
	v_ashrrev_i32_e32 v14, 6, v4
	v_add_u32_e32 v3, v14, v3
	v_and_b32_e32 v6, 3, v14
	s_ashr_i32 s13, s12, 31
	v_and_or_b32 v6, v3, s4, v6
	s_lshl_b64 s[4:5], s[12:13], 21
	s_add_u32 s6, s36, s4
	s_addc_u32 s7, s37, s5
	s_ashr_i32 s15, s14, 31
	s_lshr_b32 s4, s15, 2
	s_add_i32 s4, s14, s4
	s_ashr_i32 s4, s4, 30
	s_ashr_i32 s5, s4, 31
	v_and_b32_e32 v4, 0xffc0, v4
	s_lshl_b64 s[4:5], s[4:5], 13
	v_sub_u32_e32 v2, v2, v4
	s_add_u32 s6, s6, s4
	v_lshrrev_b16_e32 v4, 7, v2
	s_addc_u32 s7, s7, s5
	s_lshl_b64 s[4:5], s[14:15], 21
	v_and_b32_e32 v4, 1, v4
	s_add_u32 s4, s30, s4
	v_add_u16_e32 v2, v2, v4
	s_addc_u32 s5, s31, s5
	v_ashrrev_i16_sdwa v2, v188, sext(v2) dst_sel:DWORD dst_unused:UNUSED_PAD src0_sel:DWORD src1_sel:BYTE_0
	s_add_u32 s10, s4, s2
	v_lshlrev_b32_e32 v5, 5, v13
	v_bfe_i32 v15, v2, 0, 16
	v_lshlrev_b32_e32 v2, 1, v3
	v_lshrrev_b32_e32 v4, 2, v3
	s_addc_u32 s11, s5, s3
	s_add_i32 s85, s97, 0
	v_and_b32_e32 v5, 32, v5
	v_and_b32_e32 v2, 24, v2
	v_and_b32_e32 v4, 4, v4
	s_add_i32 m0, s85, 0x10000
	v_or3_b32 v2, v6, v4, v2
	v_add_lshl_u32 v4, v5, v15, 1
	global_load_lds_dwordx4 v156, s[10:11]
	s_add_i32 m0, s85, 0x12000
	v_lshl_add_u32 v160, v2, 13, v4
	s_add_u32 s4, s10, 0x100000
	global_load_lds_dwordx4 v160, s[10:11]
	s_addc_u32 s5, s11, 0
	s_add_i32 m0, s85, 0x14000
	s_mov_b32 s45, s44
	global_load_lds_dwordx4 v156, s[4:5]
	s_add_i32 m0, s85, 0x16000
	s_add_u32 s38, s6, s2
	s_mov_b32 s44, s92
	s_addc_u32 s39, s7, s3
	s_add_i32 s92, s85, 0x2000
	global_load_lds_dwordx4 v160, s[4:5]
	s_mov_b32 m0, s85
	s_add_u32 s2, s38, 0x100000
	v_lshl_add_u32 v158, v3, 13, v4
	global_load_lds_dwordx4 v154, s[38:39]
	s_mov_b32 m0, s92
	s_addc_u32 s3, s39, 0
	s_add_i32 s93, s85, 0x4000
	global_load_lds_dwordx4 v158, s[38:39]
	s_mov_b32 m0, s93
	s_add_i32 s42, s85, 0x6000
	global_load_lds_dwordx4 v154, s[2:3]
	s_mov_b32 m0, s42
	v_readlane_b32 s4, v255, 17
	global_load_lds_dwordx4 v158, s[2:3]
	v_mov_b32_e32 v157, v0
	v_mov_b32_e32 v161, v0
	v_mov_b32_e32 v155, v0
	v_mov_b32_e32 v159, v0
	v_readlane_b32 s5, v255, 18
	s_mov_b64 s[70:71], s[24:25]
	s_mov_b64 s[24:25], s[0:1]
	s_mov_b64 s[0:1], s[46:47]
	s_mov_b64 s[46:47], s[78:79]
	s_mov_b32 s78, s56
	v_lshl_add_u64 v[8:9], s[10:11], 0, v[156:157]
	v_lshl_add_u64 v[4:5], s[10:11], 0, v[160:161]
	v_lshl_add_u64 v[2:3], s[38:39], 0, v[154:155]
	v_cmp_ne_u32_e64 s[2:3], 1, v196
	s_andn2_b64 vcc, exec, s[4:5]
	v_lshl_add_u64 v[6:7], s[38:39], 0, v[158:159]
	s_cbranch_vccnz .LBB0_244
	s_barrier
	s_setprio 1

.LBB0_261:
	s_ashr_i32 s35, s34, 31
	s_lshl_b64 vcc, s[34:35], 21
	s_add_u32 s13, s30, vcc_lo
	s_addc_u32 s15, s31, vcc_hi
	s_add_u32 s54, s13, s54
	s_addc_u32 s55, s15, s55
	s_and_b64 s[86:87], s[86:87], exec
	s_cselect_b32 s13, s55, s11
	s_cselect_b32 s15, s54, s10
	s_add_i32 s35, s19, -2
	s_add_u32 s40, s10, 0x100
	s_addc_u32 s49, s11, 0
	s_add_u32 s10, s38, 0x100080
	s_addc_u32 s11, s39, 0
	s_mov_b32 s38, 0
	s_add_i32 vcc_lo, s38, 2
	s_add_u32 s39, s10, 0xfff00080
	s_addc_u32 s66, s11, -1
	s_add_i32 s67, 0, 0x10000
	s_cmp_eq_u32 s35, s38
	s_cselect_b32 s87, s53, s66
	s_cselect_b32 s86, s52, s39
	s_cselect_b32 s39, s13, s49
	s_cselect_b32 s38, s15, s40
	s_add_i32 vcc_hi, 0, 0x14000
	v_add_u32_e32 v142, s67, v1
	v_add_u32_e32 v180, vcc_hi, v1
	ds_read_b128 v[130:133], v142
	ds_read_b128 v[134:137], v142 offset:1024
	ds_read_b128 v[138:141], v142 offset:2048
	ds_read_b128 v[142:145], v142 offset:3072
	ds_read_b128 v[168:171], v180
	ds_read_b128 v[172:175], v180 offset:1024
	ds_read_b128 v[176:179], v180 offset:2048
	ds_read_b128 v[180:183], v180 offset:3072
	s_add_i32 m0, s85, 0xc000
	ds_read_b128 v[198:201], v197
	ds_read_b128 v[202:205], v197 offset:1024
	ds_read_b128 v[206:209], v197 offset:2048
	ds_read_b128 v[210:213], v197 offset:3072
	ds_read_b128 v[214:217], v197 offset:4096
	ds_read_b128 v[218:221], v197 offset:5120
	ds_read_b128 v[222:225], v197 offset:6144
	ds_read_b128 v[226:229], v197 offset:7168
	global_load_lds_dwordx4 v164, s[10:11]
	s_add_i32 m0, s85, 0xe000
	s_nop 0
	global_load_lds_dwordx4 v166, s[10:11]
	s_waitcnt vmcnt(8)
	s_waitcnt lgkmcnt(0)
	s_barrier
	v_mfma_f32_16x16x32_bf16 v[114:117], v[130:133], v[198:201], 0
	v_mfma_f32_16x16x32_bf16 v[118:121], v[138:141], v[198:201], 0
	v_mfma_f32_16x16x32_bf16 v[102:105], v[130:133], v[206:209], 0
	v_mfma_f32_16x16x32_bf16 v[98:101], v[138:141], v[206:209], 0
	v_mfma_f32_16x16x32_bf16 v[86:89], v[130:133], v[214:217], 0
	v_mfma_f32_16x16x32_bf16 v[82:85], v[138:141], v[214:217], 0
	v_mfma_f32_16x16x32_bf16 v[54:57], v[130:133], v[222:225], 0
	v_mfma_f32_16x16x32_bf16 v[50:53], v[138:141], v[222:225], 0
	v_mfma_f32_16x16x32_bf16 v[114:117], v[134:137], v[202:205], v[114:117]
	v_mfma_f32_16x16x32_bf16 v[118:121], v[142:145], v[202:205], v[118:121]
	v_mfma_f32_16x16x32_bf16 v[102:105], v[134:137], v[210:213], v[102:105]
	v_mfma_f32_16x16x32_bf16 v[98:101], v[142:145], v[210:213], v[98:101]
	v_mfma_f32_16x16x32_bf16 v[86:89], v[134:137], v[218:221], v[86:89]
	v_mfma_f32_16x16x32_bf16 v[82:85], v[142:145], v[218:221], v[82:85]
	v_mfma_f32_16x16x32_bf16 v[54:57], v[134:137], v[226:229], v[54:57]
	v_mfma_f32_16x16x32_bf16 v[50:53], v[142:145], v[226:229], v[50:53]
	v_mfma_f32_16x16x32_bf16 v[126:129], v[168:171], v[198:201], 0
	v_mfma_f32_16x16x32_bf16 v[122:125], v[176:179], v[198:201], 0
	v_mfma_f32_16x16x32_bf16 v[110:113], v[168:171], v[206:209], 0
	v_mfma_f32_16x16x32_bf16 v[106:109], v[176:179], v[206:209], 0
	v_mfma_f32_16x16x32_bf16 v[94:97], v[168:171], v[214:217], 0
	v_mfma_f32_16x16x32_bf16 v[90:93], v[176:179], v[214:217], 0
	v_mfma_f32_16x16x32_bf16 v[70:73], v[168:171], v[222:225], 0
	v_mfma_f32_16x16x32_bf16 v[66:69], v[176:179], v[222:225], 0
	v_mfma_f32_16x16x32_bf16 v[126:129], v[172:175], v[202:205], v[126:129]
	v_mfma_f32_16x16x32_bf16 v[122:125], v[180:183], v[202:205], v[122:125]
	v_mfma_f32_16x16x32_bf16 v[110:113], v[172:175], v[210:213], v[110:113]
	v_mfma_f32_16x16x32_bf16 v[106:109], v[180:183], v[210:213], v[106:109]
	v_mfma_f32_16x16x32_bf16 v[94:97], v[172:175], v[218:221], v[94:97]
	v_mfma_f32_16x16x32_bf16 v[90:93], v[180:183], v[218:221], v[90:93]
	v_mfma_f32_16x16x32_bf16 v[70:73], v[172:175], v[226:229], v[70:73]
	v_mfma_f32_16x16x32_bf16 v[66:69], v[180:183], v[226:229], v[66:69]
	s_barrier
	s_add_i32 s66, s67, s97
	s_add_u32 s98, s38, 0x80
	s_addc_u32 s99, s39, 0
	s_mov_b32 m0, s66
	ds_read_b128 v[198:201], v197 offset:16384
	ds_read_b128 v[202:205], v197 offset:17408
	ds_read_b128 v[206:209], v197 offset:18432
	ds_read_b128 v[210:213], v197 offset:19456
	ds_read_b128 v[214:217], v197 offset:20480
	ds_read_b128 v[218:221], v197 offset:21504
	ds_read_b128 v[222:225], v197 offset:22528
	ds_read_b128 v[226:229], v197 offset:23552
	global_load_lds_dwordx4 v156, s[38:39]
	s_add_i32 m0, s66, 0x2000
	s_add_u32 s66, s38, 0x100000
	s_addc_u32 s67, s39, 0
	s_add_i32 vcc_hi, vcc_hi, s97
	global_load_lds_dwordx4 v160, s[38:39]
	s_mov_b32 m0, vcc_hi
	s_add_u32 s100, s86, 0x80
	s_addc_u32 s101, s87, 0
	global_load_lds_dwordx4 v156, s[66:67]
	s_add_i32 m0, vcc_hi, 0x2000
	s_nop 0
	global_load_lds_dwordx4 v160, s[66:67]
	s_mov_b32 m0, s85
	s_nop 0
	global_load_lds_dwordx4 v154, s[86:87]
	s_mov_b32 m0, s92
	s_nop 0
	global_load_lds_dwordx4 v158, s[86:87]
	s_waitcnt vmcnt(8)
	s_waitcnt lgkmcnt(0)
	s_barrier
	v_mfma_f32_16x16x32_bf16 v[62:65], v[130:133], v[198:201], 0
	v_mfma_f32_16x16x32_bf16 v[58:61], v[138:141], v[198:201], 0
	v_mfma_f32_16x16x32_bf16 v[38:41], v[130:133], v[206:209], 0
	v_mfma_f32_16x16x32_bf16 v[34:37], v[138:141], v[206:209], 0
	v_mfma_f32_16x16x32_bf16 v[22:25], v[130:133], v[214:217], 0
	v_mfma_f32_16x16x32_bf16 v[18:21], v[138:141], v[214:217], 0
	v_mfma_f32_16x16x32_bf16 v[6:9], v[130:133], v[222:225], 0
	v_mfma_f32_16x16x32_bf16 v[2:5], v[138:141], v[222:225], 0
	v_mfma_f32_16x16x32_bf16 v[62:65], v[134:137], v[202:205], v[62:65]
	v_mfma_f32_16x16x32_bf16 v[58:61], v[142:145], v[202:205], v[58:61]
	v_mfma_f32_16x16x32_bf16 v[38:41], v[134:137], v[210:213], v[38:41]
	v_mfma_f32_16x16x32_bf16 v[34:37], v[142:145], v[210:213], v[34:37]
	v_mfma_f32_16x16x32_bf16 v[22:25], v[134:137], v[218:221], v[22:25]
	v_mfma_f32_16x16x32_bf16 v[18:21], v[142:145], v[218:221], v[18:21]
	v_mfma_f32_16x16x32_bf16 v[6:9], v[134:137], v[226:229], v[6:9]
	v_mfma_f32_16x16x32_bf16 v[2:5], v[142:145], v[226:229], v[2:5]
	v_mfma_f32_16x16x32_bf16 v[78:81], v[168:171], v[198:201], 0
	v_mfma_f32_16x16x32_bf16 v[74:77], v[176:179], v[198:201], 0
	v_mfma_f32_16x16x32_bf16 v[46:49], v[168:171], v[206:209], 0
	v_mfma_f32_16x16x32_bf16 v[42:45], v[176:179], v[206:209], 0
	v_mfma_f32_16x16x32_bf16 v[30:33], v[168:171], v[214:217], 0
	v_mfma_f32_16x16x32_bf16 v[26:29], v[176:179], v[214:217], 0
	v_mfma_f32_16x16x32_bf16 v[14:17], v[168:171], v[222:225], 0
	v_mfma_f32_16x16x32_bf16 v[10:13], v[176:179], v[222:225], 0
	v_mfma_f32_16x16x32_bf16 v[78:81], v[172:175], v[202:205], v[78:81]
	v_mfma_f32_16x16x32_bf16 v[74:77], v[180:183], v[202:205], v[74:77]
	v_mfma_f32_16x16x32_bf16 v[46:49], v[172:175], v[210:213], v[46:49]
	v_mfma_f32_16x16x32_bf16 v[42:45], v[180:183], v[210:213], v[42:45]
	v_mfma_f32_16x16x32_bf16 v[30:33], v[172:175], v[218:221], v[30:33]
	v_mfma_f32_16x16x32_bf16 v[26:29], v[180:183], v[218:221], v[26:29]
	v_mfma_f32_16x16x32_bf16 v[14:17], v[172:175], v[226:229], v[14:17]
	v_mfma_f32_16x16x32_bf16 v[10:13], v[180:183], v[226:229], v[10:13]
	s_barrier
	s_add_i32 vcc_hi, 0, 0x18000
	s_add_i32 s56, 0, 0x1c000
	v_add_u32_e32 v142, vcc_hi, v1
	v_add_u32_e32 v180, s56, v1
	ds_read_b128 v[130:133], v142
	ds_read_b128 v[134:137], v142 offset:1024
	ds_read_b128 v[138:141], v142 offset:2048
	ds_read_b128 v[142:145], v142 offset:3072
	ds_read_b128 v[168:171], v180
	ds_read_b128 v[172:175], v180 offset:1024
	ds_read_b128 v[176:179], v180 offset:2048
	ds_read_b128 v[180:183], v180 offset:3072
	s_add_u32 s66, s86, 0x100000
	s_addc_u32 s67, s87, 0
	s_mov_b32 m0, s93
	ds_read_b128 v[198:201], v197 offset:32768
	ds_read_b128 v[202:205], v197 offset:33792
	ds_read_b128 v[206:209], v197 offset:34816
	ds_read_b128 v[210:213], v197 offset:35840
	ds_read_b128 v[214:217], v197 offset:36864
	ds_read_b128 v[218:221], v197 offset:37888
	ds_read_b128 v[222:225], v197 offset:38912
	ds_read_b128 v[226:229], v197 offset:39936
	global_load_lds_dwordx4 v154, s[66:67]
	s_mov_b32 m0, s42
	s_nop 0
	global_load_lds_dwordx4 v158, s[66:67]
	s_waitcnt vmcnt(8)
	s_waitcnt lgkmcnt(0)
	s_barrier
	v_mfma_f32_16x16x32_bf16 v[114:117], v[130:133], v[198:201], v[114:117]
	v_mfma_f32_16x16x32_bf16 v[118:121], v[138:141], v[198:201], v[118:121]
	v_mfma_f32_16x16x32_bf16 v[102:105], v[130:133], v[206:209], v[102:105]
	v_mfma_f32_16x16x32_bf16 v[98:101], v[138:141], v[206:209], v[98:101]
	v_mfma_f32_16x16x32_bf16 v[86:89], v[130:133], v[214:217], v[86:89]
	v_mfma_f32_16x16x32_bf16 v[82:85], v[138:141], v[214:217], v[82:85]
	v_mfma_f32_16x16x32_bf16 v[54:57], v[130:133], v[222:225], v[54:57]
	v_mfma_f32_16x16x32_bf16 v[50:53], v[138:141], v[222:225], v[50:53]
	v_mfma_f32_16x16x32_bf16 v[114:117], v[134:137], v[202:205], v[114:117]
	v_mfma_f32_16x16x32_bf16 v[118:121], v[142:145], v[202:205], v[118:121]
	v_mfma_f32_16x16x32_bf16 v[102:105], v[134:137], v[210:213], v[102:105]
	v_mfma_f32_16x16x32_bf16 v[98:101], v[142:145], v[210:213], v[98:101]
	v_mfma_f32_16x16x32_bf16 v[86:89], v[134:137], v[218:221], v[86:89]
	v_mfma_f32_16x16x32_bf16 v[82:85], v[142:145], v[218:221], v[82:85]
	v_mfma_f32_16x16x32_bf16 v[54:57], v[134:137], v[226:229], v[54:57]
	v_mfma_f32_16x16x32_bf16 v[50:53], v[142:145], v[226:229], v[50:53]
	v_mfma_f32_16x16x32_bf16 v[126:129], v[168:171], v[198:201], v[126:129]
	v_mfma_f32_16x16x32_bf16 v[122:125], v[176:179], v[198:201], v[122:125]
	v_mfma_f32_16x16x32_bf16 v[110:113], v[168:171], v[206:209], v[110:113]
	v_mfma_f32_16x16x32_bf16 v[106:109], v[176:179], v[206:209], v[106:109]
	v_mfma_f32_16x16x32_bf16 v[94:97], v[168:171], v[214:217], v[94:97]
	v_mfma_f32_16x16x32_bf16 v[90:93], v[176:179], v[214:217], v[90:93]
	v_mfma_f32_16x16x32_bf16 v[70:73], v[168:171], v[222:225], v[70:73]
	v_mfma_f32_16x16x32_bf16 v[66:69], v[176:179], v[222:225], v[66:69]
	v_mfma_f32_16x16x32_bf16 v[126:129], v[172:175], v[202:205], v[126:129]
	v_mfma_f32_16x16x32_bf16 v[122:125], v[180:183], v[202:205], v[122:125]
	v_mfma_f32_16x16x32_bf16 v[110:113], v[172:175], v[210:213], v[110:113]
	v_mfma_f32_16x16x32_bf16 v[106:109], v[180:183], v[210:213], v[106:109]
	v_mfma_f32_16x16x32_bf16 v[94:97], v[172:175], v[218:221], v[94:97]
	v_mfma_f32_16x16x32_bf16 v[90:93], v[180:183], v[218:221], v[90:93]
	v_mfma_f32_16x16x32_bf16 v[70:73], v[172:175], v[226:229], v[70:73]
	v_mfma_f32_16x16x32_bf16 v[66:69], v[180:183], v[226:229], v[66:69]
	s_barrier
	s_add_i32 s57, vcc_hi, s97
	s_mov_b32 m0, s57
	ds_read_b128 v[198:201], v197 offset:49152
	ds_read_b128 v[202:205], v197 offset:50176
	ds_read_b128 v[206:209], v197 offset:51200
	ds_read_b128 v[210:213], v197 offset:52224
	ds_read_b128 v[214:217], v197 offset:53248
	ds_read_b128 v[218:221], v197 offset:54272
	ds_read_b128 v[222:225], v197 offset:55296
	ds_read_b128 v[226:229], v197 offset:56320
	global_load_lds_dwordx4 v156, s[98:99]
	s_add_i32 m0, s57, 0x2000
	s_add_u32 s38, s38, 0x100080
	s_addc_u32 s39, s39, 0
	s_add_i32 s56, s56, s97
	global_load_lds_dwordx4 v160, s[98:99]
	s_mov_b32 m0, s56
	s_nop 0
	global_load_lds_dwordx4 v156, s[38:39]
	s_add_i32 m0, s56, 0x2000
	s_nop 0
	global_load_lds_dwordx4 v160, s[38:39]
	s_mov_b32 m0, s43
	s_nop 0
	global_load_lds_dwordx4 v154, s[100:101]
	s_mov_b32 m0, s90
	s_nop 0
	global_load_lds_dwordx4 v158, s[100:101]
	s_waitcnt vmcnt(8)
	s_waitcnt lgkmcnt(0)
	s_barrier
	v_mfma_f32_16x16x32_bf16 v[62:65], v[130:133], v[198:201], v[62:65]
	v_mfma_f32_16x16x32_bf16 v[58:61], v[138:141], v[198:201], v[58:61]
	v_mfma_f32_16x16x32_bf16 v[38:41], v[130:133], v[206:209], v[38:41]
	v_mfma_f32_16x16x32_bf16 v[34:37], v[138:141], v[206:209], v[34:37]
	v_mfma_f32_16x16x32_bf16 v[22:25], v[130:133], v[214:217], v[22:25]
	v_mfma_f32_16x16x32_bf16 v[18:21], v[138:141], v[214:217], v[18:21]
	v_mfma_f32_16x16x32_bf16 v[6:9], v[130:133], v[222:225], v[6:9]
	v_mfma_f32_16x16x32_bf16 v[2:5], v[138:141], v[222:225], v[2:5]
	v_mfma_f32_16x16x32_bf16 v[62:65], v[134:137], v[202:205], v[62:65]
	v_mfma_f32_16x16x32_bf16 v[58:61], v[142:145], v[202:205], v[58:61]
	v_mfma_f32_16x16x32_bf16 v[38:41], v[134:137], v[210:213], v[38:41]
	v_mfma_f32_16x16x32_bf16 v[34:37], v[142:145], v[210:213], v[34:37]
	v_mfma_f32_16x16x32_bf16 v[22:25], v[134:137], v[218:221], v[22:25]
	v_mfma_f32_16x16x32_bf16 v[18:21], v[142:145], v[218:221], v[18:21]
	v_mfma_f32_16x16x32_bf16 v[6:9], v[134:137], v[226:229], v[6:9]
	v_mfma_f32_16x16x32_bf16 v[2:5], v[142:145], v[226:229], v[2:5]
	v_mfma_f32_16x16x32_bf16 v[78:81], v[168:171], v[198:201], v[78:81]
	v_mfma_f32_16x16x32_bf16 v[74:77], v[176:179], v[198:201], v[74:77]
	v_mfma_f32_16x16x32_bf16 v[46:49], v[168:171], v[206:209], v[46:49]
	v_mfma_f32_16x16x32_bf16 v[42:45], v[176:179], v[206:209], v[42:45]
	v_mfma_f32_16x16x32_bf16 v[30:33], v[168:171], v[214:217], v[30:33]
	v_mfma_f32_16x16x32_bf16 v[26:29], v[176:179], v[214:217], v[26:29]
	v_mfma_f32_16x16x32_bf16 v[14:17], v[168:171], v[222:225], v[14:17]
	v_mfma_f32_16x16x32_bf16 v[10:13], v[176:179], v[222:225], v[10:13]
	v_mfma_f32_16x16x32_bf16 v[78:81], v[172:175], v[202:205], v[78:81]
	v_mfma_f32_16x16x32_bf16 v[74:77], v[180:183], v[202:205], v[74:77]
	v_mfma_f32_16x16x32_bf16 v[46:49], v[172:175], v[210:213], v[46:49]
	v_mfma_f32_16x16x32_bf16 v[42:45], v[180:183], v[210:213], v[42:45]
	v_mfma_f32_16x16x32_bf16 v[30:33], v[172:175], v[218:221], v[30:33]
	v_mfma_f32_16x16x32_bf16 v[26:29], v[180:183], v[218:221], v[26:29]
	v_mfma_f32_16x16x32_bf16 v[14:17], v[172:175], v[226:229], v[14:17]
	v_mfma_f32_16x16x32_bf16 v[10:13], v[180:183], v[226:229], v[10:13]
	s_barrier
	s_add_u32 s40, s40, 0x100
	s_addc_u32 s49, s49, 0
	s_add_u32 s10, s10, 0x100
	s_addc_u32 s11, s11, 0
	s_cmp_ge_u32 vcc_lo, s19
	s_mov_b32 s38, vcc_lo
	s_cbranch_scc1 .Lpeel_done_0
.LBB0_262:
	s_add_i32 vcc_lo, s38, 2
	s_add_u32 s39, s10, 0xfff00080
	s_addc_u32 s66, s11, -1
	s_add_i32 s67, 0, 0x10000
	s_cmp_eq_u32 s35, s38
	s_cselect_b32 s87, s53, s66
	s_cselect_b32 s86, s52, s39
	s_cselect_b32 s39, s13, s49
	s_cselect_b32 s38, s15, s40
	s_add_i32 vcc_hi, 0, 0x14000
	v_add_u32_e32 v142, s67, v1
	v_add_u32_e32 v180, vcc_hi, v1
	ds_read_b128 v[130:133], v142
	ds_read_b128 v[134:137], v142 offset:1024
	ds_read_b128 v[138:141], v142 offset:2048
	ds_read_b128 v[142:145], v142 offset:3072
	ds_read_b128 v[168:171], v180
	ds_read_b128 v[172:175], v180 offset:1024
	ds_read_b128 v[176:179], v180 offset:2048
	ds_read_b128 v[180:183], v180 offset:3072
	s_add_i32 m0, s85, 0xc000
	ds_read_b128 v[198:201], v197
	ds_read_b128 v[202:205], v197 offset:1024
	ds_read_b128 v[206:209], v197 offset:2048
	ds_read_b128 v[210:213], v197 offset:3072
	ds_read_b128 v[214:217], v197 offset:4096
	ds_read_b128 v[218:221], v197 offset:5120
	ds_read_b128 v[222:225], v197 offset:6144
	ds_read_b128 v[226:229], v197 offset:7168
	global_load_lds_dwordx4 v164, s[10:11]
	s_add_i32 m0, s85, 0xe000
	s_nop 0
	global_load_lds_dwordx4 v166, s[10:11]
	s_waitcnt vmcnt(8)
	s_waitcnt lgkmcnt(0)
	s_barrier
	v_mfma_f32_16x16x32_bf16 v[114:117], v[130:133], v[198:201], v[114:117]
	v_mfma_f32_16x16x32_bf16 v[118:121], v[138:141], v[198:201], v[118:121]
	v_mfma_f32_16x16x32_bf16 v[102:105], v[130:133], v[206:209], v[102:105]
	v_mfma_f32_16x16x32_bf16 v[98:101], v[138:141], v[206:209], v[98:101]
	v_mfma_f32_16x16x32_bf16 v[86:89], v[130:133], v[214:217], v[86:89]
	v_mfma_f32_16x16x32_bf16 v[82:85], v[138:141], v[214:217], v[82:85]
	v_mfma_f32_16x16x32_bf16 v[54:57], v[130:133], v[222:225], v[54:57]
	v_mfma_f32_16x16x32_bf16 v[50:53], v[138:141], v[222:225], v[50:53]
	v_mfma_f32_16x16x32_bf16 v[114:117], v[134:137], v[202:205], v[114:117]
	v_mfma_f32_16x16x32_bf16 v[118:121], v[142:145], v[202:205], v[118:121]
	v_mfma_f32_16x16x32_bf16 v[102:105], v[134:137], v[210:213], v[102:105]
	v_mfma_f32_16x16x32_bf16 v[98:101], v[142:145], v[210:213], v[98:101]
	v_mfma_f32_16x16x32_bf16 v[86:89], v[134:137], v[218:221], v[86:89]
	v_mfma_f32_16x16x32_bf16 v[82:85], v[142:145], v[218:221], v[82:85]
	v_mfma_f32_16x16x32_bf16 v[54:57], v[134:137], v[226:229], v[54:57]
	v_mfma_f32_16x16x32_bf16 v[50:53], v[142:145], v[226:229], v[50:53]
	v_mfma_f32_16x16x32_bf16 v[126:129], v[168:171], v[198:201], v[126:129]
	v_mfma_f32_16x16x32_bf16 v[122:125], v[176:179], v[198:201], v[122:125]
	v_mfma_f32_16x16x32_bf16 v[110:113], v[168:171], v[206:209], v[110:113]
	v_mfma_f32_16x16x32_bf16 v[106:109], v[176:179], v[206:209], v[106:109]
	v_mfma_f32_16x16x32_bf16 v[94:97], v[168:171], v[214:217], v[94:97]
	v_mfma_f32_16x16x32_bf16 v[90:93], v[176:179], v[214:217], v[90:93]
	v_mfma_f32_16x16x32_bf16 v[70:73], v[168:171], v[222:225], v[70:73]
	v_mfma_f32_16x16x32_bf16 v[66:69], v[176:179], v[222:225], v[66:69]
	v_mfma_f32_16x16x32_bf16 v[126:129], v[172:175], v[202:205], v[126:129]
	v_mfma_f32_16x16x32_bf16 v[122:125], v[180:183], v[202:205], v[122:125]
	v_mfma_f32_16x16x32_bf16 v[110:113], v[172:175], v[210:213], v[110:113]
	v_mfma_f32_16x16x32_bf16 v[106:109], v[180:183], v[210:213], v[106:109]
	v_mfma_f32_16x16x32_bf16 v[94:97], v[172:175], v[218:221], v[94:97]
	v_mfma_f32_16x16x32_bf16 v[90:93], v[180:183], v[218:221], v[90:93]
	v_mfma_f32_16x16x32_bf16 v[70:73], v[172:175], v[226:229], v[70:73]
	v_mfma_f32_16x16x32_bf16 v[66:69], v[180:183], v[226:229], v[66:69]
	s_barrier
	s_add_i32 s66, s67, s97
	s_add_u32 s98, s38, 0x80
	s_addc_u32 s99, s39, 0
	s_mov_b32 m0, s66
	ds_read_b128 v[198:201], v197 offset:16384
	ds_read_b128 v[202:205], v197 offset:17408
	ds_read_b128 v[206:209], v197 offset:18432
	ds_read_b128 v[210:213], v197 offset:19456
	ds_read_b128 v[214:217], v197 offset:20480
	ds_read_b128 v[218:221], v197 offset:21504
	ds_read_b128 v[222:225], v197 offset:22528
	ds_read_b128 v[226:229], v197 offset:23552
	global_load_lds_dwordx4 v156, s[38:39]
	s_add_i32 m0, s66, 0x2000
	s_add_u32 s66, s38, 0x100000
	s_addc_u32 s67, s39, 0
	s_add_i32 vcc_hi, vcc_hi, s97
	global_load_lds_dwordx4 v160, s[38:39]
	s_mov_b32 m0, vcc_hi
	s_add_u32 s100, s86, 0x80
	s_addc_u32 s101, s87, 0
	global_load_lds_dwordx4 v156, s[66:67]
	s_add_i32 m0, vcc_hi, 0x2000
	s_nop 0
	global_load_lds_dwordx4 v160, s[66:67]
	s_mov_b32 m0, s85
	s_nop 0
	global_load_lds_dwordx4 v154, s[86:87]
	s_mov_b32 m0, s92
	s_nop 0
	global_load_lds_dwordx4 v158, s[86:87]
	s_waitcnt vmcnt(8)
	s_waitcnt lgkmcnt(0)
	s_barrier
	v_mfma_f32_16x16x32_bf16 v[62:65], v[130:133], v[198:201], v[62:65]
	v_mfma_f32_16x16x32_bf16 v[58:61], v[138:141], v[198:201], v[58:61]
	v_mfma_f32_16x16x32_bf16 v[38:41], v[130:133], v[206:209], v[38:41]
	v_mfma_f32_16x16x32_bf16 v[34:37], v[138:141], v[206:209], v[34:37]
	v_mfma_f32_16x16x32_bf16 v[22:25], v[130:133], v[214:217], v[22:25]
	v_mfma_f32_16x16x32_bf16 v[18:21], v[138:141], v[214:217], v[18:21]
	v_mfma_f32_16x16x32_bf16 v[6:9], v[130:133], v[222:225], v[6:9]
	v_mfma_f32_16x16x32_bf16 v[2:5], v[138:141], v[222:225], v[2:5]
	v_mfma_f32_16x16x32_bf16 v[62:65], v[134:137], v[202:205], v[62:65]
	v_mfma_f32_16x16x32_bf16 v[58:61], v[142:145], v[202:205], v[58:61]
	v_mfma_f32_16x16x32_bf16 v[38:41], v[134:137], v[210:213], v[38:41]
	v_mfma_f32_16x16x32_bf16 v[34:37], v[142:145], v[210:213], v[34:37]
	v_mfma_f32_16x16x32_bf16 v[22:25], v[134:137], v[218:221], v[22:25]
	v_mfma_f32_16x16x32_bf16 v[18:21], v[142:145], v[218:221], v[18:21]
	v_mfma_f32_16x16x32_bf16 v[6:9], v[134:137], v[226:229], v[6:9]
	v_mfma_f32_16x16x32_bf16 v[2:5], v[142:145], v[226:229], v[2:5]
	v_mfma_f32_16x16x32_bf16 v[78:81], v[168:171], v[198:201], v[78:81]
	v_mfma_f32_16x16x32_bf16 v[74:77], v[176:179], v[198:201], v[74:77]
	v_mfma_f32_16x16x32_bf16 v[46:49], v[168:171], v[206:209], v[46:49]
	v_mfma_f32_16x16x32_bf16 v[42:45], v[176:179], v[206:209], v[42:45]
	v_mfma_f32_16x16x32_bf16 v[30:33], v[168:171], v[214:217], v[30:33]
	v_mfma_f32_16x16x32_bf16 v[26:29], v[176:179], v[214:217], v[26:29]
	v_mfma_f32_16x16x32_bf16 v[14:17], v[168:171], v[222:225], v[14:17]
	v_mfma_f32_16x16x32_bf16 v[10:13], v[176:179], v[222:225], v[10:13]
	v_mfma_f32_16x16x32_bf16 v[78:81], v[172:175], v[202:205], v[78:81]
	v_mfma_f32_16x16x32_bf16 v[74:77], v[180:183], v[202:205], v[74:77]
	v_mfma_f32_16x16x32_bf16 v[46:49], v[172:175], v[210:213], v[46:49]
	v_mfma_f32_16x16x32_bf16 v[42:45], v[180:183], v[210:213], v[42:45]
	v_mfma_f32_16x16x32_bf16 v[30:33], v[172:175], v[218:221], v[30:33]
	v_mfma_f32_16x16x32_bf16 v[26:29], v[180:183], v[218:221], v[26:29]
	v_mfma_f32_16x16x32_bf16 v[14:17], v[172:175], v[226:229], v[14:17]
	v_mfma_f32_16x16x32_bf16 v[10:13], v[180:183], v[226:229], v[10:13]
	s_barrier
	s_add_i32 vcc_hi, 0, 0x18000
	s_add_i32 s56, 0, 0x1c000
	v_add_u32_e32 v142, vcc_hi, v1
	v_add_u32_e32 v180, s56, v1
	ds_read_b128 v[130:133], v142
	ds_read_b128 v[134:137], v142 offset:1024
	ds_read_b128 v[138:141], v142 offset:2048
	ds_read_b128 v[142:145], v142 offset:3072
	ds_read_b128 v[168:171], v180
	ds_read_b128 v[172:175], v180 offset:1024
	ds_read_b128 v[176:179], v180 offset:2048
	ds_read_b128 v[180:183], v180 offset:3072
	s_add_u32 s66, s86, 0x100000
	s_addc_u32 s67, s87, 0
	s_mov_b32 m0, s93
	ds_read_b128 v[198:201], v197 offset:32768
	ds_read_b128 v[202:205], v197 offset:33792
	ds_read_b128 v[206:209], v197 offset:34816
	ds_read_b128 v[210:213], v197 offset:35840
	ds_read_b128 v[214:217], v197 offset:36864
	ds_read_b128 v[218:221], v197 offset:37888
	ds_read_b128 v[222:225], v197 offset:38912
	ds_read_b128 v[226:229], v197 offset:39936
	global_load_lds_dwordx4 v154, s[66:67]
	s_mov_b32 m0, s42
	s_nop 0
	global_load_lds_dwordx4 v158, s[66:67]
	s_waitcnt vmcnt(8)
	s_waitcnt lgkmcnt(0)
	s_barrier
	v_mfma_f32_16x16x32_bf16 v[114:117], v[130:133], v[198:201], v[114:117]
	v_mfma_f32_16x16x32_bf16 v[118:121], v[138:141], v[198:201], v[118:121]
	v_mfma_f32_16x16x32_bf16 v[102:105], v[130:133], v[206:209], v[102:105]
	v_mfma_f32_16x16x32_bf16 v[98:101], v[138:141], v[206:209], v[98:101]
	v_mfma_f32_16x16x32_bf16 v[86:89], v[130:133], v[214:217], v[86:89]
	v_mfma_f32_16x16x32_bf16 v[82:85], v[138:141], v[214:217], v[82:85]
	v_mfma_f32_16x16x32_bf16 v[54:57], v[130:133], v[222:225], v[54:57]
	v_mfma_f32_16x16x32_bf16 v[50:53], v[138:141], v[222:225], v[50:53]
	v_mfma_f32_16x16x32_bf16 v[114:117], v[134:137], v[202:205], v[114:117]
	v_mfma_f32_16x16x32_bf16 v[118:121], v[142:145], v[202:205], v[118:121]
	v_mfma_f32_16x16x32_bf16 v[102:105], v[134:137], v[210:213], v[102:105]
	v_mfma_f32_16x16x32_bf16 v[98:101], v[142:145], v[210:213], v[98:101]
	v_mfma_f32_16x16x32_bf16 v[86:89], v[134:137], v[218:221], v[86:89]
	v_mfma_f32_16x16x32_bf16 v[82:85], v[142:145], v[218:221], v[82:85]
	v_mfma_f32_16x16x32_bf16 v[54:57], v[134:137], v[226:229], v[54:57]
	v_mfma_f32_16x16x32_bf16 v[50:53], v[142:145], v[226:229], v[50:53]
	v_mfma_f32_16x16x32_bf16 v[126:129], v[168:171], v[198:201], v[126:129]
	v_mfma_f32_16x16x32_bf16 v[122:125], v[176:179], v[198:201], v[122:125]
	v_mfma_f32_16x16x32_bf16 v[110:113], v[168:171], v[206:209], v[110:113]
	v_mfma_f32_16x16x32_bf16 v[106:109], v[176:179], v[206:209], v[106:109]
	v_mfma_f32_16x16x32_bf16 v[94:97], v[168:171], v[214:217], v[94:97]
	v_mfma_f32_16x16x32_bf16 v[90:93], v[176:179], v[214:217], v[90:93]
	v_mfma_f32_16x16x32_bf16 v[70:73], v[168:171], v[222:225], v[70:73]
	v_mfma_f32_16x16x32_bf16 v[66:69], v[176:179], v[222:225], v[66:69]
	v_mfma_f32_16x16x32_bf16 v[126:129], v[172:175], v[202:205], v[126:129]
	v_mfma_f32_16x16x32_bf16 v[122:125], v[180:183], v[202:205], v[122:125]
	v_mfma_f32_16x16x32_bf16 v[110:113], v[172:175], v[210:213], v[110:113]
	v_mfma_f32_16x16x32_bf16 v[106:109], v[180:183], v[210:213], v[106:109]
	v_mfma_f32_16x16x32_bf16 v[94:97], v[172:175], v[218:221], v[94:97]
	v_mfma_f32_16x16x32_bf16 v[90:93], v[180:183], v[218:221], v[90:93]
	v_mfma_f32_16x16x32_bf16 v[70:73], v[172:175], v[226:229], v[70:73]
	v_mfma_f32_16x16x32_bf16 v[66:69], v[180:183], v[226:229], v[66:69]
	s_barrier
	s_add_i32 s57, vcc_hi, s97
	s_mov_b32 m0, s57
	ds_read_b128 v[198:201], v197 offset:49152
	ds_read_b128 v[202:205], v197 offset:50176
	ds_read_b128 v[206:209], v197 offset:51200
	ds_read_b128 v[210:213], v197 offset:52224
	ds_read_b128 v[214:217], v197 offset:53248
	ds_read_b128 v[218:221], v197 offset:54272
	ds_read_b128 v[222:225], v197 offset:55296
	ds_read_b128 v[226:229], v197 offset:56320
	global_load_lds_dwordx4 v156, s[98:99]
	s_add_i32 m0, s57, 0x2000
	s_add_u32 s38, s38, 0x100080
	s_addc_u32 s39, s39, 0
	s_add_i32 s56, s56, s97
	global_load_lds_dwordx4 v160, s[98:99]
	s_mov_b32 m0, s56
	s_nop 0
	global_load_lds_dwordx4 v156, s[38:39]
	s_add_i32 m0, s56, 0x2000
	s_nop 0
	global_load_lds_dwordx4 v160, s[38:39]
	s_mov_b32 m0, s43
	s_nop 0
	global_load_lds_dwordx4 v154, s[100:101]
	s_mov_b32 m0, s90
	s_nop 0
	global_load_lds_dwordx4 v158, s[100:101]
	s_waitcnt vmcnt(8)
	s_waitcnt lgkmcnt(0)
	s_barrier
	v_mfma_f32_16x16x32_bf16 v[62:65], v[130:133], v[198:201], v[62:65]
	v_mfma_f32_16x16x32_bf16 v[58:61], v[138:141], v[198:201], v[58:61]
	v_mfma_f32_16x16x32_bf16 v[38:41], v[130:133], v[206:209], v[38:41]
	v_mfma_f32_16x16x32_bf16 v[34:37], v[138:141], v[206:209], v[34:37]
	v_mfma_f32_16x16x32_bf16 v[22:25], v[130:133], v[214:217], v[22:25]
	v_mfma_f32_16x16x32_bf16 v[18:21], v[138:141], v[214:217], v[18:21]
	v_mfma_f32_16x16x32_bf16 v[6:9], v[130:133], v[222:225], v[6:9]
	v_mfma_f32_16x16x32_bf16 v[2:5], v[138:141], v[222:225], v[2:5]
	v_mfma_f32_16x16x32_bf16 v[62:65], v[134:137], v[202:205], v[62:65]
	v_mfma_f32_16x16x32_bf16 v[58:61], v[142:145], v[202:205], v[58:61]
	v_mfma_f32_16x16x32_bf16 v[38:41], v[134:137], v[210:213], v[38:41]
	v_mfma_f32_16x16x32_bf16 v[34:37], v[142:145], v[210:213], v[34:37]
	v_mfma_f32_16x16x32_bf16 v[22:25], v[134:137], v[218:221], v[22:25]
	v_mfma_f32_16x16x32_bf16 v[18:21], v[142:145], v[218:221], v[18:21]
	v_mfma_f32_16x16x32_bf16 v[6:9], v[134:137], v[226:229], v[6:9]
	v_mfma_f32_16x16x32_bf16 v[2:5], v[142:145], v[226:229], v[2:5]
	v_mfma_f32_16x16x32_bf16 v[78:81], v[168:171], v[198:201], v[78:81]
	v_mfma_f32_16x16x32_bf16 v[74:77], v[176:179], v[198:201], v[74:77]
	v_mfma_f32_16x16x32_bf16 v[46:49], v[168:171], v[206:209], v[46:49]
	v_mfma_f32_16x16x32_bf16 v[42:45], v[176:179], v[206:209], v[42:45]
	v_mfma_f32_16x16x32_bf16 v[30:33], v[168:171], v[214:217], v[30:33]
	v_mfma_f32_16x16x32_bf16 v[26:29], v[176:179], v[214:217], v[26:29]
	v_mfma_f32_16x16x32_bf16 v[14:17], v[168:171], v[222:225], v[14:17]
	v_mfma_f32_16x16x32_bf16 v[10:13], v[176:179], v[222:225], v[10:13]
	v_mfma_f32_16x16x32_bf16 v[78:81], v[172:175], v[202:205], v[78:81]
	v_mfma_f32_16x16x32_bf16 v[74:77], v[180:183], v[202:205], v[74:77]
	v_mfma_f32_16x16x32_bf16 v[46:49], v[172:175], v[210:213], v[46:49]
	v_mfma_f32_16x16x32_bf16 v[42:45], v[180:183], v[210:213], v[42:45]
	v_mfma_f32_16x16x32_bf16 v[30:33], v[172:175], v[218:221], v[30:33]
	v_mfma_f32_16x16x32_bf16 v[26:29], v[180:183], v[218:221], v[26:29]
	v_mfma_f32_16x16x32_bf16 v[14:17], v[172:175], v[226:229], v[14:17]
	v_mfma_f32_16x16x32_bf16 v[10:13], v[180:183], v[226:229], v[10:13]
	s_barrier
	s_add_u32 s40, s40, 0x100
	s_addc_u32 s49, s49, 0
	s_add_u32 s10, s10, 0x100
	s_addc_u32 s11, s11, 0
	s_cmp_ge_u32 vcc_lo, s19
	s_mov_b32 s38, vcc_lo
	s_cbranch_scc0 .LBB0_262

.LBB0_376:
	s_setprio 0
	s_waitcnt vmcnt(0)
	s_mov_b32 s56, s78
	s_mov_b64 s[78:79], s[46:47]
	s_mov_b64 s[46:47], s[0:1]
	s_mov_b64 s[0:1], s[24:25]
	s_mov_b64 s[24:25], s[70:71]
	v_readlane_b32 s70, v255, 34
	v_readlane_b32 s91, v255, 33
	s_mov_b32 s92, s44
	s_mov_b32 s44, s45
	v_readlane_b32 s71, v255, 35
	s_mov_b32 s21, 0x21000
	s_mov_b32 s22, 0x41000
	s_mov_b32 s23, 0x61000
	s_mov_b32 s45, 0x23000
	s_mov_b32 s57, 0x43000
	s_mov_b32 s85, 0x63000
	s_barrier

.LBB0_1684:
	s_and_b32 s2, s91, 7
	v_readlane_b32 s3, v254, 56
	s_cmp_lt_i32 s3, 16
	s_cselect_b64 s[0:1], -1, 0
	s_cmp_lg_u64 s[0:1], 0
	s_addc_u32 s0, s3, 0
	s_lshl_b32 s0, s0, 3
	s_cmp_lg_u32 s3, 16
	s_cselect_b32 s0, s0, 8
	s_and_b32 s1, s51, 0x60
	v_writelane_b32 v255, s1, 14
	s_lshr_b32 s1, s1, 3
	s_cmp_gt_u32 s91, 7
	s_cselect_b32 s0, s0, 0
	s_or_b32 s2, s0, s2
	v_writelane_b32 v255, s1, 11
	s_and_b64 s[0:1], s[60:61], exec
	s_cselect_b32 s2, s2, s91
	s_cmpk_lt_i32 s2, 0x110
	s_cselect_b32 s0, s2, 0
	s_ashr_i32 s1, s0, 31
	s_lshr_b32 s1, s1, 29
	s_add_i32 s1, s0, s1
	s_ashr_i32 s3, s1, 3
	s_and_b32 s1, s1, -8
	s_sub_i32 s0, s0, s1
	s_cmp_lt_i32 s0, 0
	s_cselect_b32 s1, 35, 34
	s_mul_i32 s4, s0, s1
	s_add_i32 s4, s4, s3
	s_ashr_i32 s0, s4, 31
	s_lshr_b32 s0, s0, 26
	s_add_i32 s5, s4, s0
	s_ashr_i32 s0, s5, 6
	s_lshl_b32 s0, s0, 3
	s_sub_i32 s1, 34, s0
	s_min_i32 s1, s1, 8
	s_abs_i32 s3, s1
	v_cvt_f32_u32_e32 v0, s3
	v_cmp_ne_u32_e64 s[8:9], 1, v196
	s_cmpk_gt_i32 s2, 0x10f
	v_mbcnt_lo_u32_b32 v11, -1, 0
	v_mbcnt_hi_u32_b32 v11, -1, v11
	v_rcp_iflag_f32_e32 v0, v0
	v_writelane_b32 v254, s8, 58
	v_mul_f32_e32 v0, 0x4f7ffffe, v0
	v_cvt_u32_f32_e32 v0, v0
	v_writelane_b32 v254, s9, 59
	v_readfirstlane_b32 s7, v0
	s_cbranch_scc1 .LBB0_1700
	s_sub_i32 s12, 0, s3
	s_andn2_b32 s5, s5, 63
	s_mul_i32 s12, s12, s7
	v_lshl_add_u32 v0, v11, 4, s97
	s_sub_i32 s4, s4, s5
	s_mul_hi_u32 s12, s7, s12
	v_add_u32_e32 v1, 0x2000, v0
	s_abs_i32 s9, s4
	s_add_i32 s7, s7, s12
	v_ashrrev_i32_e32 v2, 31, v1
	s_ashr_i32 s5, s4, 31
	s_ashr_i32 s8, s1, 31
	s_mul_hi_u32 s7, s9, s7
	v_lshrrev_b32_e32 v2, 22, v2
	s_xor_b32 s5, s5, s8
	s_mul_i32 s8, s7, s3
	v_add_u32_e32 v2, v1, v2
	s_sub_i32 s8, s9, s8
	v_ashrrev_i32_e32 v8, 10, v2
	s_add_i32 s9, s7, 1
	s_sub_i32 s12, s8, s3
	v_mul_i32_i24_e32 v2, 0x400, v8
	s_cmp_ge_u32 s8, s3
	v_sub_u32_e32 v1, v1, v2
	s_cselect_b32 s7, s9, s7
	v_lshrrev_b32_e32 v2, 4, v1
	s_cselect_b32 s8, s12, s8
	s_add_i32 s9, s7, 1
	v_bitop3_b32 v1, v2, v1, 32 bitop3:0x6c
	s_cmp_ge_u32 s8, s3
	v_ashrrev_i32_e32 v2, 31, v1
	s_cselect_b32 s3, s9, s7
	v_lshrrev_b32_e32 v2, 26, v2
	s_xor_b32 s3, s3, s5
	v_add_u32_e32 v2, v1, v2
	s_sub_i32 s20, s3, s5
	v_ashrrev_i32_e32 v9, 6, v2
	v_lshlrev_b32_e32 v3, 3, v8
	v_and_b32_e32 v2, 0xffc0, v2
	s_mul_i32 s1, s20, s1
	v_and_b32_e32 v3, -16, v3
	v_sub_u32_e32 v1, v1, v2
	s_sub_i32 s1, s4, s1
	v_add_u32_e32 v3, v9, v3
	v_lshrrev_b16_e32 v2, 7, v1
	s_add_i32 s18, s0, s1
	v_and_b32_e32 v4, 3, v9
	s_mov_b32 s0, 0x3fffe0
	v_lshrrev_b32_e32 v5, 2, v3
	v_lshlrev_b32_e32 v6, 1, v3
	v_and_b32_e32 v2, 1, v2
	v_and_or_b32 v4, v3, s0, v4
	v_and_b32_e32 v5, 4, v5
	v_and_b32_e32 v6, 24, v6
	v_add_u16_e32 v1, v1, v2
	v_mov_b32_e32 v2, 1
	v_or3_b32 v4, v4, v5, v6
	v_lshlrev_b32_e32 v5, 5, v8
	v_ashrrev_i16_sdwa v1, v2, sext(v1) dst_sel:DWORD dst_unused:UNUSED_PAD src0_sel:DWORD src1_sel:BYTE_0
	v_and_b32_e32 v5, 32, v5
	v_bfe_i32 v10, v1, 0, 16
	v_add_lshl_u32 v1, v5, v10, 1
	v_lshl_add_u32 v144, v4, 10, v1
	v_lshl_add_u32 v146, v3, 12, v1
	v_ashrrev_i32_e32 v1, 31, v0
	v_lshrrev_b32_e32 v1, 22, v1
	v_add_u32_e32 v1, v0, v1
	v_ashrrev_i32_e32 v12, 10, v1
	v_mul_i32_i24_e32 v1, 0x400, v12
	v_sub_u32_e32 v0, v0, v1
	v_lshrrev_b32_e32 v1, 4, v0
	v_bitop3_b32 v0, v1, v0, 32 bitop3:0x6c
	v_ashrrev_i32_e32 v1, 31, v0
	v_lshrrev_b32_e32 v1, 26, v1
	v_add_u32_e32 v1, v0, v1
	v_lshlrev_b32_e32 v3, 3, v12
	v_ashrrev_i32_e32 v13, 6, v1
	v_and_b32_e32 v3, -16, v3
	v_add_u32_e32 v3, v13, v3
	v_and_b32_e32 v4, 3, v13
	s_ashr_i32 s19, s18, 31
	v_and_or_b32 v4, v3, s0, v4
	s_lshl_b64 s[0:1], s[18:19], 20
	s_add_u32 s3, s10, s0
	s_addc_u32 s4, s11, s1
	s_bfe_u32 s0, s20, 0x10007
	s_add_i32 s0, s20, s0
	s_bfe_i32 s0, s0, 0x80000
	s_sext_i32_i16 s0, s0
	s_lshr_b32 s0, s0, 1
	s_bfe_i64 s[0:1], s[0:1], 0x100000
	v_lshrrev_b32_e32 v5, 2, v3
	v_lshlrev_b32_e32 v6, 1, v3
	v_and_b32_e32 v1, 0xc0, v1
	s_lshl_b64 s[0:1], s[0:1], 10
	v_and_b32_e32 v5, 4, v5
	v_and_b32_e32 v6, 24, v6
	v_sub_u32_e32 v0, v0, v1
	s_add_u32 s22, s3, s0
	v_or3_b32 v4, v4, v5, v6
	v_lshlrev_b32_e32 v5, 5, v12
	v_ashrrev_i16_sdwa v0, v2, sext(v0) dst_sel:DWORD dst_unused:UNUSED_PAD src0_sel:DWORD src1_sel:BYTE_0
	s_addc_u32 s23, s4, s1
	s_ashr_i32 s21, s20, 31
	v_and_b32_e32 v5, 32, v5
	v_bfe_i32 v14, v0, 0, 16
	s_lshl_b64 s[0:1], s[20:21], 18
	v_add_lshl_u32 v0, v5, v14, 1
	s_add_u32 s24, s45, s0
	v_lshl_add_u32 v148, v4, 10, v0
	s_addc_u32 s25, s44, s1
	s_add_i32 m0, s94, 0x10000
	v_lshl_add_u32 v150, v3, 12, v0
	global_load_lds_dwordx4 v148, s[24:25]
	s_add_i32 m0, s94, 0x12000
	s_add_u32 s0, s24, 0x20000
	global_load_lds_dwordx4 v144, s[24:25]
	s_addc_u32 s1, s25, 0
	s_add_i32 m0, s94, 0x14000
	s_add_i32 s3, s94, 0x2000
	global_load_lds_dwordx4 v148, s[0:1]
	s_add_i32 m0, s94, 0x16000
	v_mov_b32_e32 v149, 0
	global_load_lds_dwordx4 v144, s[0:1]
	s_mov_b32 m0, s94
	s_add_u32 s0, s22, 0x80000
	global_load_lds_dwordx4 v150, s[22:23]
	s_mov_b32 m0, s3
	s_addc_u32 s1, s23, 0
	s_add_i32 s7, s94, 0x4000
	global_load_lds_dwordx4 v146, s[22:23]
	s_mov_b32 m0, s7
	s_add_i32 s19, s94, 0x6000
	global_load_lds_dwordx4 v150, s[0:1]
	s_mov_b32 m0, s19
	v_mov_b32_e32 v145, v149
	global_load_lds_dwordx4 v146, s[0:1]
	v_readlane_b32 s0, v254, 58
	v_mov_b32_e32 v151, v149
	v_mov_b32_e32 v147, v149
	v_readlane_b32 s1, v254, 59
	v_lshl_add_u64 v[6:7], s[24:25], 0, v[148:149]
	s_mov_b32 s21, 0
	v_lshl_add_u64 v[4:5], s[24:25], 0, v[144:145]
	v_lshl_add_u64 v[0:1], s[22:23], 0, v[150:151]
	s_and_b64 vcc, exec, s[0:1]
	v_lshl_add_u64 v[2:3], s[22:23], 0, v[146:147]
	s_cbranch_vccnz .LBB0_1687
	s_barrier
	s_setprio 1

.LBB0_1692:
	s_ashr_i32 s13, s12, 31
	s_lshl_b64 s[16:17], s[12:13], 18
	s_add_u32 s16, s45, s16
	s_addc_u32 s17, s44, s17
	s_and_b64 s[26:27], s[26:27], exec
	s_cselect_b32 s13, s17, s25
	s_cselect_b32 s15, s16, s24
	s_add_u32 s34, s24, 0x100
	s_addc_u32 s35, s25, 0
	s_add_u32 s22, s22, 0x80080
	s_addc_u32 s23, s23, 0
	s_mov_b32 s36, -2
	ds_read_b128 v[128:131], v169
	ds_read_b128 v[132:135], v169 offset:1024
	ds_read_b128 v[136:139], v169 offset:2048
	ds_read_b128 v[140:143], v169 offset:3072
	ds_read_b128 v[158:161], v170
	ds_read_b128 v[162:165], v170 offset:1024
	ds_read_b128 v[172:175], v170 offset:2048
	ds_read_b128 v[176:179], v170 offset:3072
	s_add_u32 s24, s22, 0xfff80080
	s_addc_u32 s25, s23, -1
	s_cmp_eq_u32 s36, 4
	s_cselect_b32 s27, s5, s25
	s_cselect_b32 s26, s4, s24
	s_cselect_b32 s25, s13, s35
	s_cselect_b32 s24, s15, s34
	s_add_i32 m0, s94, 0xc000
	ds_read_b128 v[180:183], v171
	ds_read_b128 v[184:187], v171 offset:1024
	ds_read_b128 v[188:191], v171 offset:2048
	ds_read_b128 v[192:195], v171 offset:3072
	ds_read_b128 v[196:199], v171 offset:4096
	ds_read_b128 v[200:203], v171 offset:5120
	ds_read_b128 v[204:207], v171 offset:6144
	ds_read_b128 v[208:211], v171 offset:7168
	global_load_lds_dwordx4 v152, s[22:23]
	s_add_i32 m0, s94, 0xe000
	s_nop 0
	global_load_lds_dwordx4 v154, s[22:23]
	s_waitcnt vmcnt(8)
	s_waitcnt lgkmcnt(0)
	s_barrier
	v_mfma_f32_16x16x32_bf16 v[80:83], v[128:131], v[180:183], 0
	v_mfma_f32_16x16x32_bf16 v[92:95], v[136:139], v[180:183], 0
	v_mfma_f32_16x16x32_bf16 v[84:87], v[128:131], v[188:191], 0
	v_mfma_f32_16x16x32_bf16 v[96:99], v[136:139], v[188:191], 0
	v_mfma_f32_16x16x32_bf16 v[88:91], v[128:131], v[196:199], 0
	v_mfma_f32_16x16x32_bf16 v[100:103], v[136:139], v[196:199], 0
	v_mfma_f32_16x16x32_bf16 v[72:75], v[128:131], v[204:207], 0
	v_mfma_f32_16x16x32_bf16 v[76:79], v[136:139], v[204:207], 0
	v_mfma_f32_16x16x32_bf16 v[80:83], v[132:135], v[184:187], v[80:83]
	v_mfma_f32_16x16x32_bf16 v[92:95], v[140:143], v[184:187], v[92:95]
	v_mfma_f32_16x16x32_bf16 v[84:87], v[132:135], v[192:195], v[84:87]
	v_mfma_f32_16x16x32_bf16 v[96:99], v[140:143], v[192:195], v[96:99]
	v_mfma_f32_16x16x32_bf16 v[88:91], v[132:135], v[200:203], v[88:91]
	v_mfma_f32_16x16x32_bf16 v[100:103], v[140:143], v[200:203], v[100:103]
	v_mfma_f32_16x16x32_bf16 v[72:75], v[132:135], v[208:211], v[72:75]
	v_mfma_f32_16x16x32_bf16 v[76:79], v[140:143], v[208:211], v[76:79]
	v_mfma_f32_16x16x32_bf16 v[104:107], v[158:161], v[180:183], 0
	v_mfma_f32_16x16x32_bf16 v[116:119], v[172:175], v[180:183], 0
	v_mfma_f32_16x16x32_bf16 v[108:111], v[158:161], v[188:191], 0
	v_mfma_f32_16x16x32_bf16 v[120:123], v[172:175], v[188:191], 0
	v_mfma_f32_16x16x32_bf16 v[112:115], v[158:161], v[196:199], 0
	v_mfma_f32_16x16x32_bf16 v[124:127], v[172:175], v[196:199], 0
	v_mfma_f32_16x16x32_bf16 v[68:71], v[158:161], v[204:207], 0
	v_mfma_f32_16x16x32_bf16 v[64:67], v[172:175], v[204:207], 0
	v_mfma_f32_16x16x32_bf16 v[104:107], v[162:165], v[184:187], v[104:107]
	v_mfma_f32_16x16x32_bf16 v[116:119], v[176:179], v[184:187], v[116:119]
	v_mfma_f32_16x16x32_bf16 v[108:111], v[162:165], v[192:195], v[108:111]
	v_mfma_f32_16x16x32_bf16 v[120:123], v[176:179], v[192:195], v[120:123]
	v_mfma_f32_16x16x32_bf16 v[112:115], v[162:165], v[200:203], v[112:115]
	v_mfma_f32_16x16x32_bf16 v[124:127], v[176:179], v[200:203], v[124:127]
	v_mfma_f32_16x16x32_bf16 v[68:71], v[162:165], v[208:211], v[68:71]
	v_mfma_f32_16x16x32_bf16 v[64:67], v[176:179], v[208:211], v[64:67]
	s_barrier
	s_add_i32 s37, s31, s97
	s_add_u32 s98, s24, 0x80
	s_addc_u32 s99, s25, 0
	s_mov_b32 m0, s37
	ds_read_b128 v[180:183], v171 offset:16384
	ds_read_b128 v[184:187], v171 offset:17408
	ds_read_b128 v[188:191], v171 offset:18432
	ds_read_b128 v[192:195], v171 offset:19456
	ds_read_b128 v[196:199], v171 offset:20480
	ds_read_b128 v[200:203], v171 offset:21504
	ds_read_b128 v[204:207], v171 offset:22528
	ds_read_b128 v[208:211], v171 offset:23552
	global_load_lds_dwordx4 v148, s[24:25]
	s_add_i32 m0, s37, 0x2000
	s_add_u32 s38, s24, 0x20000
	s_addc_u32 s39, s25, 0
	s_add_i32 s37, s33, s97
	global_load_lds_dwordx4 v144, s[24:25]
	s_mov_b32 m0, s37
	s_add_u32 s100, s26, 0x80
	s_addc_u32 s101, s27, 0
	global_load_lds_dwordx4 v148, s[38:39]
	s_add_i32 m0, s37, 0x2000
	s_nop 0
	global_load_lds_dwordx4 v144, s[38:39]
	s_mov_b32 m0, s94
	s_nop 0
	global_load_lds_dwordx4 v150, s[26:27]
	s_mov_b32 m0, s3
	s_nop 0
	global_load_lds_dwordx4 v146, s[26:27]
	s_waitcnt vmcnt(8)
	s_waitcnt lgkmcnt(0)
	s_barrier
	v_mfma_f32_16x16x32_bf16 v[48:51], v[128:131], v[180:183], 0
	v_mfma_f32_16x16x32_bf16 v[52:55], v[136:139], v[180:183], 0
	v_mfma_f32_16x16x32_bf16 v[32:35], v[128:131], v[188:191], 0
	v_mfma_f32_16x16x32_bf16 v[36:39], v[136:139], v[188:191], 0
	v_mfma_f32_16x16x32_bf16 v[16:19], v[128:131], v[196:199], 0
	v_mfma_f32_16x16x32_bf16 v[20:23], v[136:139], v[196:199], 0
	v_mfma_f32_16x16x32_bf16 v[0:3], v[128:131], v[204:207], 0
	v_mfma_f32_16x16x32_bf16 v[4:7], v[136:139], v[204:207], 0
	v_mfma_f32_16x16x32_bf16 v[48:51], v[132:135], v[184:187], v[48:51]
	v_mfma_f32_16x16x32_bf16 v[52:55], v[140:143], v[184:187], v[52:55]
	v_mfma_f32_16x16x32_bf16 v[32:35], v[132:135], v[192:195], v[32:35]
	v_mfma_f32_16x16x32_bf16 v[36:39], v[140:143], v[192:195], v[36:39]
	v_mfma_f32_16x16x32_bf16 v[16:19], v[132:135], v[200:203], v[16:19]
	v_mfma_f32_16x16x32_bf16 v[20:23], v[140:143], v[200:203], v[20:23]
	v_mfma_f32_16x16x32_bf16 v[0:3], v[132:135], v[208:211], v[0:3]
	v_mfma_f32_16x16x32_bf16 v[4:7], v[140:143], v[208:211], v[4:7]
	v_mfma_f32_16x16x32_bf16 v[56:59], v[158:161], v[180:183], 0
	v_mfma_f32_16x16x32_bf16 v[60:63], v[172:175], v[180:183], 0
	v_mfma_f32_16x16x32_bf16 v[40:43], v[158:161], v[188:191], 0
	v_mfma_f32_16x16x32_bf16 v[44:47], v[172:175], v[188:191], 0
	v_mfma_f32_16x16x32_bf16 v[24:27], v[158:161], v[196:199], 0
	v_mfma_f32_16x16x32_bf16 v[28:31], v[172:175], v[196:199], 0
	v_mfma_f32_16x16x32_bf16 v[8:11], v[158:161], v[204:207], 0
	v_mfma_f32_16x16x32_bf16 v[12:15], v[172:175], v[204:207], 0
	v_mfma_f32_16x16x32_bf16 v[56:59], v[162:165], v[184:187], v[56:59]
	v_mfma_f32_16x16x32_bf16 v[60:63], v[176:179], v[184:187], v[60:63]
	v_mfma_f32_16x16x32_bf16 v[40:43], v[162:165], v[192:195], v[40:43]
	v_mfma_f32_16x16x32_bf16 v[44:47], v[176:179], v[192:195], v[44:47]
	v_mfma_f32_16x16x32_bf16 v[24:27], v[162:165], v[200:203], v[24:27]
	v_mfma_f32_16x16x32_bf16 v[28:31], v[176:179], v[200:203], v[28:31]
	v_mfma_f32_16x16x32_bf16 v[8:11], v[162:165], v[208:211], v[8:11]
	v_mfma_f32_16x16x32_bf16 v[12:15], v[176:179], v[208:211], v[12:15]
	s_barrier
	s_add_i32 s37, 0, 0x18000
	s_add_i32 s38, 0, 0x1c000
	v_add_u32_e32 v140, s37, v167
	v_add_u32_e32 v176, s38, v167
	ds_read_b128 v[128:131], v140
	ds_read_b128 v[132:135], v140 offset:1024
	ds_read_b128 v[136:139], v140 offset:2048
	ds_read_b128 v[140:143], v140 offset:3072
	ds_read_b128 v[158:161], v176
	ds_read_b128 v[162:165], v176 offset:1024
	ds_read_b128 v[172:175], v176 offset:2048
	ds_read_b128 v[176:179], v176 offset:3072
	s_add_u32 s26, s26, 0x80000
	s_addc_u32 s27, s27, 0
	s_mov_b32 m0, s7
	ds_read_b128 v[180:183], v171 offset:32768
	ds_read_b128 v[184:187], v171 offset:33792
	ds_read_b128 v[188:191], v171 offset:34816
	ds_read_b128 v[192:195], v171 offset:35840
	ds_read_b128 v[196:199], v171 offset:36864
	ds_read_b128 v[200:203], v171 offset:37888
	ds_read_b128 v[204:207], v171 offset:38912
	ds_read_b128 v[208:211], v171 offset:39936
	global_load_lds_dwordx4 v150, s[26:27]
	s_mov_b32 m0, s19
	s_nop 0
	global_load_lds_dwordx4 v146, s[26:27]
	s_waitcnt vmcnt(8)
	s_waitcnt lgkmcnt(0)
	s_barrier
	v_mfma_f32_16x16x32_bf16 v[80:83], v[128:131], v[180:183], v[80:83]
	v_mfma_f32_16x16x32_bf16 v[92:95], v[136:139], v[180:183], v[92:95]
	v_mfma_f32_16x16x32_bf16 v[84:87], v[128:131], v[188:191], v[84:87]
	v_mfma_f32_16x16x32_bf16 v[96:99], v[136:139], v[188:191], v[96:99]
	v_mfma_f32_16x16x32_bf16 v[88:91], v[128:131], v[196:199], v[88:91]
	v_mfma_f32_16x16x32_bf16 v[100:103], v[136:139], v[196:199], v[100:103]
	v_mfma_f32_16x16x32_bf16 v[72:75], v[128:131], v[204:207], v[72:75]
	v_mfma_f32_16x16x32_bf16 v[76:79], v[136:139], v[204:207], v[76:79]
	v_mfma_f32_16x16x32_bf16 v[80:83], v[132:135], v[184:187], v[80:83]
	v_mfma_f32_16x16x32_bf16 v[92:95], v[140:143], v[184:187], v[92:95]
	v_mfma_f32_16x16x32_bf16 v[84:87], v[132:135], v[192:195], v[84:87]
	v_mfma_f32_16x16x32_bf16 v[96:99], v[140:143], v[192:195], v[96:99]
	v_mfma_f32_16x16x32_bf16 v[88:91], v[132:135], v[200:203], v[88:91]
	v_mfma_f32_16x16x32_bf16 v[100:103], v[140:143], v[200:203], v[100:103]
	v_mfma_f32_16x16x32_bf16 v[72:75], v[132:135], v[208:211], v[72:75]
	v_mfma_f32_16x16x32_bf16 v[76:79], v[140:143], v[208:211], v[76:79]
	v_mfma_f32_16x16x32_bf16 v[104:107], v[158:161], v[180:183], v[104:107]
	v_mfma_f32_16x16x32_bf16 v[116:119], v[172:175], v[180:183], v[116:119]
	v_mfma_f32_16x16x32_bf16 v[108:111], v[158:161], v[188:191], v[108:111]
	v_mfma_f32_16x16x32_bf16 v[120:123], v[172:175], v[188:191], v[120:123]
	v_mfma_f32_16x16x32_bf16 v[112:115], v[158:161], v[196:199], v[112:115]
	v_mfma_f32_16x16x32_bf16 v[124:127], v[172:175], v[196:199], v[124:127]
	v_mfma_f32_16x16x32_bf16 v[68:71], v[158:161], v[204:207], v[68:71]
	v_mfma_f32_16x16x32_bf16 v[64:67], v[172:175], v[204:207], v[64:67]
	v_mfma_f32_16x16x32_bf16 v[104:107], v[162:165], v[184:187], v[104:107]
	v_mfma_f32_16x16x32_bf16 v[116:119], v[176:179], v[184:187], v[116:119]
	v_mfma_f32_16x16x32_bf16 v[108:111], v[162:165], v[192:195], v[108:111]
	v_mfma_f32_16x16x32_bf16 v[120:123], v[176:179], v[192:195], v[120:123]
	v_mfma_f32_16x16x32_bf16 v[112:115], v[162:165], v[200:203], v[112:115]
	v_mfma_f32_16x16x32_bf16 v[124:127], v[176:179], v[200:203], v[124:127]
	v_mfma_f32_16x16x32_bf16 v[68:71], v[162:165], v[208:211], v[68:71]
	v_mfma_f32_16x16x32_bf16 v[64:67], v[176:179], v[208:211], v[64:67]
	s_barrier
	s_add_i32 s26, s37, s97
	s_mov_b32 m0, s26
	ds_read_b128 v[180:183], v171 offset:49152
	ds_read_b128 v[184:187], v171 offset:50176
	ds_read_b128 v[188:191], v171 offset:51200
	ds_read_b128 v[192:195], v171 offset:52224
	ds_read_b128 v[196:199], v171 offset:53248
	ds_read_b128 v[200:203], v171 offset:54272
	ds_read_b128 v[204:207], v171 offset:55296
	ds_read_b128 v[208:211], v171 offset:56320
	global_load_lds_dwordx4 v148, s[98:99]
	s_add_i32 m0, s26, 0x2000
	s_add_u32 s24, s24, 0x20080
	s_addc_u32 s25, s25, 0
	s_add_i32 s26, s38, s97
	global_load_lds_dwordx4 v144, s[98:99]
	s_mov_b32 m0, s26
	s_nop 0
	global_load_lds_dwordx4 v148, s[24:25]
	s_add_i32 m0, s26, 0x2000
	s_nop 0
	global_load_lds_dwordx4 v144, s[24:25]
	s_mov_b32 m0, s28
	s_nop 0
	global_load_lds_dwordx4 v150, s[100:101]
	s_mov_b32 m0, s29
	s_nop 0
	global_load_lds_dwordx4 v146, s[100:101]
	s_waitcnt vmcnt(8)
	s_waitcnt lgkmcnt(0)
	s_barrier
	v_mfma_f32_16x16x32_bf16 v[48:51], v[128:131], v[180:183], v[48:51]
	v_mfma_f32_16x16x32_bf16 v[52:55], v[136:139], v[180:183], v[52:55]
	v_mfma_f32_16x16x32_bf16 v[32:35], v[128:131], v[188:191], v[32:35]
	v_mfma_f32_16x16x32_bf16 v[36:39], v[136:139], v[188:191], v[36:39]
	v_mfma_f32_16x16x32_bf16 v[16:19], v[128:131], v[196:199], v[16:19]
	v_mfma_f32_16x16x32_bf16 v[20:23], v[136:139], v[196:199], v[20:23]
	v_mfma_f32_16x16x32_bf16 v[0:3], v[128:131], v[204:207], v[0:3]
	v_mfma_f32_16x16x32_bf16 v[4:7], v[136:139], v[204:207], v[4:7]
	v_mfma_f32_16x16x32_bf16 v[48:51], v[132:135], v[184:187], v[48:51]
	v_mfma_f32_16x16x32_bf16 v[52:55], v[140:143], v[184:187], v[52:55]
	v_mfma_f32_16x16x32_bf16 v[32:35], v[132:135], v[192:195], v[32:35]
	v_mfma_f32_16x16x32_bf16 v[36:39], v[140:143], v[192:195], v[36:39]
	v_mfma_f32_16x16x32_bf16 v[16:19], v[132:135], v[200:203], v[16:19]
	v_mfma_f32_16x16x32_bf16 v[20:23], v[140:143], v[200:203], v[20:23]
	v_mfma_f32_16x16x32_bf16 v[0:3], v[132:135], v[208:211], v[0:3]
	v_mfma_f32_16x16x32_bf16 v[4:7], v[140:143], v[208:211], v[4:7]
	v_mfma_f32_16x16x32_bf16 v[56:59], v[158:161], v[180:183], v[56:59]
	v_mfma_f32_16x16x32_bf16 v[60:63], v[172:175], v[180:183], v[60:63]
	v_mfma_f32_16x16x32_bf16 v[40:43], v[158:161], v[188:191], v[40:43]
	v_mfma_f32_16x16x32_bf16 v[44:47], v[172:175], v[188:191], v[44:47]
	v_mfma_f32_16x16x32_bf16 v[24:27], v[158:161], v[196:199], v[24:27]
	v_mfma_f32_16x16x32_bf16 v[28:31], v[172:175], v[196:199], v[28:31]
	v_mfma_f32_16x16x32_bf16 v[8:11], v[158:161], v[204:207], v[8:11]
	v_mfma_f32_16x16x32_bf16 v[12:15], v[172:175], v[204:207], v[12:15]
	v_mfma_f32_16x16x32_bf16 v[56:59], v[162:165], v[184:187], v[56:59]
	v_mfma_f32_16x16x32_bf16 v[60:63], v[176:179], v[184:187], v[60:63]
	v_mfma_f32_16x16x32_bf16 v[40:43], v[162:165], v[192:195], v[40:43]
	v_mfma_f32_16x16x32_bf16 v[44:47], v[176:179], v[192:195], v[44:47]
	v_mfma_f32_16x16x32_bf16 v[24:27], v[162:165], v[200:203], v[24:27]
	v_mfma_f32_16x16x32_bf16 v[28:31], v[176:179], v[200:203], v[28:31]
	v_mfma_f32_16x16x32_bf16 v[8:11], v[162:165], v[208:211], v[8:11]
	v_mfma_f32_16x16x32_bf16 v[12:15], v[176:179], v[208:211], v[12:15]
	s_barrier
	s_add_i32 s36, s36, 2
	s_add_u32 s34, s34, 0x100
	s_addc_u32 s35, s35, 0
	s_add_u32 s22, s22, 0x100
	s_addc_u32 s23, s23, 0
	s_cmp_gt_u32 s36, 5
	s_cbranch_scc1 .Lpeel_done_1
.LBB0_1693:
	ds_read_b128 v[128:131], v169
	ds_read_b128 v[132:135], v169 offset:1024
	ds_read_b128 v[136:139], v169 offset:2048
	ds_read_b128 v[140:143], v169 offset:3072
	ds_read_b128 v[158:161], v170
	ds_read_b128 v[162:165], v170 offset:1024
	ds_read_b128 v[172:175], v170 offset:2048
	ds_read_b128 v[176:179], v170 offset:3072
	s_add_u32 s24, s22, 0xfff80080
	s_addc_u32 s25, s23, -1
	s_cmp_eq_u32 s36, 4
	s_cselect_b32 s27, s5, s25
	s_cselect_b32 s26, s4, s24
	s_cselect_b32 s25, s13, s35
	s_cselect_b32 s24, s15, s34
	s_add_i32 m0, s94, 0xc000
	ds_read_b128 v[180:183], v171
	ds_read_b128 v[184:187], v171 offset:1024
	ds_read_b128 v[188:191], v171 offset:2048
	ds_read_b128 v[192:195], v171 offset:3072
	ds_read_b128 v[196:199], v171 offset:4096
	ds_read_b128 v[200:203], v171 offset:5120
	ds_read_b128 v[204:207], v171 offset:6144
	ds_read_b128 v[208:211], v171 offset:7168
	global_load_lds_dwordx4 v152, s[22:23]
	s_add_i32 m0, s94, 0xe000
	s_nop 0
	global_load_lds_dwordx4 v154, s[22:23]
	s_waitcnt vmcnt(8)
	s_waitcnt lgkmcnt(0)
	s_barrier
	v_mfma_f32_16x16x32_bf16 v[80:83], v[128:131], v[180:183], v[80:83]
	v_mfma_f32_16x16x32_bf16 v[92:95], v[136:139], v[180:183], v[92:95]
	v_mfma_f32_16x16x32_bf16 v[84:87], v[128:131], v[188:191], v[84:87]
	v_mfma_f32_16x16x32_bf16 v[96:99], v[136:139], v[188:191], v[96:99]
	v_mfma_f32_16x16x32_bf16 v[88:91], v[128:131], v[196:199], v[88:91]
	v_mfma_f32_16x16x32_bf16 v[100:103], v[136:139], v[196:199], v[100:103]
	v_mfma_f32_16x16x32_bf16 v[72:75], v[128:131], v[204:207], v[72:75]
	v_mfma_f32_16x16x32_bf16 v[76:79], v[136:139], v[204:207], v[76:79]
	v_mfma_f32_16x16x32_bf16 v[80:83], v[132:135], v[184:187], v[80:83]
	v_mfma_f32_16x16x32_bf16 v[92:95], v[140:143], v[184:187], v[92:95]
	v_mfma_f32_16x16x32_bf16 v[84:87], v[132:135], v[192:195], v[84:87]
	v_mfma_f32_16x16x32_bf16 v[96:99], v[140:143], v[192:195], v[96:99]
	v_mfma_f32_16x16x32_bf16 v[88:91], v[132:135], v[200:203], v[88:91]
	v_mfma_f32_16x16x32_bf16 v[100:103], v[140:143], v[200:203], v[100:103]
	v_mfma_f32_16x16x32_bf16 v[72:75], v[132:135], v[208:211], v[72:75]
	v_mfma_f32_16x16x32_bf16 v[76:79], v[140:143], v[208:211], v[76:79]
	v_mfma_f32_16x16x32_bf16 v[104:107], v[158:161], v[180:183], v[104:107]
	v_mfma_f32_16x16x32_bf16 v[116:119], v[172:175], v[180:183], v[116:119]
	v_mfma_f32_16x16x32_bf16 v[108:111], v[158:161], v[188:191], v[108:111]
	v_mfma_f32_16x16x32_bf16 v[120:123], v[172:175], v[188:191], v[120:123]
	v_mfma_f32_16x16x32_bf16 v[112:115], v[158:161], v[196:199], v[112:115]
	v_mfma_f32_16x16x32_bf16 v[124:127], v[172:175], v[196:199], v[124:127]
	v_mfma_f32_16x16x32_bf16 v[68:71], v[158:161], v[204:207], v[68:71]
	v_mfma_f32_16x16x32_bf16 v[64:67], v[172:175], v[204:207], v[64:67]
	v_mfma_f32_16x16x32_bf16 v[104:107], v[162:165], v[184:187], v[104:107]
	v_mfma_f32_16x16x32_bf16 v[116:119], v[176:179], v[184:187], v[116:119]
	v_mfma_f32_16x16x32_bf16 v[108:111], v[162:165], v[192:195], v[108:111]
	v_mfma_f32_16x16x32_bf16 v[120:123], v[176:179], v[192:195], v[120:123]
	v_mfma_f32_16x16x32_bf16 v[112:115], v[162:165], v[200:203], v[112:115]
	v_mfma_f32_16x16x32_bf16 v[124:127], v[176:179], v[200:203], v[124:127]
	v_mfma_f32_16x16x32_bf16 v[68:71], v[162:165], v[208:211], v[68:71]
	v_mfma_f32_16x16x32_bf16 v[64:67], v[176:179], v[208:211], v[64:67]
	s_barrier
	s_add_i32 s37, s31, s97
	s_add_u32 s98, s24, 0x80
	s_addc_u32 s99, s25, 0
	s_mov_b32 m0, s37
	ds_read_b128 v[180:183], v171 offset:16384
	ds_read_b128 v[184:187], v171 offset:17408
	ds_read_b128 v[188:191], v171 offset:18432
	ds_read_b128 v[192:195], v171 offset:19456
	ds_read_b128 v[196:199], v171 offset:20480
	ds_read_b128 v[200:203], v171 offset:21504
	ds_read_b128 v[204:207], v171 offset:22528
	ds_read_b128 v[208:211], v171 offset:23552
	global_load_lds_dwordx4 v148, s[24:25]
	s_add_i32 m0, s37, 0x2000
	s_add_u32 s38, s24, 0x20000
	s_addc_u32 s39, s25, 0
	s_add_i32 s37, s33, s97
	global_load_lds_dwordx4 v144, s[24:25]
	s_mov_b32 m0, s37
	s_add_u32 s100, s26, 0x80
	s_addc_u32 s101, s27, 0
	global_load_lds_dwordx4 v148, s[38:39]
	s_add_i32 m0, s37, 0x2000
	s_nop 0
	global_load_lds_dwordx4 v144, s[38:39]
	s_mov_b32 m0, s94
	s_nop 0
	global_load_lds_dwordx4 v150, s[26:27]
	s_mov_b32 m0, s3
	s_nop 0
	global_load_lds_dwordx4 v146, s[26:27]
	s_waitcnt vmcnt(8)
	s_waitcnt lgkmcnt(0)
	s_barrier
	v_mfma_f32_16x16x32_bf16 v[48:51], v[128:131], v[180:183], v[48:51]
	v_mfma_f32_16x16x32_bf16 v[52:55], v[136:139], v[180:183], v[52:55]
	v_mfma_f32_16x16x32_bf16 v[32:35], v[128:131], v[188:191], v[32:35]
	v_mfma_f32_16x16x32_bf16 v[36:39], v[136:139], v[188:191], v[36:39]
	v_mfma_f32_16x16x32_bf16 v[16:19], v[128:131], v[196:199], v[16:19]
	v_mfma_f32_16x16x32_bf16 v[20:23], v[136:139], v[196:199], v[20:23]
	v_mfma_f32_16x16x32_bf16 v[0:3], v[128:131], v[204:207], v[0:3]
	v_mfma_f32_16x16x32_bf16 v[4:7], v[136:139], v[204:207], v[4:7]
	v_mfma_f32_16x16x32_bf16 v[48:51], v[132:135], v[184:187], v[48:51]
	v_mfma_f32_16x16x32_bf16 v[52:55], v[140:143], v[184:187], v[52:55]
	v_mfma_f32_16x16x32_bf16 v[32:35], v[132:135], v[192:195], v[32:35]
	v_mfma_f32_16x16x32_bf16 v[36:39], v[140:143], v[192:195], v[36:39]
	v_mfma_f32_16x16x32_bf16 v[16:19], v[132:135], v[200:203], v[16:19]
	v_mfma_f32_16x16x32_bf16 v[20:23], v[140:143], v[200:203], v[20:23]
	v_mfma_f32_16x16x32_bf16 v[0:3], v[132:135], v[208:211], v[0:3]
	v_mfma_f32_16x16x32_bf16 v[4:7], v[140:143], v[208:211], v[4:7]
	v_mfma_f32_16x16x32_bf16 v[56:59], v[158:161], v[180:183], v[56:59]
	v_mfma_f32_16x16x32_bf16 v[60:63], v[172:175], v[180:183], v[60:63]
	v_mfma_f32_16x16x32_bf16 v[40:43], v[158:161], v[188:191], v[40:43]
	v_mfma_f32_16x16x32_bf16 v[44:47], v[172:175], v[188:191], v[44:47]
	v_mfma_f32_16x16x32_bf16 v[24:27], v[158:161], v[196:199], v[24:27]
	v_mfma_f32_16x16x32_bf16 v[28:31], v[172:175], v[196:199], v[28:31]
	v_mfma_f32_16x16x32_bf16 v[8:11], v[158:161], v[204:207], v[8:11]
	v_mfma_f32_16x16x32_bf16 v[12:15], v[172:175], v[204:207], v[12:15]
	v_mfma_f32_16x16x32_bf16 v[56:59], v[162:165], v[184:187], v[56:59]
	v_mfma_f32_16x16x32_bf16 v[60:63], v[176:179], v[184:187], v[60:63]
	v_mfma_f32_16x16x32_bf16 v[40:43], v[162:165], v[192:195], v[40:43]
	v_mfma_f32_16x16x32_bf16 v[44:47], v[176:179], v[192:195], v[44:47]
	v_mfma_f32_16x16x32_bf16 v[24:27], v[162:165], v[200:203], v[24:27]
	v_mfma_f32_16x16x32_bf16 v[28:31], v[176:179], v[200:203], v[28:31]
	v_mfma_f32_16x16x32_bf16 v[8:11], v[162:165], v[208:211], v[8:11]
	v_mfma_f32_16x16x32_bf16 v[12:15], v[176:179], v[208:211], v[12:15]
	s_barrier
	s_add_i32 s37, 0, 0x18000
	s_add_i32 s38, 0, 0x1c000
	v_add_u32_e32 v140, s37, v167
	v_add_u32_e32 v176, s38, v167
	ds_read_b128 v[128:131], v140
	ds_read_b128 v[132:135], v140 offset:1024
	ds_read_b128 v[136:139], v140 offset:2048
	ds_read_b128 v[140:143], v140 offset:3072
	ds_read_b128 v[158:161], v176
	ds_read_b128 v[162:165], v176 offset:1024
	ds_read_b128 v[172:175], v176 offset:2048
	ds_read_b128 v[176:179], v176 offset:3072
	s_add_u32 s26, s26, 0x80000
	s_addc_u32 s27, s27, 0
	s_mov_b32 m0, s7
	ds_read_b128 v[180:183], v171 offset:32768
	ds_read_b128 v[184:187], v171 offset:33792
	ds_read_b128 v[188:191], v171 offset:34816
	ds_read_b128 v[192:195], v171 offset:35840
	ds_read_b128 v[196:199], v171 offset:36864
	ds_read_b128 v[200:203], v171 offset:37888
	ds_read_b128 v[204:207], v171 offset:38912
	ds_read_b128 v[208:211], v171 offset:39936
	global_load_lds_dwordx4 v150, s[26:27]
	s_mov_b32 m0, s19
	s_nop 0
	global_load_lds_dwordx4 v146, s[26:27]
	s_waitcnt vmcnt(8)
	s_waitcnt lgkmcnt(0)
	s_barrier
	v_mfma_f32_16x16x32_bf16 v[80:83], v[128:131], v[180:183], v[80:83]
	v_mfma_f32_16x16x32_bf16 v[92:95], v[136:139], v[180:183], v[92:95]
	v_mfma_f32_16x16x32_bf16 v[84:87], v[128:131], v[188:191], v[84:87]
	v_mfma_f32_16x16x32_bf16 v[96:99], v[136:139], v[188:191], v[96:99]
	v_mfma_f32_16x16x32_bf16 v[88:91], v[128:131], v[196:199], v[88:91]
	v_mfma_f32_16x16x32_bf16 v[100:103], v[136:139], v[196:199], v[100:103]
	v_mfma_f32_16x16x32_bf16 v[72:75], v[128:131], v[204:207], v[72:75]
	v_mfma_f32_16x16x32_bf16 v[76:79], v[136:139], v[204:207], v[76:79]
	v_mfma_f32_16x16x32_bf16 v[80:83], v[132:135], v[184:187], v[80:83]
	v_mfma_f32_16x16x32_bf16 v[92:95], v[140:143], v[184:187], v[92:95]
	v_mfma_f32_16x16x32_bf16 v[84:87], v[132:135], v[192:195], v[84:87]
	v_mfma_f32_16x16x32_bf16 v[96:99], v[140:143], v[192:195], v[96:99]
	v_mfma_f32_16x16x32_bf16 v[88:91], v[132:135], v[200:203], v[88:91]
	v_mfma_f32_16x16x32_bf16 v[100:103], v[140:143], v[200:203], v[100:103]
	v_mfma_f32_16x16x32_bf16 v[72:75], v[132:135], v[208:211], v[72:75]
	v_mfma_f32_16x16x32_bf16 v[76:79], v[140:143], v[208:211], v[76:79]
	v_mfma_f32_16x16x32_bf16 v[104:107], v[158:161], v[180:183], v[104:107]
	v_mfma_f32_16x16x32_bf16 v[116:119], v[172:175], v[180:183], v[116:119]
	v_mfma_f32_16x16x32_bf16 v[108:111], v[158:161], v[188:191], v[108:111]
	v_mfma_f32_16x16x32_bf16 v[120:123], v[172:175], v[188:191], v[120:123]
	v_mfma_f32_16x16x32_bf16 v[112:115], v[158:161], v[196:199], v[112:115]
	v_mfma_f32_16x16x32_bf16 v[124:127], v[172:175], v[196:199], v[124:127]
	v_mfma_f32_16x16x32_bf16 v[68:71], v[158:161], v[204:207], v[68:71]
	v_mfma_f32_16x16x32_bf16 v[64:67], v[172:175], v[204:207], v[64:67]
	v_mfma_f32_16x16x32_bf16 v[104:107], v[162:165], v[184:187], v[104:107]
	v_mfma_f32_16x16x32_bf16 v[116:119], v[176:179], v[184:187], v[116:119]
	v_mfma_f32_16x16x32_bf16 v[108:111], v[162:165], v[192:195], v[108:111]
	v_mfma_f32_16x16x32_bf16 v[120:123], v[176:179], v[192:195], v[120:123]
	v_mfma_f32_16x16x32_bf16 v[112:115], v[162:165], v[200:203], v[112:115]
	v_mfma_f32_16x16x32_bf16 v[124:127], v[176:179], v[200:203], v[124:127]
	v_mfma_f32_16x16x32_bf16 v[68:71], v[162:165], v[208:211], v[68:71]
	v_mfma_f32_16x16x32_bf16 v[64:67], v[176:179], v[208:211], v[64:67]
	s_barrier
	s_add_i32 s26, s37, s97
	s_mov_b32 m0, s26
	ds_read_b128 v[180:183], v171 offset:49152
	ds_read_b128 v[184:187], v171 offset:50176
	ds_read_b128 v[188:191], v171 offset:51200
	ds_read_b128 v[192:195], v171 offset:52224
	ds_read_b128 v[196:199], v171 offset:53248
	ds_read_b128 v[200:203], v171 offset:54272
	ds_read_b128 v[204:207], v171 offset:55296
	ds_read_b128 v[208:211], v171 offset:56320
	global_load_lds_dwordx4 v148, s[98:99]
	s_add_i32 m0, s26, 0x2000
	s_add_u32 s24, s24, 0x20080
	s_addc_u32 s25, s25, 0
	s_add_i32 s26, s38, s97
	global_load_lds_dwordx4 v144, s[98:99]
	s_mov_b32 m0, s26
	s_nop 0
	global_load_lds_dwordx4 v148, s[24:25]
	s_add_i32 m0, s26, 0x2000
	s_nop 0
	global_load_lds_dwordx4 v144, s[24:25]
	s_mov_b32 m0, s28
	s_nop 0
	global_load_lds_dwordx4 v150, s[100:101]
	s_mov_b32 m0, s29
	s_nop 0
	global_load_lds_dwordx4 v146, s[100:101]
	s_waitcnt vmcnt(8)
	s_waitcnt lgkmcnt(0)
	s_barrier
	v_mfma_f32_16x16x32_bf16 v[48:51], v[128:131], v[180:183], v[48:51]
	v_mfma_f32_16x16x32_bf16 v[52:55], v[136:139], v[180:183], v[52:55]
	v_mfma_f32_16x16x32_bf16 v[32:35], v[128:131], v[188:191], v[32:35]
	v_mfma_f32_16x16x32_bf16 v[36:39], v[136:139], v[188:191], v[36:39]
	v_mfma_f32_16x16x32_bf16 v[16:19], v[128:131], v[196:199], v[16:19]
	v_mfma_f32_16x16x32_bf16 v[20:23], v[136:139], v[196:199], v[20:23]
	v_mfma_f32_16x16x32_bf16 v[0:3], v[128:131], v[204:207], v[0:3]
	v_mfma_f32_16x16x32_bf16 v[4:7], v[136:139], v[204:207], v[4:7]
	v_mfma_f32_16x16x32_bf16 v[48:51], v[132:135], v[184:187], v[48:51]
	v_mfma_f32_16x16x32_bf16 v[52:55], v[140:143], v[184:187], v[52:55]
	v_mfma_f32_16x16x32_bf16 v[32:35], v[132:135], v[192:195], v[32:35]
	v_mfma_f32_16x16x32_bf16 v[36:39], v[140:143], v[192:195], v[36:39]
	v_mfma_f32_16x16x32_bf16 v[16:19], v[132:135], v[200:203], v[16:19]
	v_mfma_f32_16x16x32_bf16 v[20:23], v[140:143], v[200:203], v[20:23]
	v_mfma_f32_16x16x32_bf16 v[0:3], v[132:135], v[208:211], v[0:3]
	v_mfma_f32_16x16x32_bf16 v[4:7], v[140:143], v[208:211], v[4:7]
	v_mfma_f32_16x16x32_bf16 v[56:59], v[158:161], v[180:183], v[56:59]
	v_mfma_f32_16x16x32_bf16 v[60:63], v[172:175], v[180:183], v[60:63]
	v_mfma_f32_16x16x32_bf16 v[40:43], v[158:161], v[188:191], v[40:43]
	v_mfma_f32_16x16x32_bf16 v[44:47], v[172:175], v[188:191], v[44:47]
	v_mfma_f32_16x16x32_bf16 v[24:27], v[158:161], v[196:199], v[24:27]
	v_mfma_f32_16x16x32_bf16 v[28:31], v[172:175], v[196:199], v[28:31]
	v_mfma_f32_16x16x32_bf16 v[8:11], v[158:161], v[204:207], v[8:11]
	v_mfma_f32_16x16x32_bf16 v[12:15], v[172:175], v[204:207], v[12:15]
	v_mfma_f32_16x16x32_bf16 v[56:59], v[162:165], v[184:187], v[56:59]
	v_mfma_f32_16x16x32_bf16 v[60:63], v[176:179], v[184:187], v[60:63]
	v_mfma_f32_16x16x32_bf16 v[40:43], v[162:165], v[192:195], v[40:43]
	v_mfma_f32_16x16x32_bf16 v[44:47], v[176:179], v[192:195], v[44:47]
	v_mfma_f32_16x16x32_bf16 v[24:27], v[162:165], v[200:203], v[24:27]
	v_mfma_f32_16x16x32_bf16 v[28:31], v[176:179], v[200:203], v[28:31]
	v_mfma_f32_16x16x32_bf16 v[8:11], v[162:165], v[208:211], v[8:11]
	v_mfma_f32_16x16x32_bf16 v[12:15], v[176:179], v[208:211], v[12:15]
	s_barrier
	s_add_i32 s36, s36, 2
	s_add_u32 s34, s34, 0x100
	s_addc_u32 s35, s35, 0
	s_add_u32 s22, s22, 0x100
	s_addc_u32 s23, s23, 0
	s_cmp_gt_u32 s36, 5
	s_cbranch_scc0 .LBB0_1693

.LBB0_1699:
	s_setprio 0
	s_waitcnt vmcnt(0)
	s_barrier

.LBB0_2001:
	s_add_u32 s52, s74, 0x48000
	s_addc_u32 s53, s75, 0
	s_waitcnt lgkmcnt(0)
	s_add_u32 s50, s26, 0xf8000000
	s_addc_u32 s51, s27, -1
	s_and_b64 s[2:3], s[60:61], exec
	s_cselect_b32 s58, 3, 0
	s_add_u32 s26, s74, 0x29f00000
	s_addc_u32 s27, s75, 0
	v_ashrrev_i32_e32 v0, 1, v239
	s_add_u32 s34, s74, 0x20000
	v_and_b32_e32 v240, 15, v239
	v_and_b32_e32 v241, -8, v0
	s_addc_u32 s35, s75, 0
	s_andn2_b64 vcc, exec, s[10:11]
	s_mov_b32 s29, 0
	s_cbranch_vccnz .LBB0_2051
	v_lshl_add_u32 v0, v239, 4, s97
	v_ashrrev_i32_e32 v1, 31, v0
	v_lshrrev_b32_e32 v1, 22, v1
	v_add_u32_e32 v1, v0, v1
	v_ashrrev_i32_e32 v8, 10, v1
	v_mul_i32_i24_e32 v1, 0x400, v8
	v_sub_u32_e32 v1, v0, v1
	v_lshrrev_b32_e32 v2, 4, v1
	v_bitop3_b32 v1, v2, v1, 32 bitop3:0x6c
	v_ashrrev_i32_e32 v3, 31, v1
	v_lshrrev_b32_e32 v3, 26, v3
	v_add_u32_e32 v3, v1, v3
	v_lshlrev_b32_e32 v2, 3, v8
	v_ashrrev_i32_e32 v9, 6, v3
	v_and_b32_e32 v3, 0xc0, v3
	v_and_b32_e32 v2, -16, v2
	v_sub_u32_e32 v1, v1, v3
	v_mov_b32_e32 v3, 1
	v_add_u32_e32 v2, v9, v2
	v_ashrrev_i16_sdwa v1, v3, sext(v1) dst_sel:DWORD dst_unused:UNUSED_PAD src0_sel:DWORD src1_sel:BYTE_0
	v_lshlrev_b32_e32 v4, 5, v8
	v_bfe_i32 v10, v1, 0, 16
	v_lshlrev_b32_e32 v1, 1, v2
	v_lshrrev_b32_e32 v5, 2, v2
	v_and_b32_e32 v6, 3, v9
	s_mov_b32 s2, 0x7ffe0
	v_and_b32_e32 v4, 32, v4
	v_and_b32_e32 v1, 24, v1
	v_and_b32_e32 v5, 4, v5
	v_and_or_b32 v6, v2, s2, v6
	v_or3_b32 v1, v6, v5, v1
	v_add_lshl_u32 v4, v4, v10, 1
	v_add_u32_e32 v0, 0x2000, v0
	v_lshl_add_u32 v210, v1, 13, v4
	v_ashrrev_i32_e32 v1, 31, v0
	v_lshrrev_b32_e32 v1, 22, v1
	v_add_u32_e32 v1, v0, v1
	v_ashrrev_i32_e32 v11, 10, v1
	v_mul_i32_i24_e32 v1, 0x400, v11
	v_sub_u32_e32 v0, v0, v1
	v_lshrrev_b32_e32 v1, 4, v0
	v_bitop3_b32 v0, v1, v0, 32 bitop3:0x6c
	v_lshl_add_u32 v208, v2, 13, v4
	v_ashrrev_i32_e32 v2, 31, v0
	v_lshrrev_b32_e32 v2, 26, v2
	v_add_u32_e32 v2, v0, v2
	v_ashrrev_i32_e32 v12, 6, v2
	v_and_b32_e32 v2, 0xffc0, v2
	v_sub_u32_e32 v0, v0, v2
	v_lshrrev_b16_e32 v2, 7, v0
	v_lshlrev_b32_e32 v1, 3, v11
	v_and_b32_e32 v2, 1, v2
	v_and_b32_e32 v1, -16, v1
	v_add_u16_e32 v0, v0, v2
	v_add_u32_e32 v1, v12, v1
	v_ashrrev_i16_sdwa v0, v3, sext(v0) dst_sel:DWORD dst_unused:UNUSED_PAD src0_sel:DWORD src1_sel:BYTE_0
	v_and_b32_e32 v3, 3, v12
	s_ashr_i32 s5, s4, 31
	v_and_or_b32 v3, v1, s2, v3
	s_lshl_b64 s[2:3], s[4:5], 21
	s_add_u32 s5, s86, s2
	s_addc_u32 s10, s87, s3
	s_ashr_i32 s43, s42, 31
	s_lshl_b64 s[2:3], s[42:43], 21
	v_readlane_b32 s16, v254, 13
	v_readlane_b32 s17, v254, 14
	s_add_u32 s2, s16, s2
	s_addc_u32 s3, s17, s3
	v_lshlrev_b32_e32 v4, 5, v11
	v_bfe_i32 v13, v0, 0, 16
	v_lshlrev_b32_e32 v0, 1, v1
	v_lshrrev_b32_e32 v2, 2, v1
	s_add_u32 s44, s2, s8
	v_and_b32_e32 v4, 32, v4
	v_and_b32_e32 v0, 24, v0
	v_and_b32_e32 v2, 4, v2
	s_addc_u32 s45, s3, s9
	s_add_i32 m0, s94, 0x10000
	v_or3_b32 v0, v3, v2, v0
	v_add_lshl_u32 v2, v4, v13, 1
	global_load_lds_dwordx4 v210, s[44:45]
	s_add_i32 m0, s94, 0x12000
	v_lshl_add_u32 v214, v0, 13, v2
	s_add_u32 s2, s44, 0x100000
	global_load_lds_dwordx4 v214, s[44:45]
	s_addc_u32 s3, s45, 0
	s_add_i32 m0, s94, 0x14000
	v_lshl_add_u32 v212, v1, 13, v2
	global_load_lds_dwordx4 v210, s[2:3]
	s_add_i32 m0, s94, 0x16000
	s_add_u32 s46, s5, s8
	global_load_lds_dwordx4 v214, s[2:3]
	s_addc_u32 s47, s10, s9
	s_add_i32 s2, s94, 0x2000
	s_mov_b32 m0, s94
	s_add_u32 s8, s46, 0x100000
	global_load_lds_dwordx4 v208, s[46:47]
	s_mov_b32 m0, s2
	s_addc_u32 s9, s47, 0
	s_add_i32 s3, s94, 0x4000
	global_load_lds_dwordx4 v212, s[46:47]
	s_mov_b32 m0, s3
	s_add_i32 s33, s94, 0x6000
	global_load_lds_dwordx4 v208, s[8:9]
	s_mov_b32 m0, s33
	v_mov_b32_e32 v211, 0
	global_load_lds_dwordx4 v212, s[8:9]
	v_readlane_b32 s8, v254, 58
	v_mov_b32_e32 v215, v211
	v_mov_b32_e32 v209, v211
	v_mov_b32_e32 v213, v211
	v_readlane_b32 s9, v254, 59
	v_lshl_add_u64 v[6:7], s[44:45], 0, v[210:211]
	v_lshl_add_u64 v[4:5], s[44:45], 0, v[214:215]
	v_lshl_add_u64 v[0:1], s[46:47], 0, v[208:209]
	s_and_b64 vcc, exec, s[8:9]
	v_lshl_add_u64 v[2:3], s[46:47], 0, v[212:213]
	s_cbranch_vccnz .LBB0_2004
	s_barrier
	s_setprio 1

.LBB0_2019:
	s_cmp_lt_u32 s5, 0x3fffffff
	s_cselect_b64 s[40:41], -1, 0
	s_ashr_i32 s23, s22, 31
	s_and_b64 s[40:41], s[36:37], s[40:41]
	s_lshl_b64 s[36:37], s[22:23], 21
	s_add_u32 s5, s86, s36
	s_addc_u32 s21, s87, s37
	s_add_u32 s36, s5, s38
	s_addc_u32 s37, s21, s39
	s_and_b64 s[48:49], s[40:41], exec
	s_cselect_b32 s5, s37, s47
	s_cselect_b32 s23, s36, s46
	s_ashr_i32 s21, s20, 31
	s_lshl_b64 s[48:49], s[20:21], 21
	v_readlane_b32 s68, v254, 13
	v_readlane_b32 s69, v254, 14
	s_add_u32 s21, s68, s48
	s_addc_u32 s43, s69, s49
	s_add_u32 s38, s21, s38
	s_addc_u32 s39, s43, s39
	s_and_b64 s[48:49], s[40:41], exec
	s_cselect_b32 s21, s39, s45
	s_cselect_b32 s43, s38, s44
	s_add_i32 s68, s67, -2
	s_add_u32 s69, s44, 0x100
	s_addc_u32 s70, s45, 0
	s_add_u32 s44, s46, 0x100080
	s_addc_u32 s45, s47, 0
	s_mov_b32 s46, 0
	s_waitcnt vmcnt(0)
	ds_read_b128 v[128:131], v244
	ds_read_b128 v[132:135], v244 offset:1024
	ds_read_b128 v[136:139], v244 offset:2048
	ds_read_b128 v[140:143], v244 offset:3072
	ds_read_b128 v[144:147], v245
	ds_read_b128 v[148:151], v245 offset:1024
	ds_read_b128 v[152:155], v245 offset:2048
	ds_read_b128 v[156:159], v245 offset:3072
	s_add_i32 s71, s46, 2
	s_add_u32 s47, s44, 0xfff00080
	s_addc_u32 s48, s45, -1
	s_cmp_eq_u32 s68, s46
	s_cselect_b32 s46, s43, s69
	s_cselect_b32 s49, s5, s48
	s_cselect_b32 s48, s23, s47
	s_cselect_b32 s47, s21, s70
	s_add_i32 m0, s94, 0xc000
	ds_read_b128 v[160:163], v246
	ds_read_b128 v[164:167], v246 offset:1024
	ds_read_b128 v[168:171], v246 offset:2048
	ds_read_b128 v[172:175], v246 offset:3072
	ds_read_b128 v[176:179], v246 offset:4096
	ds_read_b128 v[180:183], v246 offset:5120
	ds_read_b128 v[184:187], v246 offset:6144
	ds_read_b128 v[188:191], v246 offset:7168
	global_load_lds_dwordx4 v218, s[44:45]
	s_add_i32 m0, s94, 0xe000
	s_nop 0
	global_load_lds_dwordx4 v220, s[44:45]
	s_waitcnt vmcnt(8)
	s_waitcnt lgkmcnt(0)
	s_barrier
	v_mfma_f32_16x16x32_bf16 v[112:115], v[128:131], v[160:163], 0
	v_mfma_f32_16x16x32_bf16 v[116:119], v[136:139], v[160:163], 0
	v_mfma_f32_16x16x32_bf16 v[100:103], v[128:131], v[168:171], 0
	v_mfma_f32_16x16x32_bf16 v[96:99], v[136:139], v[168:171], 0
	v_mfma_f32_16x16x32_bf16 v[84:87], v[128:131], v[176:179], 0
	v_mfma_f32_16x16x32_bf16 v[80:83], v[136:139], v[176:179], 0
	v_mfma_f32_16x16x32_bf16 v[52:55], v[128:131], v[184:187], 0
	v_mfma_f32_16x16x32_bf16 v[48:51], v[136:139], v[184:187], 0
	v_mfma_f32_16x16x32_bf16 v[112:115], v[132:135], v[164:167], v[112:115]
	v_mfma_f32_16x16x32_bf16 v[116:119], v[140:143], v[164:167], v[116:119]
	v_mfma_f32_16x16x32_bf16 v[100:103], v[132:135], v[172:175], v[100:103]
	v_mfma_f32_16x16x32_bf16 v[96:99], v[140:143], v[172:175], v[96:99]
	v_mfma_f32_16x16x32_bf16 v[84:87], v[132:135], v[180:183], v[84:87]
	v_mfma_f32_16x16x32_bf16 v[80:83], v[140:143], v[180:183], v[80:83]
	v_mfma_f32_16x16x32_bf16 v[52:55], v[132:135], v[188:191], v[52:55]
	v_mfma_f32_16x16x32_bf16 v[48:51], v[140:143], v[188:191], v[48:51]
	v_mfma_f32_16x16x32_bf16 v[124:127], v[144:147], v[160:163], 0
	v_mfma_f32_16x16x32_bf16 v[120:123], v[152:155], v[160:163], 0
	v_mfma_f32_16x16x32_bf16 v[108:111], v[144:147], v[168:171], 0
	v_mfma_f32_16x16x32_bf16 v[104:107], v[152:155], v[168:171], 0
	v_mfma_f32_16x16x32_bf16 v[92:95], v[144:147], v[176:179], 0
	v_mfma_f32_16x16x32_bf16 v[88:91], v[152:155], v[176:179], 0
	v_mfma_f32_16x16x32_bf16 v[68:71], v[144:147], v[184:187], 0
	v_mfma_f32_16x16x32_bf16 v[64:67], v[152:155], v[184:187], 0
	v_mfma_f32_16x16x32_bf16 v[124:127], v[148:151], v[164:167], v[124:127]
	v_mfma_f32_16x16x32_bf16 v[120:123], v[156:159], v[164:167], v[120:123]
	v_mfma_f32_16x16x32_bf16 v[108:111], v[148:151], v[172:175], v[108:111]
	v_mfma_f32_16x16x32_bf16 v[104:107], v[156:159], v[172:175], v[104:107]
	v_mfma_f32_16x16x32_bf16 v[92:95], v[148:151], v[180:183], v[92:95]
	v_mfma_f32_16x16x32_bf16 v[88:91], v[156:159], v[180:183], v[88:91]
	v_mfma_f32_16x16x32_bf16 v[68:71], v[148:151], v[188:191], v[68:71]
	v_mfma_f32_16x16x32_bf16 v[64:67], v[156:159], v[188:191], v[64:67]
	s_barrier
	s_add_i32 s76, s60, s97
	s_add_u32 s98, s46, 0x80
	s_addc_u32 s99, s47, 0
	s_mov_b32 m0, s76
	ds_read_b128 v[160:163], v246 offset:16384
	ds_read_b128 v[164:167], v246 offset:17408
	ds_read_b128 v[168:171], v246 offset:18432
	ds_read_b128 v[172:175], v246 offset:19456
	ds_read_b128 v[176:179], v246 offset:20480
	ds_read_b128 v[180:183], v246 offset:21504
	ds_read_b128 v[184:187], v246 offset:22528
	ds_read_b128 v[188:191], v246 offset:23552
	global_load_lds_dwordx4 v210, s[46:47]
	s_add_i32 m0, s76, 0x2000
	s_add_u32 s76, s46, 0x100000
	s_addc_u32 s77, s47, 0
	s_add_i32 s78, s61, s97
	global_load_lds_dwordx4 v214, s[46:47]
	s_mov_b32 m0, s78
	s_add_u32 s100, s48, 0x80
	s_addc_u32 s101, s49, 0
	global_load_lds_dwordx4 v210, s[76:77]
	s_add_i32 m0, s78, 0x2000
	s_nop 0
	global_load_lds_dwordx4 v214, s[76:77]
	s_mov_b32 m0, s94
	s_nop 0
	global_load_lds_dwordx4 v208, s[48:49]
	s_mov_b32 m0, s2
	s_nop 0
	global_load_lds_dwordx4 v212, s[48:49]
	s_waitcnt vmcnt(8)
	s_waitcnt lgkmcnt(0)
	s_barrier
	v_mfma_f32_16x16x32_bf16 v[60:63], v[128:131], v[160:163], 0
	v_mfma_f32_16x16x32_bf16 v[56:59], v[136:139], v[160:163], 0
	v_mfma_f32_16x16x32_bf16 v[36:39], v[128:131], v[168:171], 0
	v_mfma_f32_16x16x32_bf16 v[32:35], v[136:139], v[168:171], 0
	v_mfma_f32_16x16x32_bf16 v[20:23], v[128:131], v[176:179], 0
	v_mfma_f32_16x16x32_bf16 v[16:19], v[136:139], v[176:179], 0
	v_mfma_f32_16x16x32_bf16 v[4:7], v[128:131], v[184:187], 0
	v_mfma_f32_16x16x32_bf16 v[0:3], v[136:139], v[184:187], 0
	v_mfma_f32_16x16x32_bf16 v[60:63], v[132:135], v[164:167], v[60:63]
	v_mfma_f32_16x16x32_bf16 v[56:59], v[140:143], v[164:167], v[56:59]
	v_mfma_f32_16x16x32_bf16 v[36:39], v[132:135], v[172:175], v[36:39]
	v_mfma_f32_16x16x32_bf16 v[32:35], v[140:143], v[172:175], v[32:35]
	v_mfma_f32_16x16x32_bf16 v[20:23], v[132:135], v[180:183], v[20:23]
	v_mfma_f32_16x16x32_bf16 v[16:19], v[140:143], v[180:183], v[16:19]
	v_mfma_f32_16x16x32_bf16 v[4:7], v[132:135], v[188:191], v[4:7]
	v_mfma_f32_16x16x32_bf16 v[0:3], v[140:143], v[188:191], v[0:3]
	v_mfma_f32_16x16x32_bf16 v[76:79], v[144:147], v[160:163], 0
	v_mfma_f32_16x16x32_bf16 v[72:75], v[152:155], v[160:163], 0
	v_mfma_f32_16x16x32_bf16 v[44:47], v[144:147], v[168:171], 0
	v_mfma_f32_16x16x32_bf16 v[40:43], v[152:155], v[168:171], 0
	v_mfma_f32_16x16x32_bf16 v[28:31], v[144:147], v[176:179], 0
	v_mfma_f32_16x16x32_bf16 v[24:27], v[152:155], v[176:179], 0
	v_mfma_f32_16x16x32_bf16 v[12:15], v[144:147], v[184:187], 0
	v_mfma_f32_16x16x32_bf16 v[8:11], v[152:155], v[184:187], 0
	v_mfma_f32_16x16x32_bf16 v[76:79], v[148:151], v[164:167], v[76:79]
	v_mfma_f32_16x16x32_bf16 v[72:75], v[156:159], v[164:167], v[72:75]
	v_mfma_f32_16x16x32_bf16 v[44:47], v[148:151], v[172:175], v[44:47]
	v_mfma_f32_16x16x32_bf16 v[40:43], v[156:159], v[172:175], v[40:43]
	v_mfma_f32_16x16x32_bf16 v[28:31], v[148:151], v[180:183], v[28:31]
	v_mfma_f32_16x16x32_bf16 v[24:27], v[156:159], v[180:183], v[24:27]
	v_mfma_f32_16x16x32_bf16 v[12:15], v[148:151], v[188:191], v[12:15]
	v_mfma_f32_16x16x32_bf16 v[8:11], v[156:159], v[188:191], v[8:11]
	s_barrier
	s_add_i32 s76, 0, 0x18000
	s_add_i32 s77, 0, 0x1c000
	v_add_u32_e32 v140, s76, v243
	v_add_u32_e32 v156, s77, v243
	ds_read_b128 v[128:131], v140
	ds_read_b128 v[132:135], v140 offset:1024
	ds_read_b128 v[136:139], v140 offset:2048
	ds_read_b128 v[140:143], v140 offset:3072
	ds_read_b128 v[144:147], v156
	ds_read_b128 v[148:151], v156 offset:1024
	ds_read_b128 v[152:155], v156 offset:2048
	ds_read_b128 v[156:159], v156 offset:3072
	s_add_u32 s48, s48, 0x100000
	s_addc_u32 s49, s49, 0
	s_mov_b32 m0, s3
	ds_read_b128 v[160:163], v246 offset:32768
	ds_read_b128 v[164:167], v246 offset:33792
	ds_read_b128 v[168:171], v246 offset:34816
	ds_read_b128 v[172:175], v246 offset:35840
	ds_read_b128 v[176:179], v246 offset:36864
	ds_read_b128 v[180:183], v246 offset:37888
	ds_read_b128 v[184:187], v246 offset:38912
	ds_read_b128 v[188:191], v246 offset:39936
	global_load_lds_dwordx4 v208, s[48:49]
	s_mov_b32 m0, s33
	s_nop 0
	global_load_lds_dwordx4 v212, s[48:49]
	s_waitcnt vmcnt(8)
	s_waitcnt lgkmcnt(0)
	s_barrier
	v_mfma_f32_16x16x32_bf16 v[112:115], v[128:131], v[160:163], v[112:115]
	v_mfma_f32_16x16x32_bf16 v[116:119], v[136:139], v[160:163], v[116:119]
	v_mfma_f32_16x16x32_bf16 v[100:103], v[128:131], v[168:171], v[100:103]
	v_mfma_f32_16x16x32_bf16 v[96:99], v[136:139], v[168:171], v[96:99]
	v_mfma_f32_16x16x32_bf16 v[84:87], v[128:131], v[176:179], v[84:87]
	v_mfma_f32_16x16x32_bf16 v[80:83], v[136:139], v[176:179], v[80:83]
	v_mfma_f32_16x16x32_bf16 v[52:55], v[128:131], v[184:187], v[52:55]
	v_mfma_f32_16x16x32_bf16 v[48:51], v[136:139], v[184:187], v[48:51]
	v_mfma_f32_16x16x32_bf16 v[112:115], v[132:135], v[164:167], v[112:115]
	v_mfma_f32_16x16x32_bf16 v[116:119], v[140:143], v[164:167], v[116:119]
	v_mfma_f32_16x16x32_bf16 v[100:103], v[132:135], v[172:175], v[100:103]
	v_mfma_f32_16x16x32_bf16 v[96:99], v[140:143], v[172:175], v[96:99]
	v_mfma_f32_16x16x32_bf16 v[84:87], v[132:135], v[180:183], v[84:87]
	v_mfma_f32_16x16x32_bf16 v[80:83], v[140:143], v[180:183], v[80:83]
	v_mfma_f32_16x16x32_bf16 v[52:55], v[132:135], v[188:191], v[52:55]
	v_mfma_f32_16x16x32_bf16 v[48:51], v[140:143], v[188:191], v[48:51]
	v_mfma_f32_16x16x32_bf16 v[124:127], v[144:147], v[160:163], v[124:127]
	v_mfma_f32_16x16x32_bf16 v[120:123], v[152:155], v[160:163], v[120:123]
	v_mfma_f32_16x16x32_bf16 v[108:111], v[144:147], v[168:171], v[108:111]
	v_mfma_f32_16x16x32_bf16 v[104:107], v[152:155], v[168:171], v[104:107]
	v_mfma_f32_16x16x32_bf16 v[92:95], v[144:147], v[176:179], v[92:95]
	v_mfma_f32_16x16x32_bf16 v[88:91], v[152:155], v[176:179], v[88:91]
	v_mfma_f32_16x16x32_bf16 v[68:71], v[144:147], v[184:187], v[68:71]
	v_mfma_f32_16x16x32_bf16 v[64:67], v[152:155], v[184:187], v[64:67]
	v_mfma_f32_16x16x32_bf16 v[124:127], v[148:151], v[164:167], v[124:127]
	v_mfma_f32_16x16x32_bf16 v[120:123], v[156:159], v[164:167], v[120:123]
	v_mfma_f32_16x16x32_bf16 v[108:111], v[148:151], v[172:175], v[108:111]
	v_mfma_f32_16x16x32_bf16 v[104:107], v[156:159], v[172:175], v[104:107]
	v_mfma_f32_16x16x32_bf16 v[92:95], v[148:151], v[180:183], v[92:95]
	v_mfma_f32_16x16x32_bf16 v[88:91], v[156:159], v[180:183], v[88:91]
	v_mfma_f32_16x16x32_bf16 v[68:71], v[148:151], v[188:191], v[68:71]
	v_mfma_f32_16x16x32_bf16 v[64:67], v[156:159], v[188:191], v[64:67]
	s_barrier
	s_add_i32 s48, s76, s97
	s_mov_b32 m0, s48
	ds_read_b128 v[160:163], v246 offset:49152
	ds_read_b128 v[164:167], v246 offset:50176
	ds_read_b128 v[168:171], v246 offset:51200
	ds_read_b128 v[172:175], v246 offset:52224
	ds_read_b128 v[176:179], v246 offset:53248
	ds_read_b128 v[180:183], v246 offset:54272
	ds_read_b128 v[184:187], v246 offset:55296
	ds_read_b128 v[188:191], v246 offset:56320
	global_load_lds_dwordx4 v210, s[98:99]
	s_add_i32 m0, s48, 0x2000
	s_add_u32 s46, s46, 0x100080
	s_addc_u32 s47, s47, 0
	s_add_i32 s48, s77, s97
	global_load_lds_dwordx4 v214, s[98:99]
	s_mov_b32 m0, s48
	s_nop 0
	global_load_lds_dwordx4 v210, s[46:47]
	s_add_i32 m0, s48, 0x2000
	s_nop 0
	global_load_lds_dwordx4 v214, s[46:47]
	s_mov_b32 m0, s54
	s_nop 0
	global_load_lds_dwordx4 v208, s[100:101]
	s_mov_b32 m0, s55
	s_nop 0
	global_load_lds_dwordx4 v212, s[100:101]
	s_waitcnt vmcnt(8)
	s_waitcnt lgkmcnt(0)
	s_barrier
	v_mfma_f32_16x16x32_bf16 v[60:63], v[128:131], v[160:163], v[60:63]
	v_mfma_f32_16x16x32_bf16 v[56:59], v[136:139], v[160:163], v[56:59]
	v_mfma_f32_16x16x32_bf16 v[36:39], v[128:131], v[168:171], v[36:39]
	v_mfma_f32_16x16x32_bf16 v[32:35], v[136:139], v[168:171], v[32:35]
	v_mfma_f32_16x16x32_bf16 v[20:23], v[128:131], v[176:179], v[20:23]
	v_mfma_f32_16x16x32_bf16 v[16:19], v[136:139], v[176:179], v[16:19]
	v_mfma_f32_16x16x32_bf16 v[4:7], v[128:131], v[184:187], v[4:7]
	v_mfma_f32_16x16x32_bf16 v[0:3], v[136:139], v[184:187], v[0:3]
	v_mfma_f32_16x16x32_bf16 v[60:63], v[132:135], v[164:167], v[60:63]
	v_mfma_f32_16x16x32_bf16 v[56:59], v[140:143], v[164:167], v[56:59]
	v_mfma_f32_16x16x32_bf16 v[36:39], v[132:135], v[172:175], v[36:39]
	v_mfma_f32_16x16x32_bf16 v[32:35], v[140:143], v[172:175], v[32:35]
	v_mfma_f32_16x16x32_bf16 v[20:23], v[132:135], v[180:183], v[20:23]
	v_mfma_f32_16x16x32_bf16 v[16:19], v[140:143], v[180:183], v[16:19]
	v_mfma_f32_16x16x32_bf16 v[4:7], v[132:135], v[188:191], v[4:7]
	v_mfma_f32_16x16x32_bf16 v[0:3], v[140:143], v[188:191], v[0:3]
	v_mfma_f32_16x16x32_bf16 v[76:79], v[144:147], v[160:163], v[76:79]
	v_mfma_f32_16x16x32_bf16 v[72:75], v[152:155], v[160:163], v[72:75]
	v_mfma_f32_16x16x32_bf16 v[44:47], v[144:147], v[168:171], v[44:47]
	v_mfma_f32_16x16x32_bf16 v[40:43], v[152:155], v[168:171], v[40:43]
	v_mfma_f32_16x16x32_bf16 v[28:31], v[144:147], v[176:179], v[28:31]
	v_mfma_f32_16x16x32_bf16 v[24:27], v[152:155], v[176:179], v[24:27]
	v_mfma_f32_16x16x32_bf16 v[12:15], v[144:147], v[184:187], v[12:15]
	v_mfma_f32_16x16x32_bf16 v[8:11], v[152:155], v[184:187], v[8:11]
	v_mfma_f32_16x16x32_bf16 v[76:79], v[148:151], v[164:167], v[76:79]
	v_mfma_f32_16x16x32_bf16 v[72:75], v[156:159], v[164:167], v[72:75]
	v_mfma_f32_16x16x32_bf16 v[44:47], v[148:151], v[172:175], v[44:47]
	v_mfma_f32_16x16x32_bf16 v[40:43], v[156:159], v[172:175], v[40:43]
	v_mfma_f32_16x16x32_bf16 v[28:31], v[148:151], v[180:183], v[28:31]
	v_mfma_f32_16x16x32_bf16 v[24:27], v[156:159], v[180:183], v[24:27]
	v_mfma_f32_16x16x32_bf16 v[12:15], v[148:151], v[188:191], v[12:15]
	v_mfma_f32_16x16x32_bf16 v[8:11], v[156:159], v[188:191], v[8:11]
	s_barrier
	s_add_u32 s69, s69, 0x100
	s_addc_u32 s70, s70, 0
	s_add_u32 s44, s44, 0x100
	s_addc_u32 s45, s45, 0
	s_cmp_ge_u32 s71, s67
	s_mov_b32 s46, s71
	s_cbranch_scc1 .Lpeel_done_2
.LBB0_2020:
	ds_read_b128 v[128:131], v244
	ds_read_b128 v[132:135], v244 offset:1024
	ds_read_b128 v[136:139], v244 offset:2048
	ds_read_b128 v[140:143], v244 offset:3072
	ds_read_b128 v[144:147], v245
	ds_read_b128 v[148:151], v245 offset:1024
	ds_read_b128 v[152:155], v245 offset:2048
	ds_read_b128 v[156:159], v245 offset:3072
	s_add_i32 s71, s46, 2
	s_add_u32 s47, s44, 0xfff00080
	s_addc_u32 s48, s45, -1
	s_cmp_eq_u32 s68, s46
	s_cselect_b32 s46, s43, s69
	s_cselect_b32 s49, s5, s48
	s_cselect_b32 s48, s23, s47
	s_cselect_b32 s47, s21, s70
	s_add_i32 m0, s94, 0xc000
	ds_read_b128 v[160:163], v246
	ds_read_b128 v[164:167], v246 offset:1024
	ds_read_b128 v[168:171], v246 offset:2048
	ds_read_b128 v[172:175], v246 offset:3072
	ds_read_b128 v[176:179], v246 offset:4096
	ds_read_b128 v[180:183], v246 offset:5120
	ds_read_b128 v[184:187], v246 offset:6144
	ds_read_b128 v[188:191], v246 offset:7168
	global_load_lds_dwordx4 v218, s[44:45]
	s_add_i32 m0, s94, 0xe000
	s_nop 0
	global_load_lds_dwordx4 v220, s[44:45]
	s_waitcnt vmcnt(8)
	s_waitcnt lgkmcnt(0)
	s_barrier
	v_mfma_f32_16x16x32_bf16 v[112:115], v[128:131], v[160:163], v[112:115]
	v_mfma_f32_16x16x32_bf16 v[116:119], v[136:139], v[160:163], v[116:119]
	v_mfma_f32_16x16x32_bf16 v[100:103], v[128:131], v[168:171], v[100:103]
	v_mfma_f32_16x16x32_bf16 v[96:99], v[136:139], v[168:171], v[96:99]
	v_mfma_f32_16x16x32_bf16 v[84:87], v[128:131], v[176:179], v[84:87]
	v_mfma_f32_16x16x32_bf16 v[80:83], v[136:139], v[176:179], v[80:83]
	v_mfma_f32_16x16x32_bf16 v[52:55], v[128:131], v[184:187], v[52:55]
	v_mfma_f32_16x16x32_bf16 v[48:51], v[136:139], v[184:187], v[48:51]
	v_mfma_f32_16x16x32_bf16 v[112:115], v[132:135], v[164:167], v[112:115]
	v_mfma_f32_16x16x32_bf16 v[116:119], v[140:143], v[164:167], v[116:119]
	v_mfma_f32_16x16x32_bf16 v[100:103], v[132:135], v[172:175], v[100:103]
	v_mfma_f32_16x16x32_bf16 v[96:99], v[140:143], v[172:175], v[96:99]
	v_mfma_f32_16x16x32_bf16 v[84:87], v[132:135], v[180:183], v[84:87]
	v_mfma_f32_16x16x32_bf16 v[80:83], v[140:143], v[180:183], v[80:83]
	v_mfma_f32_16x16x32_bf16 v[52:55], v[132:135], v[188:191], v[52:55]
	v_mfma_f32_16x16x32_bf16 v[48:51], v[140:143], v[188:191], v[48:51]
	v_mfma_f32_16x16x32_bf16 v[124:127], v[144:147], v[160:163], v[124:127]
	v_mfma_f32_16x16x32_bf16 v[120:123], v[152:155], v[160:163], v[120:123]
	v_mfma_f32_16x16x32_bf16 v[108:111], v[144:147], v[168:171], v[108:111]
	v_mfma_f32_16x16x32_bf16 v[104:107], v[152:155], v[168:171], v[104:107]
	v_mfma_f32_16x16x32_bf16 v[92:95], v[144:147], v[176:179], v[92:95]
	v_mfma_f32_16x16x32_bf16 v[88:91], v[152:155], v[176:179], v[88:91]
	v_mfma_f32_16x16x32_bf16 v[68:71], v[144:147], v[184:187], v[68:71]
	v_mfma_f32_16x16x32_bf16 v[64:67], v[152:155], v[184:187], v[64:67]
	v_mfma_f32_16x16x32_bf16 v[124:127], v[148:151], v[164:167], v[124:127]
	v_mfma_f32_16x16x32_bf16 v[120:123], v[156:159], v[164:167], v[120:123]
	v_mfma_f32_16x16x32_bf16 v[108:111], v[148:151], v[172:175], v[108:111]
	v_mfma_f32_16x16x32_bf16 v[104:107], v[156:159], v[172:175], v[104:107]
	v_mfma_f32_16x16x32_bf16 v[92:95], v[148:151], v[180:183], v[92:95]
	v_mfma_f32_16x16x32_bf16 v[88:91], v[156:159], v[180:183], v[88:91]
	v_mfma_f32_16x16x32_bf16 v[68:71], v[148:151], v[188:191], v[68:71]
	v_mfma_f32_16x16x32_bf16 v[64:67], v[156:159], v[188:191], v[64:67]
	s_barrier
	s_add_i32 s76, s60, s97
	s_add_u32 s98, s46, 0x80
	s_addc_u32 s99, s47, 0
	s_mov_b32 m0, s76
	ds_read_b128 v[160:163], v246 offset:16384
	ds_read_b128 v[164:167], v246 offset:17408
	ds_read_b128 v[168:171], v246 offset:18432
	ds_read_b128 v[172:175], v246 offset:19456
	ds_read_b128 v[176:179], v246 offset:20480
	ds_read_b128 v[180:183], v246 offset:21504
	ds_read_b128 v[184:187], v246 offset:22528
	ds_read_b128 v[188:191], v246 offset:23552
	global_load_lds_dwordx4 v210, s[46:47]
	s_add_i32 m0, s76, 0x2000
	s_add_u32 s76, s46, 0x100000
	s_addc_u32 s77, s47, 0
	s_add_i32 s78, s61, s97
	global_load_lds_dwordx4 v214, s[46:47]
	s_mov_b32 m0, s78
	s_add_u32 s100, s48, 0x80
	s_addc_u32 s101, s49, 0
	global_load_lds_dwordx4 v210, s[76:77]
	s_add_i32 m0, s78, 0x2000
	s_nop 0
	global_load_lds_dwordx4 v214, s[76:77]
	s_mov_b32 m0, s94
	s_nop 0
	global_load_lds_dwordx4 v208, s[48:49]
	s_mov_b32 m0, s2
	s_nop 0
	global_load_lds_dwordx4 v212, s[48:49]
	s_waitcnt vmcnt(8)
	s_waitcnt lgkmcnt(0)
	s_barrier
	v_mfma_f32_16x16x32_bf16 v[60:63], v[128:131], v[160:163], v[60:63]
	v_mfma_f32_16x16x32_bf16 v[56:59], v[136:139], v[160:163], v[56:59]
	v_mfma_f32_16x16x32_bf16 v[36:39], v[128:131], v[168:171], v[36:39]
	v_mfma_f32_16x16x32_bf16 v[32:35], v[136:139], v[168:171], v[32:35]
	v_mfma_f32_16x16x32_bf16 v[20:23], v[128:131], v[176:179], v[20:23]
	v_mfma_f32_16x16x32_bf16 v[16:19], v[136:139], v[176:179], v[16:19]
	v_mfma_f32_16x16x32_bf16 v[4:7], v[128:131], v[184:187], v[4:7]
	v_mfma_f32_16x16x32_bf16 v[0:3], v[136:139], v[184:187], v[0:3]
	v_mfma_f32_16x16x32_bf16 v[60:63], v[132:135], v[164:167], v[60:63]
	v_mfma_f32_16x16x32_bf16 v[56:59], v[140:143], v[164:167], v[56:59]
	v_mfma_f32_16x16x32_bf16 v[36:39], v[132:135], v[172:175], v[36:39]
	v_mfma_f32_16x16x32_bf16 v[32:35], v[140:143], v[172:175], v[32:35]
	v_mfma_f32_16x16x32_bf16 v[20:23], v[132:135], v[180:183], v[20:23]
	v_mfma_f32_16x16x32_bf16 v[16:19], v[140:143], v[180:183], v[16:19]
	v_mfma_f32_16x16x32_bf16 v[4:7], v[132:135], v[188:191], v[4:7]
	v_mfma_f32_16x16x32_bf16 v[0:3], v[140:143], v[188:191], v[0:3]
	v_mfma_f32_16x16x32_bf16 v[76:79], v[144:147], v[160:163], v[76:79]
	v_mfma_f32_16x16x32_bf16 v[72:75], v[152:155], v[160:163], v[72:75]
	v_mfma_f32_16x16x32_bf16 v[44:47], v[144:147], v[168:171], v[44:47]
	v_mfma_f32_16x16x32_bf16 v[40:43], v[152:155], v[168:171], v[40:43]
	v_mfma_f32_16x16x32_bf16 v[28:31], v[144:147], v[176:179], v[28:31]
	v_mfma_f32_16x16x32_bf16 v[24:27], v[152:155], v[176:179], v[24:27]
	v_mfma_f32_16x16x32_bf16 v[12:15], v[144:147], v[184:187], v[12:15]
	v_mfma_f32_16x16x32_bf16 v[8:11], v[152:155], v[184:187], v[8:11]
	v_mfma_f32_16x16x32_bf16 v[76:79], v[148:151], v[164:167], v[76:79]
	v_mfma_f32_16x16x32_bf16 v[72:75], v[156:159], v[164:167], v[72:75]
	v_mfma_f32_16x16x32_bf16 v[44:47], v[148:151], v[172:175], v[44:47]
	v_mfma_f32_16x16x32_bf16 v[40:43], v[156:159], v[172:175], v[40:43]
	v_mfma_f32_16x16x32_bf16 v[28:31], v[148:151], v[180:183], v[28:31]
	v_mfma_f32_16x16x32_bf16 v[24:27], v[156:159], v[180:183], v[24:27]
	v_mfma_f32_16x16x32_bf16 v[12:15], v[148:151], v[188:191], v[12:15]
	v_mfma_f32_16x16x32_bf16 v[8:11], v[156:159], v[188:191], v[8:11]
	s_barrier
	s_add_i32 s76, 0, 0x18000
	s_add_i32 s77, 0, 0x1c000
	v_add_u32_e32 v140, s76, v243
	v_add_u32_e32 v156, s77, v243
	ds_read_b128 v[128:131], v140
	ds_read_b128 v[132:135], v140 offset:1024
	ds_read_b128 v[136:139], v140 offset:2048
	ds_read_b128 v[140:143], v140 offset:3072
	ds_read_b128 v[144:147], v156
	ds_read_b128 v[148:151], v156 offset:1024
	ds_read_b128 v[152:155], v156 offset:2048
	ds_read_b128 v[156:159], v156 offset:3072
	s_add_u32 s48, s48, 0x100000
	s_addc_u32 s49, s49, 0
	s_mov_b32 m0, s3
	ds_read_b128 v[160:163], v246 offset:32768
	ds_read_b128 v[164:167], v246 offset:33792
	ds_read_b128 v[168:171], v246 offset:34816
	ds_read_b128 v[172:175], v246 offset:35840
	ds_read_b128 v[176:179], v246 offset:36864
	ds_read_b128 v[180:183], v246 offset:37888
	ds_read_b128 v[184:187], v246 offset:38912
	ds_read_b128 v[188:191], v246 offset:39936
	global_load_lds_dwordx4 v208, s[48:49]
	s_mov_b32 m0, s33
	s_nop 0
	global_load_lds_dwordx4 v212, s[48:49]
	s_waitcnt vmcnt(8)
	s_waitcnt lgkmcnt(0)
	s_barrier
	v_mfma_f32_16x16x32_bf16 v[112:115], v[128:131], v[160:163], v[112:115]
	v_mfma_f32_16x16x32_bf16 v[116:119], v[136:139], v[160:163], v[116:119]
	v_mfma_f32_16x16x32_bf16 v[100:103], v[128:131], v[168:171], v[100:103]
	v_mfma_f32_16x16x32_bf16 v[96:99], v[136:139], v[168:171], v[96:99]
	v_mfma_f32_16x16x32_bf16 v[84:87], v[128:131], v[176:179], v[84:87]
	v_mfma_f32_16x16x32_bf16 v[80:83], v[136:139], v[176:179], v[80:83]
	v_mfma_f32_16x16x32_bf16 v[52:55], v[128:131], v[184:187], v[52:55]
	v_mfma_f32_16x16x32_bf16 v[48:51], v[136:139], v[184:187], v[48:51]
	v_mfma_f32_16x16x32_bf16 v[112:115], v[132:135], v[164:167], v[112:115]
	v_mfma_f32_16x16x32_bf16 v[116:119], v[140:143], v[164:167], v[116:119]
	v_mfma_f32_16x16x32_bf16 v[100:103], v[132:135], v[172:175], v[100:103]
	v_mfma_f32_16x16x32_bf16 v[96:99], v[140:143], v[172:175], v[96:99]
	v_mfma_f32_16x16x32_bf16 v[84:87], v[132:135], v[180:183], v[84:87]
	v_mfma_f32_16x16x32_bf16 v[80:83], v[140:143], v[180:183], v[80:83]
	v_mfma_f32_16x16x32_bf16 v[52:55], v[132:135], v[188:191], v[52:55]
	v_mfma_f32_16x16x32_bf16 v[48:51], v[140:143], v[188:191], v[48:51]
	v_mfma_f32_16x16x32_bf16 v[124:127], v[144:147], v[160:163], v[124:127]
	v_mfma_f32_16x16x32_bf16 v[120:123], v[152:155], v[160:163], v[120:123]
	v_mfma_f32_16x16x32_bf16 v[108:111], v[144:147], v[168:171], v[108:111]
	v_mfma_f32_16x16x32_bf16 v[104:107], v[152:155], v[168:171], v[104:107]
	v_mfma_f32_16x16x32_bf16 v[92:95], v[144:147], v[176:179], v[92:95]
	v_mfma_f32_16x16x32_bf16 v[88:91], v[152:155], v[176:179], v[88:91]
	v_mfma_f32_16x16x32_bf16 v[68:71], v[144:147], v[184:187], v[68:71]
	v_mfma_f32_16x16x32_bf16 v[64:67], v[152:155], v[184:187], v[64:67]
	v_mfma_f32_16x16x32_bf16 v[124:127], v[148:151], v[164:167], v[124:127]
	v_mfma_f32_16x16x32_bf16 v[120:123], v[156:159], v[164:167], v[120:123]
	v_mfma_f32_16x16x32_bf16 v[108:111], v[148:151], v[172:175], v[108:111]
	v_mfma_f32_16x16x32_bf16 v[104:107], v[156:159], v[172:175], v[104:107]
	v_mfma_f32_16x16x32_bf16 v[92:95], v[148:151], v[180:183], v[92:95]
	v_mfma_f32_16x16x32_bf16 v[88:91], v[156:159], v[180:183], v[88:91]
	v_mfma_f32_16x16x32_bf16 v[68:71], v[148:151], v[188:191], v[68:71]
	v_mfma_f32_16x16x32_bf16 v[64:67], v[156:159], v[188:191], v[64:67]
	s_barrier
	s_add_i32 s48, s76, s97
	s_mov_b32 m0, s48
	ds_read_b128 v[160:163], v246 offset:49152
	ds_read_b128 v[164:167], v246 offset:50176
	ds_read_b128 v[168:171], v246 offset:51200
	ds_read_b128 v[172:175], v246 offset:52224
	ds_read_b128 v[176:179], v246 offset:53248
	ds_read_b128 v[180:183], v246 offset:54272
	ds_read_b128 v[184:187], v246 offset:55296
	ds_read_b128 v[188:191], v246 offset:56320
	global_load_lds_dwordx4 v210, s[98:99]
	s_add_i32 m0, s48, 0x2000
	s_add_u32 s46, s46, 0x100080
	s_addc_u32 s47, s47, 0
	s_add_i32 s48, s77, s97
	global_load_lds_dwordx4 v214, s[98:99]
	s_mov_b32 m0, s48
	s_nop 0
	global_load_lds_dwordx4 v210, s[46:47]
	s_add_i32 m0, s48, 0x2000
	s_nop 0
	global_load_lds_dwordx4 v214, s[46:47]
	s_mov_b32 m0, s54
	s_nop 0
	global_load_lds_dwordx4 v208, s[100:101]
	s_mov_b32 m0, s55
	s_nop 0
	global_load_lds_dwordx4 v212, s[100:101]
	s_waitcnt vmcnt(8)
	s_waitcnt lgkmcnt(0)
	s_barrier
	v_mfma_f32_16x16x32_bf16 v[60:63], v[128:131], v[160:163], v[60:63]
	v_mfma_f32_16x16x32_bf16 v[56:59], v[136:139], v[160:163], v[56:59]
	v_mfma_f32_16x16x32_bf16 v[36:39], v[128:131], v[168:171], v[36:39]
	v_mfma_f32_16x16x32_bf16 v[32:35], v[136:139], v[168:171], v[32:35]
	v_mfma_f32_16x16x32_bf16 v[20:23], v[128:131], v[176:179], v[20:23]
	v_mfma_f32_16x16x32_bf16 v[16:19], v[136:139], v[176:179], v[16:19]
	v_mfma_f32_16x16x32_bf16 v[4:7], v[128:131], v[184:187], v[4:7]
	v_mfma_f32_16x16x32_bf16 v[0:3], v[136:139], v[184:187], v[0:3]
	v_mfma_f32_16x16x32_bf16 v[60:63], v[132:135], v[164:167], v[60:63]
	v_mfma_f32_16x16x32_bf16 v[56:59], v[140:143], v[164:167], v[56:59]
	v_mfma_f32_16x16x32_bf16 v[36:39], v[132:135], v[172:175], v[36:39]
	v_mfma_f32_16x16x32_bf16 v[32:35], v[140:143], v[172:175], v[32:35]
	v_mfma_f32_16x16x32_bf16 v[20:23], v[132:135], v[180:183], v[20:23]
	v_mfma_f32_16x16x32_bf16 v[16:19], v[140:143], v[180:183], v[16:19]
	v_mfma_f32_16x16x32_bf16 v[4:7], v[132:135], v[188:191], v[4:7]
	v_mfma_f32_16x16x32_bf16 v[0:3], v[140:143], v[188:191], v[0:3]
	v_mfma_f32_16x16x32_bf16 v[76:79], v[144:147], v[160:163], v[76:79]
	v_mfma_f32_16x16x32_bf16 v[72:75], v[152:155], v[160:163], v[72:75]
	v_mfma_f32_16x16x32_bf16 v[44:47], v[144:147], v[168:171], v[44:47]
	v_mfma_f32_16x16x32_bf16 v[40:43], v[152:155], v[168:171], v[40:43]
	v_mfma_f32_16x16x32_bf16 v[28:31], v[144:147], v[176:179], v[28:31]
	v_mfma_f32_16x16x32_bf16 v[24:27], v[152:155], v[176:179], v[24:27]
	v_mfma_f32_16x16x32_bf16 v[12:15], v[144:147], v[184:187], v[12:15]
	v_mfma_f32_16x16x32_bf16 v[8:11], v[152:155], v[184:187], v[8:11]
	v_mfma_f32_16x16x32_bf16 v[76:79], v[148:151], v[164:167], v[76:79]
	v_mfma_f32_16x16x32_bf16 v[72:75], v[156:159], v[164:167], v[72:75]
	v_mfma_f32_16x16x32_bf16 v[44:47], v[148:151], v[172:175], v[44:47]
	v_mfma_f32_16x16x32_bf16 v[40:43], v[156:159], v[172:175], v[40:43]
	v_mfma_f32_16x16x32_bf16 v[28:31], v[148:151], v[180:183], v[28:31]
	v_mfma_f32_16x16x32_bf16 v[24:27], v[156:159], v[180:183], v[24:27]
	v_mfma_f32_16x16x32_bf16 v[12:15], v[148:151], v[188:191], v[12:15]
	v_mfma_f32_16x16x32_bf16 v[8:11], v[156:159], v[188:191], v[8:11]
	s_barrier
	s_add_u32 s69, s69, 0x100
	s_addc_u32 s70, s70, 0
	s_add_u32 s44, s44, 0x100
	s_addc_u32 s45, s45, 0
	s_cmp_ge_u32 s71, s67
	s_mov_b32 s46, s71
	s_cbranch_scc0 .LBB0_2020

.LBB0_2050:
	s_setprio 0
	s_waitcnt vmcnt(0)
	v_readlane_b32 s60, v254, 29
	v_readlane_b32 s61, v254, 30
	s_barrier

.LBB0_2266:
	s_add_u32 s50, s74, 0x50000
	s_addc_u32 s51, s75, 0
	v_ashrrev_i32_e32 v0, 1, v128
	s_add_u32 s2, s74, 0x2e300000
	v_and_b32_e32 v154, 15, v128
	s_addc_u32 s3, s75, 0
	s_andn2_b64 vcc, exec, s[8:9]
	v_and_b32_e32 v155, -8, v0
	s_cbranch_vccnz .LBB0_2304
	v_lshl_add_u32 v0, v128, 4, s97
	v_ashrrev_i32_e32 v1, 31, v0
	v_lshrrev_b32_e32 v1, 22, v1
	v_add_u32_e32 v1, v0, v1
	v_ashrrev_i32_e32 v8, 10, v1
	v_mul_i32_i24_e32 v1, 0x400, v8
	v_sub_u32_e32 v1, v0, v1
	v_lshrrev_b32_e32 v2, 4, v1
	v_bitop3_b32 v1, v2, v1, 32 bitop3:0x6c
	v_ashrrev_i32_e32 v3, 31, v1
	v_lshrrev_b32_e32 v3, 26, v3
	v_add_u32_e32 v3, v1, v3
	v_lshlrev_b32_e32 v2, 3, v8
	v_ashrrev_i32_e32 v9, 6, v3
	v_and_b32_e32 v3, 0xc0, v3
	v_and_b32_e32 v2, -16, v2
	v_sub_u32_e32 v1, v1, v3
	v_mov_b32_e32 v3, 1
	v_add_u32_e32 v2, v9, v2
	v_ashrrev_i16_sdwa v1, v3, sext(v1) dst_sel:DWORD dst_unused:UNUSED_PAD src0_sel:DWORD src1_sel:BYTE_0
	v_lshlrev_b32_e32 v4, 5, v8
	v_bfe_i32 v10, v1, 0, 16
	v_lshlrev_b32_e32 v1, 1, v2
	v_lshrrev_b32_e32 v5, 2, v2
	v_and_b32_e32 v6, 3, v9
	s_mov_b32 s8, 0x7ffe0
	v_and_b32_e32 v4, 32, v4
	v_and_b32_e32 v1, 24, v1
	v_and_b32_e32 v5, 4, v5
	v_and_or_b32 v6, v2, s8, v6
	v_or3_b32 v1, v6, v5, v1
	v_add_lshl_u32 v4, v4, v10, 1
	v_add_u32_e32 v0, 0x2000, v0
	v_lshl_add_u32 v132, v1, 13, v4
	v_ashrrev_i32_e32 v1, 31, v0
	v_lshrrev_b32_e32 v1, 22, v1
	v_add_u32_e32 v1, v0, v1
	v_ashrrev_i32_e32 v11, 10, v1
	v_mul_i32_i24_e32 v1, 0x400, v11
	v_sub_u32_e32 v0, v0, v1
	v_lshrrev_b32_e32 v1, 4, v0
	v_bitop3_b32 v0, v1, v0, 32 bitop3:0x6c
	v_lshl_add_u32 v130, v2, 13, v4
	v_ashrrev_i32_e32 v2, 31, v0
	v_lshrrev_b32_e32 v2, 26, v2
	v_add_u32_e32 v2, v0, v2
	v_ashrrev_i32_e32 v12, 6, v2
	v_and_b32_e32 v2, 0xffc0, v2
	v_sub_u32_e32 v0, v0, v2
	v_lshrrev_b16_e32 v2, 7, v0
	v_lshlrev_b32_e32 v1, 3, v11
	v_and_b32_e32 v2, 1, v2
	v_and_b32_e32 v1, -16, v1
	v_add_u16_e32 v0, v0, v2
	v_add_u32_e32 v1, v12, v1
	v_ashrrev_i16_sdwa v0, v3, sext(v0) dst_sel:DWORD dst_unused:UNUSED_PAD src0_sel:DWORD src1_sel:BYTE_0
	v_and_b32_e32 v3, 3, v12
	s_ashr_i32 s43, s42, 31
	v_and_or_b32 v3, v1, s8, v3
	s_lshl_b64 s[8:9], s[42:43], 21
	s_add_u32 s10, s26, s8
	s_addc_u32 s11, s27, s9
	s_ashr_i32 s41, s40, 31
	s_lshr_b32 s8, s41, 2
	s_add_i32 s8, s40, s8
	s_ashr_i32 s8, s8, 30
	s_ashr_i32 s9, s8, 31
	s_lshl_b64 s[8:9], s[8:9], 13
	s_add_u32 s10, s10, s8
	s_addc_u32 s11, s11, s9
	s_lshl_b64 s[8:9], s[40:41], 21
	v_readlane_b32 s18, v254, 52
	v_readlane_b32 s19, v254, 53
	s_add_u32 s8, s18, s8
	s_addc_u32 s9, s19, s9
	v_lshlrev_b32_e32 v4, 5, v11
	v_bfe_i32 v13, v0, 0, 16
	v_lshlrev_b32_e32 v0, 1, v1
	v_lshrrev_b32_e32 v2, 2, v1
	s_add_u32 s44, s8, s4
	v_and_b32_e32 v4, 32, v4
	v_and_b32_e32 v0, 24, v0
	v_and_b32_e32 v2, 4, v2
	s_addc_u32 s45, s9, s5
	s_add_i32 m0, s94, 0x10000
	v_or3_b32 v0, v3, v2, v0
	v_add_lshl_u32 v2, v4, v13, 1
	global_load_lds_dwordx4 v132, s[44:45]
	s_add_i32 m0, s94, 0x12000
	v_lshl_add_u32 v136, v0, 13, v2
	s_add_u32 s8, s44, 0x100000
	global_load_lds_dwordx4 v136, s[44:45]
	s_addc_u32 s9, s45, 0
	s_add_i32 m0, s94, 0x14000
	v_lshl_add_u32 v134, v1, 13, v2
	global_load_lds_dwordx4 v132, s[8:9]
	s_add_i32 m0, s94, 0x16000
	s_add_u32 s46, s10, s4
	s_addc_u32 s47, s11, s5
	s_add_i32 s52, s94, 0x2000
	global_load_lds_dwordx4 v136, s[8:9]
	s_mov_b32 m0, s94
	s_add_u32 s4, s46, 0x100000
	global_load_lds_dwordx4 v130, s[46:47]
	s_mov_b32 m0, s52
	s_addc_u32 s5, s47, 0
	s_add_i32 s53, s94, 0x4000
	global_load_lds_dwordx4 v134, s[46:47]
	s_mov_b32 m0, s53
	s_add_i32 s54, s94, 0x6000
	global_load_lds_dwordx4 v130, s[4:5]
	s_mov_b32 m0, s54
	v_mov_b32_e32 v133, 0
	global_load_lds_dwordx4 v134, s[4:5]
	v_readlane_b32 s4, v254, 58
	v_mov_b32_e32 v137, v133
	v_mov_b32_e32 v131, v133
	v_mov_b32_e32 v135, v133
	v_readlane_b32 s5, v254, 59
	v_lshl_add_u64 v[6:7], s[44:45], 0, v[132:133]
	s_mov_b32 s17, 0
	v_lshl_add_u64 v[4:5], s[44:45], 0, v[136:137]
	v_lshl_add_u64 v[0:1], s[46:47], 0, v[130:131]
	s_and_b64 vcc, exec, s[4:5]
	v_lshl_add_u64 v[2:3], s[46:47], 0, v[134:135]
	s_cbranch_vccnz .LBB0_2269
	s_barrier
	s_setprio 1

.LBB0_2288:
	s_ashr_i32 s25, s24, 31
	s_lshl_b64 s[86:87], s[24:25], 21
	v_readlane_b32 s88, v254, 52
	v_readlane_b32 s89, v254, 53
	s_add_u32 s5, s88, s86
	s_addc_u32 s25, s89, s87
	s_add_u32 s38, s5, s38
	s_addc_u32 s39, s25, s39
	s_and_b64 s[48:49], s[48:49], exec
	s_cselect_b32 s5, s39, s45
	s_cselect_b32 s25, s38, s44
	s_add_i32 s43, s84, -2
	s_add_u32 s85, s44, 0x100
	s_addc_u32 s86, s45, 0
	s_add_u32 s44, s46, 0x100080
	s_addc_u32 s45, s47, 0
	s_mov_b32 s46, 0
	ds_read_b128 v[148:151], v159
	ds_read_b128 v[164:167], v159 offset:1024
	ds_read_b128 v[168:171], v159 offset:2048
	ds_read_b128 v[172:175], v159 offset:3072
	ds_read_b128 v[176:179], v160
	ds_read_b128 v[180:183], v160 offset:1024
	ds_read_b128 v[184:187], v160 offset:2048
	ds_read_b128 v[188:191], v160 offset:3072
	s_add_i32 s87, s46, 2
	s_add_u32 s47, s44, 0xfff00080
	s_addc_u32 s48, s45, -1
	s_cmp_eq_u32 s43, s46
	s_cselect_b32 s46, s25, s85
	s_cselect_b32 s49, s37, s48
	s_cselect_b32 s48, s36, s47
	s_cselect_b32 s47, s5, s86
	s_add_i32 m0, s94, 0xc000
	ds_read_b128 v[192:195], v161
	ds_read_b128 v[196:199], v161 offset:1024
	ds_read_b128 v[200:203], v161 offset:2048
	ds_read_b128 v[204:207], v161 offset:3072
	ds_read_b128 v[208:211], v161 offset:4096
	ds_read_b128 v[212:215], v161 offset:5120
	ds_read_b128 v[216:219], v161 offset:6144
	ds_read_b128 v[220:223], v161 offset:7168
	global_load_lds_dwordx4 v142, s[44:45]
	s_add_i32 m0, s94, 0xe000
	s_nop 0
	global_load_lds_dwordx4 v144, s[44:45]
	s_waitcnt vmcnt(8)
	s_waitcnt lgkmcnt(0)
	s_barrier
	v_mfma_f32_16x16x32_bf16 v[112:115], v[148:151], v[192:195], 0
	v_mfma_f32_16x16x32_bf16 v[116:119], v[168:171], v[192:195], 0
	v_mfma_f32_16x16x32_bf16 v[100:103], v[148:151], v[200:203], 0
	v_mfma_f32_16x16x32_bf16 v[96:99], v[168:171], v[200:203], 0
	v_mfma_f32_16x16x32_bf16 v[84:87], v[148:151], v[208:211], 0
	v_mfma_f32_16x16x32_bf16 v[80:83], v[168:171], v[208:211], 0
	v_mfma_f32_16x16x32_bf16 v[52:55], v[148:151], v[216:219], 0
	v_mfma_f32_16x16x32_bf16 v[48:51], v[168:171], v[216:219], 0
	v_mfma_f32_16x16x32_bf16 v[112:115], v[164:167], v[196:199], v[112:115]
	v_mfma_f32_16x16x32_bf16 v[116:119], v[172:175], v[196:199], v[116:119]
	v_mfma_f32_16x16x32_bf16 v[100:103], v[164:167], v[204:207], v[100:103]
	v_mfma_f32_16x16x32_bf16 v[96:99], v[172:175], v[204:207], v[96:99]
	v_mfma_f32_16x16x32_bf16 v[84:87], v[164:167], v[212:215], v[84:87]
	v_mfma_f32_16x16x32_bf16 v[80:83], v[172:175], v[212:215], v[80:83]
	v_mfma_f32_16x16x32_bf16 v[52:55], v[164:167], v[220:223], v[52:55]
	v_mfma_f32_16x16x32_bf16 v[48:51], v[172:175], v[220:223], v[48:51]
	v_mfma_f32_16x16x32_bf16 v[124:127], v[176:179], v[192:195], 0
	v_mfma_f32_16x16x32_bf16 v[120:123], v[184:187], v[192:195], 0
	v_mfma_f32_16x16x32_bf16 v[108:111], v[176:179], v[200:203], 0
	v_mfma_f32_16x16x32_bf16 v[104:107], v[184:187], v[200:203], 0
	v_mfma_f32_16x16x32_bf16 v[92:95], v[176:179], v[208:211], 0
	v_mfma_f32_16x16x32_bf16 v[88:91], v[184:187], v[208:211], 0
	v_mfma_f32_16x16x32_bf16 v[68:71], v[176:179], v[216:219], 0
	v_mfma_f32_16x16x32_bf16 v[64:67], v[184:187], v[216:219], 0
	v_mfma_f32_16x16x32_bf16 v[124:127], v[180:183], v[196:199], v[124:127]
	v_mfma_f32_16x16x32_bf16 v[120:123], v[188:191], v[196:199], v[120:123]
	v_mfma_f32_16x16x32_bf16 v[108:111], v[180:183], v[204:207], v[108:111]
	v_mfma_f32_16x16x32_bf16 v[104:107], v[188:191], v[204:207], v[104:107]
	v_mfma_f32_16x16x32_bf16 v[92:95], v[180:183], v[212:215], v[92:95]
	v_mfma_f32_16x16x32_bf16 v[88:91], v[188:191], v[212:215], v[88:91]
	v_mfma_f32_16x16x32_bf16 v[68:71], v[180:183], v[220:223], v[68:71]
	v_mfma_f32_16x16x32_bf16 v[64:67], v[188:191], v[220:223], v[64:67]
	s_barrier
	s_add_i32 s88, s77, s97
	s_add_u32 s98, s46, 0x80
	s_addc_u32 s99, s47, 0
	s_mov_b32 m0, s88
	ds_read_b128 v[192:195], v161 offset:16384
	ds_read_b128 v[196:199], v161 offset:17408
	ds_read_b128 v[200:203], v161 offset:18432
	ds_read_b128 v[204:207], v161 offset:19456
	ds_read_b128 v[208:211], v161 offset:20480
	ds_read_b128 v[212:215], v161 offset:21504
	ds_read_b128 v[216:219], v161 offset:22528
	ds_read_b128 v[220:223], v161 offset:23552
	global_load_lds_dwordx4 v132, s[46:47]
	s_add_i32 m0, s88, 0x2000
	s_add_u32 s88, s46, 0x100000
	s_addc_u32 s89, s47, 0
	s_add_i32 s90, s78, s97
	global_load_lds_dwordx4 v136, s[46:47]
	s_mov_b32 m0, s90
	s_add_u32 s100, s48, 0x80
	s_addc_u32 s101, s49, 0
	global_load_lds_dwordx4 v132, s[88:89]
	s_add_i32 m0, s90, 0x2000
	s_nop 0
	global_load_lds_dwordx4 v136, s[88:89]
	s_mov_b32 m0, s94
	s_nop 0
	global_load_lds_dwordx4 v130, s[48:49]
	s_mov_b32 m0, s52
	s_nop 0
	global_load_lds_dwordx4 v134, s[48:49]
	s_waitcnt vmcnt(8)
	s_waitcnt lgkmcnt(0)
	s_barrier
	v_mfma_f32_16x16x32_bf16 v[60:63], v[148:151], v[192:195], 0
	v_mfma_f32_16x16x32_bf16 v[56:59], v[168:171], v[192:195], 0
	v_mfma_f32_16x16x32_bf16 v[36:39], v[148:151], v[200:203], 0
	v_mfma_f32_16x16x32_bf16 v[32:35], v[168:171], v[200:203], 0
	v_mfma_f32_16x16x32_bf16 v[20:23], v[148:151], v[208:211], 0
	v_mfma_f32_16x16x32_bf16 v[16:19], v[168:171], v[208:211], 0
	v_mfma_f32_16x16x32_bf16 v[4:7], v[148:151], v[216:219], 0
	v_mfma_f32_16x16x32_bf16 v[0:3], v[168:171], v[216:219], 0
	v_mfma_f32_16x16x32_bf16 v[60:63], v[164:167], v[196:199], v[60:63]
	v_mfma_f32_16x16x32_bf16 v[56:59], v[172:175], v[196:199], v[56:59]
	v_mfma_f32_16x16x32_bf16 v[36:39], v[164:167], v[204:207], v[36:39]
	v_mfma_f32_16x16x32_bf16 v[32:35], v[172:175], v[204:207], v[32:35]
	v_mfma_f32_16x16x32_bf16 v[20:23], v[164:167], v[212:215], v[20:23]
	v_mfma_f32_16x16x32_bf16 v[16:19], v[172:175], v[212:215], v[16:19]
	v_mfma_f32_16x16x32_bf16 v[4:7], v[164:167], v[220:223], v[4:7]
	v_mfma_f32_16x16x32_bf16 v[0:3], v[172:175], v[220:223], v[0:3]
	v_mfma_f32_16x16x32_bf16 v[76:79], v[176:179], v[192:195], 0
	v_mfma_f32_16x16x32_bf16 v[72:75], v[184:187], v[192:195], 0
	v_mfma_f32_16x16x32_bf16 v[44:47], v[176:179], v[200:203], 0
	v_mfma_f32_16x16x32_bf16 v[40:43], v[184:187], v[200:203], 0
	v_mfma_f32_16x16x32_bf16 v[28:31], v[176:179], v[208:211], 0
	v_mfma_f32_16x16x32_bf16 v[24:27], v[184:187], v[208:211], 0
	v_mfma_f32_16x16x32_bf16 v[12:15], v[176:179], v[216:219], 0
	v_mfma_f32_16x16x32_bf16 v[8:11], v[184:187], v[216:219], 0
	v_mfma_f32_16x16x32_bf16 v[76:79], v[180:183], v[196:199], v[76:79]
	v_mfma_f32_16x16x32_bf16 v[72:75], v[188:191], v[196:199], v[72:75]
	v_mfma_f32_16x16x32_bf16 v[44:47], v[180:183], v[204:207], v[44:47]
	v_mfma_f32_16x16x32_bf16 v[40:43], v[188:191], v[204:207], v[40:43]
	v_mfma_f32_16x16x32_bf16 v[28:31], v[180:183], v[212:215], v[28:31]
	v_mfma_f32_16x16x32_bf16 v[24:27], v[188:191], v[212:215], v[24:27]
	v_mfma_f32_16x16x32_bf16 v[12:15], v[180:183], v[220:223], v[12:15]
	v_mfma_f32_16x16x32_bf16 v[8:11], v[188:191], v[220:223], v[8:11]
	s_barrier
	s_add_i32 s88, 0, 0x18000
	v_add_u32_e32 v163, s88, v157
	s_add_i32 s89, 0, 0x1c000
	ds_read_b128 v[148:151], v163
	ds_read_b128 v[164:167], v163 offset:1024
	ds_read_b128 v[168:171], v163 offset:2048
	ds_read_b128 v[172:175], v163 offset:3072
	v_add_u32_e32 v163, s89, v157
	ds_read_b128 v[176:179], v163
	ds_read_b128 v[180:183], v163 offset:1024
	ds_read_b128 v[184:187], v163 offset:2048
	ds_read_b128 v[188:191], v163 offset:3072
	s_add_u32 s48, s48, 0x100000
	s_addc_u32 s49, s49, 0
	s_mov_b32 m0, s53
	ds_read_b128 v[192:195], v161 offset:32768
	ds_read_b128 v[196:199], v161 offset:33792
	ds_read_b128 v[200:203], v161 offset:34816
	ds_read_b128 v[204:207], v161 offset:35840
	ds_read_b128 v[208:211], v161 offset:36864
	ds_read_b128 v[212:215], v161 offset:37888
	ds_read_b128 v[216:219], v161 offset:38912
	ds_read_b128 v[220:223], v161 offset:39936
	global_load_lds_dwordx4 v130, s[48:49]
	s_mov_b32 m0, s54
	s_nop 0
	global_load_lds_dwordx4 v134, s[48:49]
	s_waitcnt vmcnt(8)
	s_waitcnt lgkmcnt(0)
	s_barrier
	v_mfma_f32_16x16x32_bf16 v[112:115], v[148:151], v[192:195], v[112:115]
	v_mfma_f32_16x16x32_bf16 v[116:119], v[168:171], v[192:195], v[116:119]
	v_mfma_f32_16x16x32_bf16 v[100:103], v[148:151], v[200:203], v[100:103]
	v_mfma_f32_16x16x32_bf16 v[96:99], v[168:171], v[200:203], v[96:99]
	v_mfma_f32_16x16x32_bf16 v[84:87], v[148:151], v[208:211], v[84:87]
	v_mfma_f32_16x16x32_bf16 v[80:83], v[168:171], v[208:211], v[80:83]
	v_mfma_f32_16x16x32_bf16 v[52:55], v[148:151], v[216:219], v[52:55]
	v_mfma_f32_16x16x32_bf16 v[48:51], v[168:171], v[216:219], v[48:51]
	v_mfma_f32_16x16x32_bf16 v[112:115], v[164:167], v[196:199], v[112:115]
	v_mfma_f32_16x16x32_bf16 v[116:119], v[172:175], v[196:199], v[116:119]
	v_mfma_f32_16x16x32_bf16 v[100:103], v[164:167], v[204:207], v[100:103]
	v_mfma_f32_16x16x32_bf16 v[96:99], v[172:175], v[204:207], v[96:99]
	v_mfma_f32_16x16x32_bf16 v[84:87], v[164:167], v[212:215], v[84:87]
	v_mfma_f32_16x16x32_bf16 v[80:83], v[172:175], v[212:215], v[80:83]
	v_mfma_f32_16x16x32_bf16 v[52:55], v[164:167], v[220:223], v[52:55]
	v_mfma_f32_16x16x32_bf16 v[48:51], v[172:175], v[220:223], v[48:51]
	v_mfma_f32_16x16x32_bf16 v[124:127], v[176:179], v[192:195], v[124:127]
	v_mfma_f32_16x16x32_bf16 v[120:123], v[184:187], v[192:195], v[120:123]
	v_mfma_f32_16x16x32_bf16 v[108:111], v[176:179], v[200:203], v[108:111]
	v_mfma_f32_16x16x32_bf16 v[104:107], v[184:187], v[200:203], v[104:107]
	v_mfma_f32_16x16x32_bf16 v[92:95], v[176:179], v[208:211], v[92:95]
	v_mfma_f32_16x16x32_bf16 v[88:91], v[184:187], v[208:211], v[88:91]
	v_mfma_f32_16x16x32_bf16 v[68:71], v[176:179], v[216:219], v[68:71]
	v_mfma_f32_16x16x32_bf16 v[64:67], v[184:187], v[216:219], v[64:67]
	v_mfma_f32_16x16x32_bf16 v[124:127], v[180:183], v[196:199], v[124:127]
	v_mfma_f32_16x16x32_bf16 v[120:123], v[188:191], v[196:199], v[120:123]
	v_mfma_f32_16x16x32_bf16 v[108:111], v[180:183], v[204:207], v[108:111]
	v_mfma_f32_16x16x32_bf16 v[104:107], v[188:191], v[204:207], v[104:107]
	v_mfma_f32_16x16x32_bf16 v[92:95], v[180:183], v[212:215], v[92:95]
	v_mfma_f32_16x16x32_bf16 v[88:91], v[188:191], v[212:215], v[88:91]
	v_mfma_f32_16x16x32_bf16 v[68:71], v[180:183], v[220:223], v[68:71]
	v_mfma_f32_16x16x32_bf16 v[64:67], v[188:191], v[220:223], v[64:67]
	s_barrier
	s_add_i32 s48, s88, s97
	s_mov_b32 m0, s48
	ds_read_b128 v[192:195], v161 offset:49152
	ds_read_b128 v[196:199], v161 offset:50176
	ds_read_b128 v[200:203], v161 offset:51200
	ds_read_b128 v[204:207], v161 offset:52224
	ds_read_b128 v[208:211], v161 offset:53248
	ds_read_b128 v[212:215], v161 offset:54272
	ds_read_b128 v[216:219], v161 offset:55296
	ds_read_b128 v[220:223], v161 offset:56320
	global_load_lds_dwordx4 v132, s[98:99]
	s_add_i32 m0, s48, 0x2000
	s_add_u32 s46, s46, 0x100080
	s_addc_u32 s47, s47, 0
	s_add_i32 s48, s89, s97
	global_load_lds_dwordx4 v136, s[98:99]
	s_mov_b32 m0, s48
	s_nop 0
	global_load_lds_dwordx4 v132, s[46:47]
	s_add_i32 m0, s48, 0x2000
	s_nop 0
	global_load_lds_dwordx4 v136, s[46:47]
	s_mov_b32 m0, s68
	s_nop 0
	global_load_lds_dwordx4 v130, s[100:101]
	s_mov_b32 m0, s69
	s_nop 0
	global_load_lds_dwordx4 v134, s[100:101]
	s_waitcnt vmcnt(8)
	s_waitcnt lgkmcnt(0)
	s_barrier
	v_mfma_f32_16x16x32_bf16 v[60:63], v[148:151], v[192:195], v[60:63]
	v_mfma_f32_16x16x32_bf16 v[56:59], v[168:171], v[192:195], v[56:59]
	v_mfma_f32_16x16x32_bf16 v[36:39], v[148:151], v[200:203], v[36:39]
	v_mfma_f32_16x16x32_bf16 v[32:35], v[168:171], v[200:203], v[32:35]
	v_mfma_f32_16x16x32_bf16 v[20:23], v[148:151], v[208:211], v[20:23]
	v_mfma_f32_16x16x32_bf16 v[16:19], v[168:171], v[208:211], v[16:19]
	v_mfma_f32_16x16x32_bf16 v[4:7], v[148:151], v[216:219], v[4:7]
	v_mfma_f32_16x16x32_bf16 v[0:3], v[168:171], v[216:219], v[0:3]
	v_mfma_f32_16x16x32_bf16 v[60:63], v[164:167], v[196:199], v[60:63]
	v_mfma_f32_16x16x32_bf16 v[56:59], v[172:175], v[196:199], v[56:59]
	v_mfma_f32_16x16x32_bf16 v[36:39], v[164:167], v[204:207], v[36:39]
	v_mfma_f32_16x16x32_bf16 v[32:35], v[172:175], v[204:207], v[32:35]
	v_mfma_f32_16x16x32_bf16 v[20:23], v[164:167], v[212:215], v[20:23]
	v_mfma_f32_16x16x32_bf16 v[16:19], v[172:175], v[212:215], v[16:19]
	v_mfma_f32_16x16x32_bf16 v[4:7], v[164:167], v[220:223], v[4:7]
	v_mfma_f32_16x16x32_bf16 v[0:3], v[172:175], v[220:223], v[0:3]
	v_mfma_f32_16x16x32_bf16 v[76:79], v[176:179], v[192:195], v[76:79]
	v_mfma_f32_16x16x32_bf16 v[72:75], v[184:187], v[192:195], v[72:75]
	v_mfma_f32_16x16x32_bf16 v[44:47], v[176:179], v[200:203], v[44:47]
	v_mfma_f32_16x16x32_bf16 v[40:43], v[184:187], v[200:203], v[40:43]
	v_mfma_f32_16x16x32_bf16 v[28:31], v[176:179], v[208:211], v[28:31]
	v_mfma_f32_16x16x32_bf16 v[24:27], v[184:187], v[208:211], v[24:27]
	v_mfma_f32_16x16x32_bf16 v[12:15], v[176:179], v[216:219], v[12:15]
	v_mfma_f32_16x16x32_bf16 v[8:11], v[184:187], v[216:219], v[8:11]
	v_mfma_f32_16x16x32_bf16 v[76:79], v[180:183], v[196:199], v[76:79]
	v_mfma_f32_16x16x32_bf16 v[72:75], v[188:191], v[196:199], v[72:75]
	v_mfma_f32_16x16x32_bf16 v[44:47], v[180:183], v[204:207], v[44:47]
	v_mfma_f32_16x16x32_bf16 v[40:43], v[188:191], v[204:207], v[40:43]
	v_mfma_f32_16x16x32_bf16 v[28:31], v[180:183], v[212:215], v[28:31]
	v_mfma_f32_16x16x32_bf16 v[24:27], v[188:191], v[212:215], v[24:27]
	v_mfma_f32_16x16x32_bf16 v[12:15], v[180:183], v[220:223], v[12:15]
	v_mfma_f32_16x16x32_bf16 v[8:11], v[188:191], v[220:223], v[8:11]
	s_barrier
	s_add_u32 s85, s85, 0x100
	s_addc_u32 s86, s86, 0
	s_add_u32 s44, s44, 0x100
	s_addc_u32 s45, s45, 0
	s_cmp_ge_u32 s87, s84
	s_mov_b32 s46, s87
	s_cbranch_scc1 .Lpeel_done_3
.LBB0_2289:
	ds_read_b128 v[148:151], v159
	ds_read_b128 v[164:167], v159 offset:1024
	ds_read_b128 v[168:171], v159 offset:2048
	ds_read_b128 v[172:175], v159 offset:3072
	ds_read_b128 v[176:179], v160
	ds_read_b128 v[180:183], v160 offset:1024
	ds_read_b128 v[184:187], v160 offset:2048
	ds_read_b128 v[188:191], v160 offset:3072
	s_add_i32 s87, s46, 2
	s_add_u32 s47, s44, 0xfff00080
	s_addc_u32 s48, s45, -1
	s_cmp_eq_u32 s43, s46
	s_cselect_b32 s46, s25, s85
	s_cselect_b32 s49, s37, s48
	s_cselect_b32 s48, s36, s47
	s_cselect_b32 s47, s5, s86
	s_add_i32 m0, s94, 0xc000
	ds_read_b128 v[192:195], v161
	ds_read_b128 v[196:199], v161 offset:1024
	ds_read_b128 v[200:203], v161 offset:2048
	ds_read_b128 v[204:207], v161 offset:3072
	ds_read_b128 v[208:211], v161 offset:4096
	ds_read_b128 v[212:215], v161 offset:5120
	ds_read_b128 v[216:219], v161 offset:6144
	ds_read_b128 v[220:223], v161 offset:7168
	global_load_lds_dwordx4 v142, s[44:45]
	s_add_i32 m0, s94, 0xe000
	s_nop 0
	global_load_lds_dwordx4 v144, s[44:45]
	s_waitcnt vmcnt(8)
	s_waitcnt lgkmcnt(0)
	s_barrier
	v_mfma_f32_16x16x32_bf16 v[112:115], v[148:151], v[192:195], v[112:115]
	v_mfma_f32_16x16x32_bf16 v[116:119], v[168:171], v[192:195], v[116:119]
	v_mfma_f32_16x16x32_bf16 v[100:103], v[148:151], v[200:203], v[100:103]
	v_mfma_f32_16x16x32_bf16 v[96:99], v[168:171], v[200:203], v[96:99]
	v_mfma_f32_16x16x32_bf16 v[84:87], v[148:151], v[208:211], v[84:87]
	v_mfma_f32_16x16x32_bf16 v[80:83], v[168:171], v[208:211], v[80:83]
	v_mfma_f32_16x16x32_bf16 v[52:55], v[148:151], v[216:219], v[52:55]
	v_mfma_f32_16x16x32_bf16 v[48:51], v[168:171], v[216:219], v[48:51]
	v_mfma_f32_16x16x32_bf16 v[112:115], v[164:167], v[196:199], v[112:115]
	v_mfma_f32_16x16x32_bf16 v[116:119], v[172:175], v[196:199], v[116:119]
	v_mfma_f32_16x16x32_bf16 v[100:103], v[164:167], v[204:207], v[100:103]
	v_mfma_f32_16x16x32_bf16 v[96:99], v[172:175], v[204:207], v[96:99]
	v_mfma_f32_16x16x32_bf16 v[84:87], v[164:167], v[212:215], v[84:87]
	v_mfma_f32_16x16x32_bf16 v[80:83], v[172:175], v[212:215], v[80:83]
	v_mfma_f32_16x16x32_bf16 v[52:55], v[164:167], v[220:223], v[52:55]
	v_mfma_f32_16x16x32_bf16 v[48:51], v[172:175], v[220:223], v[48:51]
	v_mfma_f32_16x16x32_bf16 v[124:127], v[176:179], v[192:195], v[124:127]
	v_mfma_f32_16x16x32_bf16 v[120:123], v[184:187], v[192:195], v[120:123]
	v_mfma_f32_16x16x32_bf16 v[108:111], v[176:179], v[200:203], v[108:111]
	v_mfma_f32_16x16x32_bf16 v[104:107], v[184:187], v[200:203], v[104:107]
	v_mfma_f32_16x16x32_bf16 v[92:95], v[176:179], v[208:211], v[92:95]
	v_mfma_f32_16x16x32_bf16 v[88:91], v[184:187], v[208:211], v[88:91]
	v_mfma_f32_16x16x32_bf16 v[68:71], v[176:179], v[216:219], v[68:71]
	v_mfma_f32_16x16x32_bf16 v[64:67], v[184:187], v[216:219], v[64:67]
	v_mfma_f32_16x16x32_bf16 v[124:127], v[180:183], v[196:199], v[124:127]
	v_mfma_f32_16x16x32_bf16 v[120:123], v[188:191], v[196:199], v[120:123]
	v_mfma_f32_16x16x32_bf16 v[108:111], v[180:183], v[204:207], v[108:111]
	v_mfma_f32_16x16x32_bf16 v[104:107], v[188:191], v[204:207], v[104:107]
	v_mfma_f32_16x16x32_bf16 v[92:95], v[180:183], v[212:215], v[92:95]
	v_mfma_f32_16x16x32_bf16 v[88:91], v[188:191], v[212:215], v[88:91]
	v_mfma_f32_16x16x32_bf16 v[68:71], v[180:183], v[220:223], v[68:71]
	v_mfma_f32_16x16x32_bf16 v[64:67], v[188:191], v[220:223], v[64:67]
	s_barrier
	s_add_i32 s88, s77, s97
	s_add_u32 s98, s46, 0x80
	s_addc_u32 s99, s47, 0
	s_mov_b32 m0, s88
	ds_read_b128 v[192:195], v161 offset:16384
	ds_read_b128 v[196:199], v161 offset:17408
	ds_read_b128 v[200:203], v161 offset:18432
	ds_read_b128 v[204:207], v161 offset:19456
	ds_read_b128 v[208:211], v161 offset:20480
	ds_read_b128 v[212:215], v161 offset:21504
	ds_read_b128 v[216:219], v161 offset:22528
	ds_read_b128 v[220:223], v161 offset:23552
	global_load_lds_dwordx4 v132, s[46:47]
	s_add_i32 m0, s88, 0x2000
	s_add_u32 s88, s46, 0x100000
	s_addc_u32 s89, s47, 0
	s_add_i32 s90, s78, s97
	global_load_lds_dwordx4 v136, s[46:47]
	s_mov_b32 m0, s90
	s_add_u32 s100, s48, 0x80
	s_addc_u32 s101, s49, 0
	global_load_lds_dwordx4 v132, s[88:89]
	s_add_i32 m0, s90, 0x2000
	s_nop 0
	global_load_lds_dwordx4 v136, s[88:89]
	s_mov_b32 m0, s94
	s_nop 0
	global_load_lds_dwordx4 v130, s[48:49]
	s_mov_b32 m0, s52
	s_nop 0
	global_load_lds_dwordx4 v134, s[48:49]
	s_waitcnt vmcnt(8)
	s_waitcnt lgkmcnt(0)
	s_barrier
	v_mfma_f32_16x16x32_bf16 v[60:63], v[148:151], v[192:195], v[60:63]
	v_mfma_f32_16x16x32_bf16 v[56:59], v[168:171], v[192:195], v[56:59]
	v_mfma_f32_16x16x32_bf16 v[36:39], v[148:151], v[200:203], v[36:39]
	v_mfma_f32_16x16x32_bf16 v[32:35], v[168:171], v[200:203], v[32:35]
	v_mfma_f32_16x16x32_bf16 v[20:23], v[148:151], v[208:211], v[20:23]
	v_mfma_f32_16x16x32_bf16 v[16:19], v[168:171], v[208:211], v[16:19]
	v_mfma_f32_16x16x32_bf16 v[4:7], v[148:151], v[216:219], v[4:7]
	v_mfma_f32_16x16x32_bf16 v[0:3], v[168:171], v[216:219], v[0:3]
	v_mfma_f32_16x16x32_bf16 v[60:63], v[164:167], v[196:199], v[60:63]
	v_mfma_f32_16x16x32_bf16 v[56:59], v[172:175], v[196:199], v[56:59]
	v_mfma_f32_16x16x32_bf16 v[36:39], v[164:167], v[204:207], v[36:39]
	v_mfma_f32_16x16x32_bf16 v[32:35], v[172:175], v[204:207], v[32:35]
	v_mfma_f32_16x16x32_bf16 v[20:23], v[164:167], v[212:215], v[20:23]
	v_mfma_f32_16x16x32_bf16 v[16:19], v[172:175], v[212:215], v[16:19]
	v_mfma_f32_16x16x32_bf16 v[4:7], v[164:167], v[220:223], v[4:7]
	v_mfma_f32_16x16x32_bf16 v[0:3], v[172:175], v[220:223], v[0:3]
	v_mfma_f32_16x16x32_bf16 v[76:79], v[176:179], v[192:195], v[76:79]
	v_mfma_f32_16x16x32_bf16 v[72:75], v[184:187], v[192:195], v[72:75]
	v_mfma_f32_16x16x32_bf16 v[44:47], v[176:179], v[200:203], v[44:47]
	v_mfma_f32_16x16x32_bf16 v[40:43], v[184:187], v[200:203], v[40:43]
	v_mfma_f32_16x16x32_bf16 v[28:31], v[176:179], v[208:211], v[28:31]
	v_mfma_f32_16x16x32_bf16 v[24:27], v[184:187], v[208:211], v[24:27]
	v_mfma_f32_16x16x32_bf16 v[12:15], v[176:179], v[216:219], v[12:15]
	v_mfma_f32_16x16x32_bf16 v[8:11], v[184:187], v[216:219], v[8:11]
	v_mfma_f32_16x16x32_bf16 v[76:79], v[180:183], v[196:199], v[76:79]
	v_mfma_f32_16x16x32_bf16 v[72:75], v[188:191], v[196:199], v[72:75]
	v_mfma_f32_16x16x32_bf16 v[44:47], v[180:183], v[204:207], v[44:47]
	v_mfma_f32_16x16x32_bf16 v[40:43], v[188:191], v[204:207], v[40:43]
	v_mfma_f32_16x16x32_bf16 v[28:31], v[180:183], v[212:215], v[28:31]
	v_mfma_f32_16x16x32_bf16 v[24:27], v[188:191], v[212:215], v[24:27]
	v_mfma_f32_16x16x32_bf16 v[12:15], v[180:183], v[220:223], v[12:15]
	v_mfma_f32_16x16x32_bf16 v[8:11], v[188:191], v[220:223], v[8:11]
	s_barrier
	s_add_i32 s88, 0, 0x18000
	v_add_u32_e32 v163, s88, v157
	s_add_i32 s89, 0, 0x1c000
	ds_read_b128 v[148:151], v163
	ds_read_b128 v[164:167], v163 offset:1024
	ds_read_b128 v[168:171], v163 offset:2048
	ds_read_b128 v[172:175], v163 offset:3072
	v_add_u32_e32 v163, s89, v157
	ds_read_b128 v[176:179], v163
	ds_read_b128 v[180:183], v163 offset:1024
	ds_read_b128 v[184:187], v163 offset:2048
	ds_read_b128 v[188:191], v163 offset:3072
	s_add_u32 s48, s48, 0x100000
	s_addc_u32 s49, s49, 0
	s_mov_b32 m0, s53
	ds_read_b128 v[192:195], v161 offset:32768
	ds_read_b128 v[196:199], v161 offset:33792
	ds_read_b128 v[200:203], v161 offset:34816
	ds_read_b128 v[204:207], v161 offset:35840
	ds_read_b128 v[208:211], v161 offset:36864
	ds_read_b128 v[212:215], v161 offset:37888
	ds_read_b128 v[216:219], v161 offset:38912
	ds_read_b128 v[220:223], v161 offset:39936
	global_load_lds_dwordx4 v130, s[48:49]
	s_mov_b32 m0, s54
	s_nop 0
	global_load_lds_dwordx4 v134, s[48:49]
	s_waitcnt vmcnt(8)
	s_waitcnt lgkmcnt(0)
	s_barrier
	v_mfma_f32_16x16x32_bf16 v[112:115], v[148:151], v[192:195], v[112:115]
	v_mfma_f32_16x16x32_bf16 v[116:119], v[168:171], v[192:195], v[116:119]
	v_mfma_f32_16x16x32_bf16 v[100:103], v[148:151], v[200:203], v[100:103]
	v_mfma_f32_16x16x32_bf16 v[96:99], v[168:171], v[200:203], v[96:99]
	v_mfma_f32_16x16x32_bf16 v[84:87], v[148:151], v[208:211], v[84:87]
	v_mfma_f32_16x16x32_bf16 v[80:83], v[168:171], v[208:211], v[80:83]
	v_mfma_f32_16x16x32_bf16 v[52:55], v[148:151], v[216:219], v[52:55]
	v_mfma_f32_16x16x32_bf16 v[48:51], v[168:171], v[216:219], v[48:51]
	v_mfma_f32_16x16x32_bf16 v[112:115], v[164:167], v[196:199], v[112:115]
	v_mfma_f32_16x16x32_bf16 v[116:119], v[172:175], v[196:199], v[116:119]
	v_mfma_f32_16x16x32_bf16 v[100:103], v[164:167], v[204:207], v[100:103]
	v_mfma_f32_16x16x32_bf16 v[96:99], v[172:175], v[204:207], v[96:99]
	v_mfma_f32_16x16x32_bf16 v[84:87], v[164:167], v[212:215], v[84:87]
	v_mfma_f32_16x16x32_bf16 v[80:83], v[172:175], v[212:215], v[80:83]
	v_mfma_f32_16x16x32_bf16 v[52:55], v[164:167], v[220:223], v[52:55]
	v_mfma_f32_16x16x32_bf16 v[48:51], v[172:175], v[220:223], v[48:51]
	v_mfma_f32_16x16x32_bf16 v[124:127], v[176:179], v[192:195], v[124:127]
	v_mfma_f32_16x16x32_bf16 v[120:123], v[184:187], v[192:195], v[120:123]
	v_mfma_f32_16x16x32_bf16 v[108:111], v[176:179], v[200:203], v[108:111]
	v_mfma_f32_16x16x32_bf16 v[104:107], v[184:187], v[200:203], v[104:107]
	v_mfma_f32_16x16x32_bf16 v[92:95], v[176:179], v[208:211], v[92:95]
	v_mfma_f32_16x16x32_bf16 v[88:91], v[184:187], v[208:211], v[88:91]
	v_mfma_f32_16x16x32_bf16 v[68:71], v[176:179], v[216:219], v[68:71]
	v_mfma_f32_16x16x32_bf16 v[64:67], v[184:187], v[216:219], v[64:67]
	v_mfma_f32_16x16x32_bf16 v[124:127], v[180:183], v[196:199], v[124:127]
	v_mfma_f32_16x16x32_bf16 v[120:123], v[188:191], v[196:199], v[120:123]
	v_mfma_f32_16x16x32_bf16 v[108:111], v[180:183], v[204:207], v[108:111]
	v_mfma_f32_16x16x32_bf16 v[104:107], v[188:191], v[204:207], v[104:107]
	v_mfma_f32_16x16x32_bf16 v[92:95], v[180:183], v[212:215], v[92:95]
	v_mfma_f32_16x16x32_bf16 v[88:91], v[188:191], v[212:215], v[88:91]
	v_mfma_f32_16x16x32_bf16 v[68:71], v[180:183], v[220:223], v[68:71]
	v_mfma_f32_16x16x32_bf16 v[64:67], v[188:191], v[220:223], v[64:67]
	s_barrier
	s_add_i32 s48, s88, s97
	s_mov_b32 m0, s48
	ds_read_b128 v[192:195], v161 offset:49152
	ds_read_b128 v[196:199], v161 offset:50176
	ds_read_b128 v[200:203], v161 offset:51200
	ds_read_b128 v[204:207], v161 offset:52224
	ds_read_b128 v[208:211], v161 offset:53248
	ds_read_b128 v[212:215], v161 offset:54272
	ds_read_b128 v[216:219], v161 offset:55296
	ds_read_b128 v[220:223], v161 offset:56320
	global_load_lds_dwordx4 v132, s[98:99]
	s_add_i32 m0, s48, 0x2000
	s_add_u32 s46, s46, 0x100080
	s_addc_u32 s47, s47, 0
	s_add_i32 s48, s89, s97
	global_load_lds_dwordx4 v136, s[98:99]
	s_mov_b32 m0, s48
	s_nop 0
	global_load_lds_dwordx4 v132, s[46:47]
	s_add_i32 m0, s48, 0x2000
	s_nop 0
	global_load_lds_dwordx4 v136, s[46:47]
	s_mov_b32 m0, s68
	s_nop 0
	global_load_lds_dwordx4 v130, s[100:101]
	s_mov_b32 m0, s69
	s_nop 0
	global_load_lds_dwordx4 v134, s[100:101]
	s_waitcnt vmcnt(8)
	s_waitcnt lgkmcnt(0)
	s_barrier
	v_mfma_f32_16x16x32_bf16 v[60:63], v[148:151], v[192:195], v[60:63]
	v_mfma_f32_16x16x32_bf16 v[56:59], v[168:171], v[192:195], v[56:59]
	v_mfma_f32_16x16x32_bf16 v[36:39], v[148:151], v[200:203], v[36:39]
	v_mfma_f32_16x16x32_bf16 v[32:35], v[168:171], v[200:203], v[32:35]
	v_mfma_f32_16x16x32_bf16 v[20:23], v[148:151], v[208:211], v[20:23]
	v_mfma_f32_16x16x32_bf16 v[16:19], v[168:171], v[208:211], v[16:19]
	v_mfma_f32_16x16x32_bf16 v[4:7], v[148:151], v[216:219], v[4:7]
	v_mfma_f32_16x16x32_bf16 v[0:3], v[168:171], v[216:219], v[0:3]
	v_mfma_f32_16x16x32_bf16 v[60:63], v[164:167], v[196:199], v[60:63]
	v_mfma_f32_16x16x32_bf16 v[56:59], v[172:175], v[196:199], v[56:59]
	v_mfma_f32_16x16x32_bf16 v[36:39], v[164:167], v[204:207], v[36:39]
	v_mfma_f32_16x16x32_bf16 v[32:35], v[172:175], v[204:207], v[32:35]
	v_mfma_f32_16x16x32_bf16 v[20:23], v[164:167], v[212:215], v[20:23]
	v_mfma_f32_16x16x32_bf16 v[16:19], v[172:175], v[212:215], v[16:19]
	v_mfma_f32_16x16x32_bf16 v[4:7], v[164:167], v[220:223], v[4:7]
	v_mfma_f32_16x16x32_bf16 v[0:3], v[172:175], v[220:223], v[0:3]
	v_mfma_f32_16x16x32_bf16 v[76:79], v[176:179], v[192:195], v[76:79]
	v_mfma_f32_16x16x32_bf16 v[72:75], v[184:187], v[192:195], v[72:75]
	v_mfma_f32_16x16x32_bf16 v[44:47], v[176:179], v[200:203], v[44:47]
	v_mfma_f32_16x16x32_bf16 v[40:43], v[184:187], v[200:203], v[40:43]
	v_mfma_f32_16x16x32_bf16 v[28:31], v[176:179], v[208:211], v[28:31]
	v_mfma_f32_16x16x32_bf16 v[24:27], v[184:187], v[208:211], v[24:27]
	v_mfma_f32_16x16x32_bf16 v[12:15], v[176:179], v[216:219], v[12:15]
	v_mfma_f32_16x16x32_bf16 v[8:11], v[184:187], v[216:219], v[8:11]
	v_mfma_f32_16x16x32_bf16 v[76:79], v[180:183], v[196:199], v[76:79]
	v_mfma_f32_16x16x32_bf16 v[72:75], v[188:191], v[196:199], v[72:75]
	v_mfma_f32_16x16x32_bf16 v[44:47], v[180:183], v[204:207], v[44:47]
	v_mfma_f32_16x16x32_bf16 v[40:43], v[188:191], v[204:207], v[40:43]
	v_mfma_f32_16x16x32_bf16 v[28:31], v[180:183], v[212:215], v[28:31]
	v_mfma_f32_16x16x32_bf16 v[24:27], v[188:191], v[212:215], v[24:27]
	v_mfma_f32_16x16x32_bf16 v[12:15], v[180:183], v[220:223], v[12:15]
	v_mfma_f32_16x16x32_bf16 v[8:11], v[188:191], v[220:223], v[8:11]
	s_barrier
	s_add_u32 s85, s85, 0x100
	s_addc_u32 s86, s86, 0
	s_add_u32 s44, s44, 0x100
	s_addc_u32 s45, s45, 0
	s_cmp_ge_u32 s87, s84
	s_mov_b32 s46, s87
	s_cbranch_scc0 .LBB0_2289

.LBB0_2434:
	v_ashrrev_i32_e32 v0, 1, v224
	s_add_u32 s33, s74, 0x58000
	v_and_b32_e32 v222, 15, v224
	s_addc_u32 s50, s75, 0
	s_andn2_b64 vcc, exec, s[0:1]
	v_and_b32_e32 v223, -8, v0
	s_cbranch_vccnz .LBB0_2468
	v_lshl_add_u32 v0, v224, 4, s97
	v_ashrrev_i32_e32 v1, 31, v0
	v_lshrrev_b32_e32 v1, 22, v1
	v_add_u32_e32 v1, v0, v1
	v_ashrrev_i32_e32 v8, 10, v1
	v_mul_i32_i24_e32 v1, 0x400, v8
	v_sub_u32_e32 v1, v0, v1
	v_lshrrev_b32_e32 v2, 4, v1
	v_bitop3_b32 v1, v2, v1, 32 bitop3:0x6c
	v_ashrrev_i32_e32 v3, 31, v1
	v_lshrrev_b32_e32 v3, 26, v3
	v_add_u32_e32 v3, v1, v3
	v_lshlrev_b32_e32 v2, 3, v8
	v_ashrrev_i32_e32 v9, 6, v3
	v_and_b32_e32 v3, 0xc0, v3
	v_and_b32_e32 v2, -16, v2
	v_sub_u32_e32 v1, v1, v3
	v_mov_b32_e32 v3, 1
	v_add_u32_e32 v2, v9, v2
	v_ashrrev_i16_sdwa v1, v3, sext(v1) dst_sel:DWORD dst_unused:UNUSED_PAD src0_sel:DWORD src1_sel:BYTE_0
	v_lshlrev_b32_e32 v4, 5, v8
	v_bfe_i32 v10, v1, 0, 16
	v_lshlrev_b32_e32 v1, 1, v2
	v_lshrrev_b32_e32 v5, 2, v2
	v_and_b32_e32 v6, 3, v9
	s_mov_b32 s0, 0x1ffe0
	v_and_b32_e32 v4, 32, v4
	v_and_b32_e32 v1, 24, v1
	v_and_b32_e32 v5, 4, v5
	v_and_or_b32 v6, v2, s0, v6
	v_or3_b32 v1, v6, v5, v1
	v_add_lshl_u32 v4, v4, v10, 1
	v_add_u32_e32 v0, 0x2000, v0
	v_lshl_add_u32 v194, v1, 15, v4
	v_ashrrev_i32_e32 v1, 31, v0
	v_lshrrev_b32_e32 v1, 22, v1
	v_add_u32_e32 v1, v0, v1
	v_ashrrev_i32_e32 v11, 10, v1
	v_mul_i32_i24_e32 v1, 0x400, v11
	v_sub_u32_e32 v0, v0, v1
	v_lshrrev_b32_e32 v1, 4, v0
	v_bitop3_b32 v0, v1, v0, 32 bitop3:0x6c
	v_lshl_add_u32 v192, v2, 15, v4
	v_ashrrev_i32_e32 v2, 31, v0
	v_lshrrev_b32_e32 v2, 26, v2
	v_add_u32_e32 v2, v0, v2
	v_ashrrev_i32_e32 v12, 6, v2
	v_and_b32_e32 v2, 0xffc0, v2
	v_sub_u32_e32 v0, v0, v2
	v_lshrrev_b16_e32 v2, 7, v0
	v_lshlrev_b32_e32 v1, 3, v11
	v_and_b32_e32 v2, 1, v2
	v_and_b32_e32 v1, -16, v1
	v_add_u16_e32 v0, v0, v2
	v_add_u32_e32 v1, v12, v1
	v_ashrrev_i16_sdwa v0, v3, sext(v0) dst_sel:DWORD dst_unused:UNUSED_PAD src0_sel:DWORD src1_sel:BYTE_0
	v_and_b32_e32 v3, 3, v12
	s_ashr_i32 s41, s40, 31
	v_and_or_b32 v3, v1, s0, v3
	s_lshl_b64 s[0:1], s[40:41], 23
	s_add_u32 s11, s2, s0
	s_addc_u32 s12, s3, s1
	s_ashr_i32 s43, s42, 31
	s_lshl_b64 s[0:1], s[42:43], 23
	v_readlane_b32 s14, v254, 54
	v_readlane_b32 s15, v254, 55
	s_add_u32 s0, s14, s0
	s_addc_u32 s1, s15, s1
	v_lshlrev_b32_e32 v4, 5, v11
	v_bfe_i32 v13, v0, 0, 16
	v_lshlrev_b32_e32 v0, 1, v1
	v_lshrrev_b32_e32 v2, 2, v1
	s_add_u32 s44, s0, s4
	v_and_b32_e32 v4, 32, v4
	v_and_b32_e32 v0, 24, v0
	v_and_b32_e32 v2, 4, v2
	s_addc_u32 s45, s1, s5
	s_add_i32 m0, s94, 0x10000
	v_or3_b32 v0, v3, v2, v0
	v_add_lshl_u32 v2, v4, v13, 1
	global_load_lds_dwordx4 v194, s[44:45]
	s_add_i32 m0, s94, 0x12000
	v_lshl_add_u32 v198, v0, 15, v2
	s_add_u32 s0, s44, 0x400000
	global_load_lds_dwordx4 v198, s[44:45]
	s_addc_u32 s1, s45, 0
	s_add_i32 m0, s94, 0x14000
	v_lshl_add_u32 v196, v1, 15, v2
	global_load_lds_dwordx4 v194, s[0:1]
	s_add_i32 m0, s94, 0x16000
	s_add_u32 s46, s11, s4
	s_addc_u32 s47, s12, s5
	s_add_i32 s51, s94, 0x2000
	global_load_lds_dwordx4 v198, s[0:1]
	s_mov_b32 m0, s94
	s_add_u32 s0, s46, 0x400000
	global_load_lds_dwordx4 v192, s[46:47]
	s_mov_b32 m0, s51
	s_addc_u32 s1, s47, 0
	s_add_i32 s52, s94, 0x4000
	global_load_lds_dwordx4 v196, s[46:47]
	s_mov_b32 m0, s52
	s_add_i32 s53, s94, 0x6000
	global_load_lds_dwordx4 v192, s[0:1]
	s_mov_b32 m0, s53
	v_mov_b32_e32 v195, 0
	global_load_lds_dwordx4 v196, s[0:1]
	v_readlane_b32 s0, v254, 58
	v_mov_b32_e32 v199, v195
	v_mov_b32_e32 v193, v195
	v_mov_b32_e32 v197, v195
	v_readlane_b32 s1, v254, 59
	v_lshl_add_u64 v[6:7], s[44:45], 0, v[194:195]
	s_mov_b32 s11, 0
	v_lshl_add_u64 v[4:5], s[44:45], 0, v[198:199]
	v_lshl_add_u64 v[0:1], s[46:47], 0, v[192:193]
	s_and_b64 vcc, exec, s[0:1]
	v_lshl_add_u64 v[2:3], s[46:47], 0, v[196:197]
	s_cbranch_vccnz .LBB0_2437
	s_barrier
	s_setprio 1

.LBB0_2452:
	s_cmp_lt_u32 s35, 0x3fffffff
	s_cselect_b64 s[38:39], -1, 0
	s_ashr_i32 s35, s34, 31
	s_and_b64 s[38:39], s[4:5], s[38:39]
	s_lshl_b64 s[4:5], s[34:35], 23
	s_add_u32 s4, s2, s4
	s_addc_u32 s5, s3, s5
	s_add_u32 s4, s4, s36
	s_addc_u32 s5, s5, s37
	s_and_b64 s[48:49], s[38:39], exec
	s_cselect_b32 s35, s5, s47
	s_cselect_b32 s41, s4, s46
	s_ashr_i32 s31, s30, 31
	s_lshl_b64 s[48:49], s[30:31], 23
	v_readlane_b32 s78, v254, 54
	v_readlane_b32 s79, v254, 55
	s_add_u32 s31, s78, s48
	s_addc_u32 s43, s79, s49
	s_add_u32 s36, s31, s36
	s_addc_u32 s37, s43, s37
	s_and_b64 s[48:49], s[38:39], exec
	s_cselect_b32 s31, s37, s45
	s_cselect_b32 s43, s36, s44
	s_add_i32 s75, s76, -2
	s_add_u32 s77, s44, 0x100
	s_addc_u32 s78, s45, 0
	s_add_u32 s44, s46, 0x400080
	s_addc_u32 s45, s47, 0
	s_mov_b32 s46, 0
	ds_read_b128 v[128:131], v228
	ds_read_b128 v[132:135], v228 offset:1024
	ds_read_b128 v[136:139], v228 offset:2048
	ds_read_b128 v[140:143], v228 offset:3072
	ds_read_b128 v[144:147], v229
	ds_read_b128 v[148:151], v229 offset:1024
	ds_read_b128 v[152:155], v229 offset:2048
	ds_read_b128 v[156:159], v229 offset:3072
	s_add_i32 s79, s46, 2
	s_add_u32 s47, s44, 0xffc00080
	s_addc_u32 s48, s45, -1
	s_cmp_eq_u32 s75, s46
	s_cselect_b32 s46, s43, s77
	s_cselect_b32 s49, s35, s48
	s_cselect_b32 s48, s41, s47
	s_cselect_b32 s47, s31, s78
	s_add_i32 m0, s94, 0xc000
	ds_read_b128 v[160:163], v230
	ds_read_b128 v[164:167], v230 offset:1024
	ds_read_b128 v[168:171], v230 offset:2048
	ds_read_b128 v[172:175], v230 offset:3072
	ds_read_b128 v[176:179], v230 offset:4096
	ds_read_b128 v[180:183], v230 offset:5120
	ds_read_b128 v[184:187], v230 offset:6144
	ds_read_b128 v[188:191], v230 offset:7168
	global_load_lds_dwordx4 v202, s[44:45]
	s_add_i32 m0, s94, 0xe000
	s_nop 0
	global_load_lds_dwordx4 v204, s[44:45]
	s_waitcnt vmcnt(8)
	s_waitcnt lgkmcnt(0)
	s_barrier
	v_mfma_f32_16x16x32_bf16 v[112:115], v[128:131], v[160:163], 0
	v_mfma_f32_16x16x32_bf16 v[116:119], v[136:139], v[160:163], 0
	v_mfma_f32_16x16x32_bf16 v[100:103], v[128:131], v[168:171], 0
	v_mfma_f32_16x16x32_bf16 v[96:99], v[136:139], v[168:171], 0
	v_mfma_f32_16x16x32_bf16 v[84:87], v[128:131], v[176:179], 0
	v_mfma_f32_16x16x32_bf16 v[80:83], v[136:139], v[176:179], 0
	v_mfma_f32_16x16x32_bf16 v[52:55], v[128:131], v[184:187], 0
	v_mfma_f32_16x16x32_bf16 v[48:51], v[136:139], v[184:187], 0
	v_mfma_f32_16x16x32_bf16 v[112:115], v[132:135], v[164:167], v[112:115]
	v_mfma_f32_16x16x32_bf16 v[116:119], v[140:143], v[164:167], v[116:119]
	v_mfma_f32_16x16x32_bf16 v[100:103], v[132:135], v[172:175], v[100:103]
	v_mfma_f32_16x16x32_bf16 v[96:99], v[140:143], v[172:175], v[96:99]
	v_mfma_f32_16x16x32_bf16 v[84:87], v[132:135], v[180:183], v[84:87]
	v_mfma_f32_16x16x32_bf16 v[80:83], v[140:143], v[180:183], v[80:83]
	v_mfma_f32_16x16x32_bf16 v[52:55], v[132:135], v[188:191], v[52:55]
	v_mfma_f32_16x16x32_bf16 v[48:51], v[140:143], v[188:191], v[48:51]
	v_mfma_f32_16x16x32_bf16 v[124:127], v[144:147], v[160:163], 0
	v_mfma_f32_16x16x32_bf16 v[120:123], v[152:155], v[160:163], 0
	v_mfma_f32_16x16x32_bf16 v[108:111], v[144:147], v[168:171], 0
	v_mfma_f32_16x16x32_bf16 v[104:107], v[152:155], v[168:171], 0
	v_mfma_f32_16x16x32_bf16 v[92:95], v[144:147], v[176:179], 0
	v_mfma_f32_16x16x32_bf16 v[88:91], v[152:155], v[176:179], 0
	v_mfma_f32_16x16x32_bf16 v[68:71], v[144:147], v[184:187], 0
	v_mfma_f32_16x16x32_bf16 v[64:67], v[152:155], v[184:187], 0
	v_mfma_f32_16x16x32_bf16 v[124:127], v[148:151], v[164:167], v[124:127]
	v_mfma_f32_16x16x32_bf16 v[120:123], v[156:159], v[164:167], v[120:123]
	v_mfma_f32_16x16x32_bf16 v[108:111], v[148:151], v[172:175], v[108:111]
	v_mfma_f32_16x16x32_bf16 v[104:107], v[156:159], v[172:175], v[104:107]
	v_mfma_f32_16x16x32_bf16 v[92:95], v[148:151], v[180:183], v[92:95]
	v_mfma_f32_16x16x32_bf16 v[88:91], v[156:159], v[180:183], v[88:91]
	v_mfma_f32_16x16x32_bf16 v[68:71], v[148:151], v[188:191], v[68:71]
	v_mfma_f32_16x16x32_bf16 v[64:67], v[156:159], v[188:191], v[64:67]
	s_barrier
	s_add_i32 s80, s68, s97
	s_add_u32 s98, s46, 0x80
	s_addc_u32 s99, s47, 0
	s_mov_b32 m0, s80
	ds_read_b128 v[160:163], v230 offset:16384
	ds_read_b128 v[164:167], v230 offset:17408
	ds_read_b128 v[168:171], v230 offset:18432
	ds_read_b128 v[172:175], v230 offset:19456
	ds_read_b128 v[176:179], v230 offset:20480
	ds_read_b128 v[180:183], v230 offset:21504
	ds_read_b128 v[184:187], v230 offset:22528
	ds_read_b128 v[188:191], v230 offset:23552
	global_load_lds_dwordx4 v194, s[46:47]
	s_add_i32 m0, s80, 0x2000
	s_add_u32 s80, s46, 0x400000
	s_addc_u32 s81, s47, 0
	s_add_i32 s84, s69, s97
	global_load_lds_dwordx4 v198, s[46:47]
	s_mov_b32 m0, s84
	s_add_u32 s100, s48, 0x80
	s_addc_u32 s101, s49, 0
	global_load_lds_dwordx4 v194, s[80:81]
	s_add_i32 m0, s84, 0x2000
	s_nop 0
	global_load_lds_dwordx4 v198, s[80:81]
	s_mov_b32 m0, s94
	s_nop 0
	global_load_lds_dwordx4 v192, s[48:49]
	s_mov_b32 m0, s51
	s_nop 0
	global_load_lds_dwordx4 v196, s[48:49]
	s_waitcnt vmcnt(8)
	s_waitcnt lgkmcnt(0)
	s_barrier
	v_mfma_f32_16x16x32_bf16 v[60:63], v[128:131], v[160:163], 0
	v_mfma_f32_16x16x32_bf16 v[56:59], v[136:139], v[160:163], 0
	v_mfma_f32_16x16x32_bf16 v[36:39], v[128:131], v[168:171], 0
	v_mfma_f32_16x16x32_bf16 v[32:35], v[136:139], v[168:171], 0
	v_mfma_f32_16x16x32_bf16 v[20:23], v[128:131], v[176:179], 0
	v_mfma_f32_16x16x32_bf16 v[16:19], v[136:139], v[176:179], 0
	v_mfma_f32_16x16x32_bf16 v[4:7], v[128:131], v[184:187], 0
	v_mfma_f32_16x16x32_bf16 v[0:3], v[136:139], v[184:187], 0
	v_mfma_f32_16x16x32_bf16 v[60:63], v[132:135], v[164:167], v[60:63]
	v_mfma_f32_16x16x32_bf16 v[56:59], v[140:143], v[164:167], v[56:59]
	v_mfma_f32_16x16x32_bf16 v[36:39], v[132:135], v[172:175], v[36:39]
	v_mfma_f32_16x16x32_bf16 v[32:35], v[140:143], v[172:175], v[32:35]
	v_mfma_f32_16x16x32_bf16 v[20:23], v[132:135], v[180:183], v[20:23]
	v_mfma_f32_16x16x32_bf16 v[16:19], v[140:143], v[180:183], v[16:19]
	v_mfma_f32_16x16x32_bf16 v[4:7], v[132:135], v[188:191], v[4:7]
	v_mfma_f32_16x16x32_bf16 v[0:3], v[140:143], v[188:191], v[0:3]
	v_mfma_f32_16x16x32_bf16 v[76:79], v[144:147], v[160:163], 0
	v_mfma_f32_16x16x32_bf16 v[72:75], v[152:155], v[160:163], 0
	v_mfma_f32_16x16x32_bf16 v[44:47], v[144:147], v[168:171], 0
	v_mfma_f32_16x16x32_bf16 v[40:43], v[152:155], v[168:171], 0
	v_mfma_f32_16x16x32_bf16 v[28:31], v[144:147], v[176:179], 0
	v_mfma_f32_16x16x32_bf16 v[24:27], v[152:155], v[176:179], 0
	v_mfma_f32_16x16x32_bf16 v[12:15], v[144:147], v[184:187], 0
	v_mfma_f32_16x16x32_bf16 v[8:11], v[152:155], v[184:187], 0
	v_mfma_f32_16x16x32_bf16 v[76:79], v[148:151], v[164:167], v[76:79]
	v_mfma_f32_16x16x32_bf16 v[72:75], v[156:159], v[164:167], v[72:75]
	v_mfma_f32_16x16x32_bf16 v[44:47], v[148:151], v[172:175], v[44:47]
	v_mfma_f32_16x16x32_bf16 v[40:43], v[156:159], v[172:175], v[40:43]
	v_mfma_f32_16x16x32_bf16 v[28:31], v[148:151], v[180:183], v[28:31]
	v_mfma_f32_16x16x32_bf16 v[24:27], v[156:159], v[180:183], v[24:27]
	v_mfma_f32_16x16x32_bf16 v[12:15], v[148:151], v[188:191], v[12:15]
	v_mfma_f32_16x16x32_bf16 v[8:11], v[156:159], v[188:191], v[8:11]
	s_barrier
	s_add_i32 s80, 0, 0x18000
	s_add_i32 s81, 0, 0x1c000
	v_add_u32_e32 v140, s80, v226
	v_add_u32_e32 v156, s81, v226
	ds_read_b128 v[128:131], v140
	ds_read_b128 v[132:135], v140 offset:1024
	ds_read_b128 v[136:139], v140 offset:2048
	ds_read_b128 v[140:143], v140 offset:3072
	ds_read_b128 v[144:147], v156
	ds_read_b128 v[148:151], v156 offset:1024
	ds_read_b128 v[152:155], v156 offset:2048
	ds_read_b128 v[156:159], v156 offset:3072
	s_add_u32 s48, s48, 0x400000
	s_addc_u32 s49, s49, 0
	s_mov_b32 m0, s52
	ds_read_b128 v[160:163], v230 offset:32768
	ds_read_b128 v[164:167], v230 offset:33792
	ds_read_b128 v[168:171], v230 offset:34816
	ds_read_b128 v[172:175], v230 offset:35840
	ds_read_b128 v[176:179], v230 offset:36864
	ds_read_b128 v[180:183], v230 offset:37888
	ds_read_b128 v[184:187], v230 offset:38912
	ds_read_b128 v[188:191], v230 offset:39936
	global_load_lds_dwordx4 v192, s[48:49]
	s_mov_b32 m0, s53
	s_nop 0
	global_load_lds_dwordx4 v196, s[48:49]
	s_waitcnt vmcnt(8)
	s_waitcnt lgkmcnt(0)
	s_barrier
	v_mfma_f32_16x16x32_bf16 v[112:115], v[128:131], v[160:163], v[112:115]
	v_mfma_f32_16x16x32_bf16 v[116:119], v[136:139], v[160:163], v[116:119]
	v_mfma_f32_16x16x32_bf16 v[100:103], v[128:131], v[168:171], v[100:103]
	v_mfma_f32_16x16x32_bf16 v[96:99], v[136:139], v[168:171], v[96:99]
	v_mfma_f32_16x16x32_bf16 v[84:87], v[128:131], v[176:179], v[84:87]
	v_mfma_f32_16x16x32_bf16 v[80:83], v[136:139], v[176:179], v[80:83]
	v_mfma_f32_16x16x32_bf16 v[52:55], v[128:131], v[184:187], v[52:55]
	v_mfma_f32_16x16x32_bf16 v[48:51], v[136:139], v[184:187], v[48:51]
	v_mfma_f32_16x16x32_bf16 v[112:115], v[132:135], v[164:167], v[112:115]
	v_mfma_f32_16x16x32_bf16 v[116:119], v[140:143], v[164:167], v[116:119]
	v_mfma_f32_16x16x32_bf16 v[100:103], v[132:135], v[172:175], v[100:103]
	v_mfma_f32_16x16x32_bf16 v[96:99], v[140:143], v[172:175], v[96:99]
	v_mfma_f32_16x16x32_bf16 v[84:87], v[132:135], v[180:183], v[84:87]
	v_mfma_f32_16x16x32_bf16 v[80:83], v[140:143], v[180:183], v[80:83]
	v_mfma_f32_16x16x32_bf16 v[52:55], v[132:135], v[188:191], v[52:55]
	v_mfma_f32_16x16x32_bf16 v[48:51], v[140:143], v[188:191], v[48:51]
	v_mfma_f32_16x16x32_bf16 v[124:127], v[144:147], v[160:163], v[124:127]
	v_mfma_f32_16x16x32_bf16 v[120:123], v[152:155], v[160:163], v[120:123]
	v_mfma_f32_16x16x32_bf16 v[108:111], v[144:147], v[168:171], v[108:111]
	v_mfma_f32_16x16x32_bf16 v[104:107], v[152:155], v[168:171], v[104:107]
	v_mfma_f32_16x16x32_bf16 v[92:95], v[144:147], v[176:179], v[92:95]
	v_mfma_f32_16x16x32_bf16 v[88:91], v[152:155], v[176:179], v[88:91]
	v_mfma_f32_16x16x32_bf16 v[68:71], v[144:147], v[184:187], v[68:71]
	v_mfma_f32_16x16x32_bf16 v[64:67], v[152:155], v[184:187], v[64:67]
	v_mfma_f32_16x16x32_bf16 v[124:127], v[148:151], v[164:167], v[124:127]
	v_mfma_f32_16x16x32_bf16 v[120:123], v[156:159], v[164:167], v[120:123]
	v_mfma_f32_16x16x32_bf16 v[108:111], v[148:151], v[172:175], v[108:111]
	v_mfma_f32_16x16x32_bf16 v[104:107], v[156:159], v[172:175], v[104:107]
	v_mfma_f32_16x16x32_bf16 v[92:95], v[148:151], v[180:183], v[92:95]
	v_mfma_f32_16x16x32_bf16 v[88:91], v[156:159], v[180:183], v[88:91]
	v_mfma_f32_16x16x32_bf16 v[68:71], v[148:151], v[188:191], v[68:71]
	v_mfma_f32_16x16x32_bf16 v[64:67], v[156:159], v[188:191], v[64:67]
	s_barrier
	s_add_i32 s48, s80, s97
	s_mov_b32 m0, s48
	ds_read_b128 v[160:163], v230 offset:49152
	ds_read_b128 v[164:167], v230 offset:50176
	ds_read_b128 v[168:171], v230 offset:51200
	ds_read_b128 v[172:175], v230 offset:52224
	ds_read_b128 v[176:179], v230 offset:53248
	ds_read_b128 v[180:183], v230 offset:54272
	ds_read_b128 v[184:187], v230 offset:55296
	ds_read_b128 v[188:191], v230 offset:56320
	global_load_lds_dwordx4 v194, s[98:99]
	s_add_i32 m0, s48, 0x2000
	s_add_u32 s46, s46, 0x400080
	s_addc_u32 s47, s47, 0
	s_add_i32 s48, s81, s97
	global_load_lds_dwordx4 v198, s[98:99]
	s_mov_b32 m0, s48
	s_nop 0
	global_load_lds_dwordx4 v194, s[46:47]
	s_add_i32 m0, s48, 0x2000
	s_nop 0
	global_load_lds_dwordx4 v198, s[46:47]
	s_mov_b32 m0, s54
	s_nop 0
	global_load_lds_dwordx4 v192, s[100:101]
	s_mov_b32 m0, s55
	s_nop 0
	global_load_lds_dwordx4 v196, s[100:101]
	s_waitcnt vmcnt(8)
	s_waitcnt lgkmcnt(0)
	s_barrier
	v_mfma_f32_16x16x32_bf16 v[60:63], v[128:131], v[160:163], v[60:63]
	v_mfma_f32_16x16x32_bf16 v[56:59], v[136:139], v[160:163], v[56:59]
	v_mfma_f32_16x16x32_bf16 v[36:39], v[128:131], v[168:171], v[36:39]
	v_mfma_f32_16x16x32_bf16 v[32:35], v[136:139], v[168:171], v[32:35]
	v_mfma_f32_16x16x32_bf16 v[20:23], v[128:131], v[176:179], v[20:23]
	v_mfma_f32_16x16x32_bf16 v[16:19], v[136:139], v[176:179], v[16:19]
	v_mfma_f32_16x16x32_bf16 v[4:7], v[128:131], v[184:187], v[4:7]
	v_mfma_f32_16x16x32_bf16 v[0:3], v[136:139], v[184:187], v[0:3]
	v_mfma_f32_16x16x32_bf16 v[60:63], v[132:135], v[164:167], v[60:63]
	v_mfma_f32_16x16x32_bf16 v[56:59], v[140:143], v[164:167], v[56:59]
	v_mfma_f32_16x16x32_bf16 v[36:39], v[132:135], v[172:175], v[36:39]
	v_mfma_f32_16x16x32_bf16 v[32:35], v[140:143], v[172:175], v[32:35]
	v_mfma_f32_16x16x32_bf16 v[20:23], v[132:135], v[180:183], v[20:23]
	v_mfma_f32_16x16x32_bf16 v[16:19], v[140:143], v[180:183], v[16:19]
	v_mfma_f32_16x16x32_bf16 v[4:7], v[132:135], v[188:191], v[4:7]
	v_mfma_f32_16x16x32_bf16 v[0:3], v[140:143], v[188:191], v[0:3]
	v_mfma_f32_16x16x32_bf16 v[76:79], v[144:147], v[160:163], v[76:79]
	v_mfma_f32_16x16x32_bf16 v[72:75], v[152:155], v[160:163], v[72:75]
	v_mfma_f32_16x16x32_bf16 v[44:47], v[144:147], v[168:171], v[44:47]
	v_mfma_f32_16x16x32_bf16 v[40:43], v[152:155], v[168:171], v[40:43]
	v_mfma_f32_16x16x32_bf16 v[28:31], v[144:147], v[176:179], v[28:31]
	v_mfma_f32_16x16x32_bf16 v[24:27], v[152:155], v[176:179], v[24:27]
	v_mfma_f32_16x16x32_bf16 v[12:15], v[144:147], v[184:187], v[12:15]
	v_mfma_f32_16x16x32_bf16 v[8:11], v[152:155], v[184:187], v[8:11]
	v_mfma_f32_16x16x32_bf16 v[76:79], v[148:151], v[164:167], v[76:79]
	v_mfma_f32_16x16x32_bf16 v[72:75], v[156:159], v[164:167], v[72:75]
	v_mfma_f32_16x16x32_bf16 v[44:47], v[148:151], v[172:175], v[44:47]
	v_mfma_f32_16x16x32_bf16 v[40:43], v[156:159], v[172:175], v[40:43]
	v_mfma_f32_16x16x32_bf16 v[28:31], v[148:151], v[180:183], v[28:31]
	v_mfma_f32_16x16x32_bf16 v[24:27], v[156:159], v[180:183], v[24:27]
	v_mfma_f32_16x16x32_bf16 v[12:15], v[148:151], v[188:191], v[12:15]
	v_mfma_f32_16x16x32_bf16 v[8:11], v[156:159], v[188:191], v[8:11]
	s_barrier
	s_add_u32 s77, s77, 0x100
	s_addc_u32 s78, s78, 0
	s_add_u32 s44, s44, 0x100
	s_addc_u32 s45, s45, 0
	s_cmp_ge_u32 s79, s76
	s_mov_b32 s46, s79
	s_cbranch_scc1 .Lpeel_done_4
.LBB0_2453:
	ds_read_b128 v[128:131], v228
	ds_read_b128 v[132:135], v228 offset:1024
	ds_read_b128 v[136:139], v228 offset:2048
	ds_read_b128 v[140:143], v228 offset:3072
	ds_read_b128 v[144:147], v229
	ds_read_b128 v[148:151], v229 offset:1024
	ds_read_b128 v[152:155], v229 offset:2048
	ds_read_b128 v[156:159], v229 offset:3072
	s_add_i32 s79, s46, 2
	s_add_u32 s47, s44, 0xffc00080
	s_addc_u32 s48, s45, -1
	s_cmp_eq_u32 s75, s46
	s_cselect_b32 s46, s43, s77
	s_cselect_b32 s49, s35, s48
	s_cselect_b32 s48, s41, s47
	s_cselect_b32 s47, s31, s78
	s_add_i32 m0, s94, 0xc000
	ds_read_b128 v[160:163], v230
	ds_read_b128 v[164:167], v230 offset:1024
	ds_read_b128 v[168:171], v230 offset:2048
	ds_read_b128 v[172:175], v230 offset:3072
	ds_read_b128 v[176:179], v230 offset:4096
	ds_read_b128 v[180:183], v230 offset:5120
	ds_read_b128 v[184:187], v230 offset:6144
	ds_read_b128 v[188:191], v230 offset:7168
	global_load_lds_dwordx4 v202, s[44:45]
	s_add_i32 m0, s94, 0xe000
	s_nop 0
	global_load_lds_dwordx4 v204, s[44:45]
	s_waitcnt vmcnt(8)
	s_waitcnt lgkmcnt(0)
	s_barrier
	v_mfma_f32_16x16x32_bf16 v[112:115], v[128:131], v[160:163], v[112:115]
	v_mfma_f32_16x16x32_bf16 v[116:119], v[136:139], v[160:163], v[116:119]
	v_mfma_f32_16x16x32_bf16 v[100:103], v[128:131], v[168:171], v[100:103]
	v_mfma_f32_16x16x32_bf16 v[96:99], v[136:139], v[168:171], v[96:99]
	v_mfma_f32_16x16x32_bf16 v[84:87], v[128:131], v[176:179], v[84:87]
	v_mfma_f32_16x16x32_bf16 v[80:83], v[136:139], v[176:179], v[80:83]
	v_mfma_f32_16x16x32_bf16 v[52:55], v[128:131], v[184:187], v[52:55]
	v_mfma_f32_16x16x32_bf16 v[48:51], v[136:139], v[184:187], v[48:51]
	v_mfma_f32_16x16x32_bf16 v[112:115], v[132:135], v[164:167], v[112:115]
	v_mfma_f32_16x16x32_bf16 v[116:119], v[140:143], v[164:167], v[116:119]
	v_mfma_f32_16x16x32_bf16 v[100:103], v[132:135], v[172:175], v[100:103]
	v_mfma_f32_16x16x32_bf16 v[96:99], v[140:143], v[172:175], v[96:99]
	v_mfma_f32_16x16x32_bf16 v[84:87], v[132:135], v[180:183], v[84:87]
	v_mfma_f32_16x16x32_bf16 v[80:83], v[140:143], v[180:183], v[80:83]
	v_mfma_f32_16x16x32_bf16 v[52:55], v[132:135], v[188:191], v[52:55]
	v_mfma_f32_16x16x32_bf16 v[48:51], v[140:143], v[188:191], v[48:51]
	v_mfma_f32_16x16x32_bf16 v[124:127], v[144:147], v[160:163], v[124:127]
	v_mfma_f32_16x16x32_bf16 v[120:123], v[152:155], v[160:163], v[120:123]
	v_mfma_f32_16x16x32_bf16 v[108:111], v[144:147], v[168:171], v[108:111]
	v_mfma_f32_16x16x32_bf16 v[104:107], v[152:155], v[168:171], v[104:107]
	v_mfma_f32_16x16x32_bf16 v[92:95], v[144:147], v[176:179], v[92:95]
	v_mfma_f32_16x16x32_bf16 v[88:91], v[152:155], v[176:179], v[88:91]
	v_mfma_f32_16x16x32_bf16 v[68:71], v[144:147], v[184:187], v[68:71]
	v_mfma_f32_16x16x32_bf16 v[64:67], v[152:155], v[184:187], v[64:67]
	v_mfma_f32_16x16x32_bf16 v[124:127], v[148:151], v[164:167], v[124:127]
	v_mfma_f32_16x16x32_bf16 v[120:123], v[156:159], v[164:167], v[120:123]
	v_mfma_f32_16x16x32_bf16 v[108:111], v[148:151], v[172:175], v[108:111]
	v_mfma_f32_16x16x32_bf16 v[104:107], v[156:159], v[172:175], v[104:107]
	v_mfma_f32_16x16x32_bf16 v[92:95], v[148:151], v[180:183], v[92:95]
	v_mfma_f32_16x16x32_bf16 v[88:91], v[156:159], v[180:183], v[88:91]
	v_mfma_f32_16x16x32_bf16 v[68:71], v[148:151], v[188:191], v[68:71]
	v_mfma_f32_16x16x32_bf16 v[64:67], v[156:159], v[188:191], v[64:67]
	s_barrier
	s_add_i32 s80, s68, s97
	s_add_u32 s98, s46, 0x80
	s_addc_u32 s99, s47, 0
	s_mov_b32 m0, s80
	ds_read_b128 v[160:163], v230 offset:16384
	ds_read_b128 v[164:167], v230 offset:17408
	ds_read_b128 v[168:171], v230 offset:18432
	ds_read_b128 v[172:175], v230 offset:19456
	ds_read_b128 v[176:179], v230 offset:20480
	ds_read_b128 v[180:183], v230 offset:21504
	ds_read_b128 v[184:187], v230 offset:22528
	ds_read_b128 v[188:191], v230 offset:23552
	global_load_lds_dwordx4 v194, s[46:47]
	s_add_i32 m0, s80, 0x2000
	s_add_u32 s80, s46, 0x400000
	s_addc_u32 s81, s47, 0
	s_add_i32 s84, s69, s97
	global_load_lds_dwordx4 v198, s[46:47]
	s_mov_b32 m0, s84
	s_add_u32 s100, s48, 0x80
	s_addc_u32 s101, s49, 0
	global_load_lds_dwordx4 v194, s[80:81]
	s_add_i32 m0, s84, 0x2000
	s_nop 0
	global_load_lds_dwordx4 v198, s[80:81]
	s_mov_b32 m0, s94
	s_nop 0
	global_load_lds_dwordx4 v192, s[48:49]
	s_mov_b32 m0, s51
	s_nop 0
	global_load_lds_dwordx4 v196, s[48:49]
	s_waitcnt vmcnt(8)
	s_waitcnt lgkmcnt(0)
	s_barrier
	v_mfma_f32_16x16x32_bf16 v[60:63], v[128:131], v[160:163], v[60:63]
	v_mfma_f32_16x16x32_bf16 v[56:59], v[136:139], v[160:163], v[56:59]
	v_mfma_f32_16x16x32_bf16 v[36:39], v[128:131], v[168:171], v[36:39]
	v_mfma_f32_16x16x32_bf16 v[32:35], v[136:139], v[168:171], v[32:35]
	v_mfma_f32_16x16x32_bf16 v[20:23], v[128:131], v[176:179], v[20:23]
	v_mfma_f32_16x16x32_bf16 v[16:19], v[136:139], v[176:179], v[16:19]
	v_mfma_f32_16x16x32_bf16 v[4:7], v[128:131], v[184:187], v[4:7]
	v_mfma_f32_16x16x32_bf16 v[0:3], v[136:139], v[184:187], v[0:3]
	v_mfma_f32_16x16x32_bf16 v[60:63], v[132:135], v[164:167], v[60:63]
	v_mfma_f32_16x16x32_bf16 v[56:59], v[140:143], v[164:167], v[56:59]
	v_mfma_f32_16x16x32_bf16 v[36:39], v[132:135], v[172:175], v[36:39]
	v_mfma_f32_16x16x32_bf16 v[32:35], v[140:143], v[172:175], v[32:35]
	v_mfma_f32_16x16x32_bf16 v[20:23], v[132:135], v[180:183], v[20:23]
	v_mfma_f32_16x16x32_bf16 v[16:19], v[140:143], v[180:183], v[16:19]
	v_mfma_f32_16x16x32_bf16 v[4:7], v[132:135], v[188:191], v[4:7]
	v_mfma_f32_16x16x32_bf16 v[0:3], v[140:143], v[188:191], v[0:3]
	v_mfma_f32_16x16x32_bf16 v[76:79], v[144:147], v[160:163], v[76:79]
	v_mfma_f32_16x16x32_bf16 v[72:75], v[152:155], v[160:163], v[72:75]
	v_mfma_f32_16x16x32_bf16 v[44:47], v[144:147], v[168:171], v[44:47]
	v_mfma_f32_16x16x32_bf16 v[40:43], v[152:155], v[168:171], v[40:43]
	v_mfma_f32_16x16x32_bf16 v[28:31], v[144:147], v[176:179], v[28:31]
	v_mfma_f32_16x16x32_bf16 v[24:27], v[152:155], v[176:179], v[24:27]
	v_mfma_f32_16x16x32_bf16 v[12:15], v[144:147], v[184:187], v[12:15]
	v_mfma_f32_16x16x32_bf16 v[8:11], v[152:155], v[184:187], v[8:11]
	v_mfma_f32_16x16x32_bf16 v[76:79], v[148:151], v[164:167], v[76:79]
	v_mfma_f32_16x16x32_bf16 v[72:75], v[156:159], v[164:167], v[72:75]
	v_mfma_f32_16x16x32_bf16 v[44:47], v[148:151], v[172:175], v[44:47]
	v_mfma_f32_16x16x32_bf16 v[40:43], v[156:159], v[172:175], v[40:43]
	v_mfma_f32_16x16x32_bf16 v[28:31], v[148:151], v[180:183], v[28:31]
	v_mfma_f32_16x16x32_bf16 v[24:27], v[156:159], v[180:183], v[24:27]
	v_mfma_f32_16x16x32_bf16 v[12:15], v[148:151], v[188:191], v[12:15]
	v_mfma_f32_16x16x32_bf16 v[8:11], v[156:159], v[188:191], v[8:11]
	s_barrier
	s_add_i32 s80, 0, 0x18000
	s_add_i32 s81, 0, 0x1c000
	v_add_u32_e32 v140, s80, v226
	v_add_u32_e32 v156, s81, v226
	ds_read_b128 v[128:131], v140
	ds_read_b128 v[132:135], v140 offset:1024
	ds_read_b128 v[136:139], v140 offset:2048
	ds_read_b128 v[140:143], v140 offset:3072
	ds_read_b128 v[144:147], v156
	ds_read_b128 v[148:151], v156 offset:1024
	ds_read_b128 v[152:155], v156 offset:2048
	ds_read_b128 v[156:159], v156 offset:3072
	s_add_u32 s48, s48, 0x400000
	s_addc_u32 s49, s49, 0
	s_mov_b32 m0, s52
	ds_read_b128 v[160:163], v230 offset:32768
	ds_read_b128 v[164:167], v230 offset:33792
	ds_read_b128 v[168:171], v230 offset:34816
	ds_read_b128 v[172:175], v230 offset:35840
	ds_read_b128 v[176:179], v230 offset:36864
	ds_read_b128 v[180:183], v230 offset:37888
	ds_read_b128 v[184:187], v230 offset:38912
	ds_read_b128 v[188:191], v230 offset:39936
	global_load_lds_dwordx4 v192, s[48:49]
	s_mov_b32 m0, s53
	s_nop 0
	global_load_lds_dwordx4 v196, s[48:49]
	s_waitcnt vmcnt(8)
	s_waitcnt lgkmcnt(0)
	s_barrier
	v_mfma_f32_16x16x32_bf16 v[112:115], v[128:131], v[160:163], v[112:115]
	v_mfma_f32_16x16x32_bf16 v[116:119], v[136:139], v[160:163], v[116:119]
	v_mfma_f32_16x16x32_bf16 v[100:103], v[128:131], v[168:171], v[100:103]
	v_mfma_f32_16x16x32_bf16 v[96:99], v[136:139], v[168:171], v[96:99]
	v_mfma_f32_16x16x32_bf16 v[84:87], v[128:131], v[176:179], v[84:87]
	v_mfma_f32_16x16x32_bf16 v[80:83], v[136:139], v[176:179], v[80:83]
	v_mfma_f32_16x16x32_bf16 v[52:55], v[128:131], v[184:187], v[52:55]
	v_mfma_f32_16x16x32_bf16 v[48:51], v[136:139], v[184:187], v[48:51]
	v_mfma_f32_16x16x32_bf16 v[112:115], v[132:135], v[164:167], v[112:115]
	v_mfma_f32_16x16x32_bf16 v[116:119], v[140:143], v[164:167], v[116:119]
	v_mfma_f32_16x16x32_bf16 v[100:103], v[132:135], v[172:175], v[100:103]
	v_mfma_f32_16x16x32_bf16 v[96:99], v[140:143], v[172:175], v[96:99]
	v_mfma_f32_16x16x32_bf16 v[84:87], v[132:135], v[180:183], v[84:87]
	v_mfma_f32_16x16x32_bf16 v[80:83], v[140:143], v[180:183], v[80:83]
	v_mfma_f32_16x16x32_bf16 v[52:55], v[132:135], v[188:191], v[52:55]
	v_mfma_f32_16x16x32_bf16 v[48:51], v[140:143], v[188:191], v[48:51]
	v_mfma_f32_16x16x32_bf16 v[124:127], v[144:147], v[160:163], v[124:127]
	v_mfma_f32_16x16x32_bf16 v[120:123], v[152:155], v[160:163], v[120:123]
	v_mfma_f32_16x16x32_bf16 v[108:111], v[144:147], v[168:171], v[108:111]
	v_mfma_f32_16x16x32_bf16 v[104:107], v[152:155], v[168:171], v[104:107]
	v_mfma_f32_16x16x32_bf16 v[92:95], v[144:147], v[176:179], v[92:95]
	v_mfma_f32_16x16x32_bf16 v[88:91], v[152:155], v[176:179], v[88:91]
	v_mfma_f32_16x16x32_bf16 v[68:71], v[144:147], v[184:187], v[68:71]
	v_mfma_f32_16x16x32_bf16 v[64:67], v[152:155], v[184:187], v[64:67]
	v_mfma_f32_16x16x32_bf16 v[124:127], v[148:151], v[164:167], v[124:127]
	v_mfma_f32_16x16x32_bf16 v[120:123], v[156:159], v[164:167], v[120:123]
	v_mfma_f32_16x16x32_bf16 v[108:111], v[148:151], v[172:175], v[108:111]
	v_mfma_f32_16x16x32_bf16 v[104:107], v[156:159], v[172:175], v[104:107]
	v_mfma_f32_16x16x32_bf16 v[92:95], v[148:151], v[180:183], v[92:95]
	v_mfma_f32_16x16x32_bf16 v[88:91], v[156:159], v[180:183], v[88:91]
	v_mfma_f32_16x16x32_bf16 v[68:71], v[148:151], v[188:191], v[68:71]
	v_mfma_f32_16x16x32_bf16 v[64:67], v[156:159], v[188:191], v[64:67]
	s_barrier
	s_add_i32 s48, s80, s97
	s_mov_b32 m0, s48
	ds_read_b128 v[160:163], v230 offset:49152
	ds_read_b128 v[164:167], v230 offset:50176
	ds_read_b128 v[168:171], v230 offset:51200
	ds_read_b128 v[172:175], v230 offset:52224
	ds_read_b128 v[176:179], v230 offset:53248
	ds_read_b128 v[180:183], v230 offset:54272
	ds_read_b128 v[184:187], v230 offset:55296
	ds_read_b128 v[188:191], v230 offset:56320
	global_load_lds_dwordx4 v194, s[98:99]
	s_add_i32 m0, s48, 0x2000
	s_add_u32 s46, s46, 0x400080
	s_addc_u32 s47, s47, 0
	s_add_i32 s48, s81, s97
	global_load_lds_dwordx4 v198, s[98:99]
	s_mov_b32 m0, s48
	s_nop 0
	global_load_lds_dwordx4 v194, s[46:47]
	s_add_i32 m0, s48, 0x2000
	s_nop 0
	global_load_lds_dwordx4 v198, s[46:47]
	s_mov_b32 m0, s54
	s_nop 0
	global_load_lds_dwordx4 v192, s[100:101]
	s_mov_b32 m0, s55
	s_nop 0
	global_load_lds_dwordx4 v196, s[100:101]
	s_waitcnt vmcnt(8)
	s_waitcnt lgkmcnt(0)
	s_barrier
	v_mfma_f32_16x16x32_bf16 v[60:63], v[128:131], v[160:163], v[60:63]
	v_mfma_f32_16x16x32_bf16 v[56:59], v[136:139], v[160:163], v[56:59]
	v_mfma_f32_16x16x32_bf16 v[36:39], v[128:131], v[168:171], v[36:39]
	v_mfma_f32_16x16x32_bf16 v[32:35], v[136:139], v[168:171], v[32:35]
	v_mfma_f32_16x16x32_bf16 v[20:23], v[128:131], v[176:179], v[20:23]
	v_mfma_f32_16x16x32_bf16 v[16:19], v[136:139], v[176:179], v[16:19]
	v_mfma_f32_16x16x32_bf16 v[4:7], v[128:131], v[184:187], v[4:7]
	v_mfma_f32_16x16x32_bf16 v[0:3], v[136:139], v[184:187], v[0:3]
	v_mfma_f32_16x16x32_bf16 v[60:63], v[132:135], v[164:167], v[60:63]
	v_mfma_f32_16x16x32_bf16 v[56:59], v[140:143], v[164:167], v[56:59]
	v_mfma_f32_16x16x32_bf16 v[36:39], v[132:135], v[172:175], v[36:39]
	v_mfma_f32_16x16x32_bf16 v[32:35], v[140:143], v[172:175], v[32:35]
	v_mfma_f32_16x16x32_bf16 v[20:23], v[132:135], v[180:183], v[20:23]
	v_mfma_f32_16x16x32_bf16 v[16:19], v[140:143], v[180:183], v[16:19]
	v_mfma_f32_16x16x32_bf16 v[4:7], v[132:135], v[188:191], v[4:7]
	v_mfma_f32_16x16x32_bf16 v[0:3], v[140:143], v[188:191], v[0:3]
	v_mfma_f32_16x16x32_bf16 v[76:79], v[144:147], v[160:163], v[76:79]
	v_mfma_f32_16x16x32_bf16 v[72:75], v[152:155], v[160:163], v[72:75]
	v_mfma_f32_16x16x32_bf16 v[44:47], v[144:147], v[168:171], v[44:47]
	v_mfma_f32_16x16x32_bf16 v[40:43], v[152:155], v[168:171], v[40:43]
	v_mfma_f32_16x16x32_bf16 v[28:31], v[144:147], v[176:179], v[28:31]
	v_mfma_f32_16x16x32_bf16 v[24:27], v[152:155], v[176:179], v[24:27]
	v_mfma_f32_16x16x32_bf16 v[12:15], v[144:147], v[184:187], v[12:15]
	v_mfma_f32_16x16x32_bf16 v[8:11], v[152:155], v[184:187], v[8:11]
	v_mfma_f32_16x16x32_bf16 v[76:79], v[148:151], v[164:167], v[76:79]
	v_mfma_f32_16x16x32_bf16 v[72:75], v[156:159], v[164:167], v[72:75]
	v_mfma_f32_16x16x32_bf16 v[44:47], v[148:151], v[172:175], v[44:47]
	v_mfma_f32_16x16x32_bf16 v[40:43], v[156:159], v[172:175], v[40:43]
	v_mfma_f32_16x16x32_bf16 v[28:31], v[148:151], v[180:183], v[28:31]
	v_mfma_f32_16x16x32_bf16 v[24:27], v[156:159], v[180:183], v[24:27]
	v_mfma_f32_16x16x32_bf16 v[12:15], v[148:151], v[188:191], v[12:15]
	v_mfma_f32_16x16x32_bf16 v[8:11], v[156:159], v[188:191], v[8:11]
	s_barrier
	s_add_u32 s77, s77, 0x100
	s_addc_u32 s78, s78, 0
	s_add_u32 s44, s44, 0x100
	s_addc_u32 s45, s45, 0
	s_cmp_ge_u32 s79, s76
	s_mov_b32 s46, s79
	s_cbranch_scc0 .LBB0_2453
